# NA fast path: 64B-coalesced K loads + ds_bpermute to fragment layout, 128B-coalesced V loads, non-blocking bias prefetch; P3 rebalanced (NA 0/4, conv 3/1, ret1 1/3 between GEMM and non-GEMM workgroups
# speedup vs baseline: 1.0675x; 1.0064x over previous
; __device__ __forceinline__ KParams kparams() { KParams k = (KParams)__builtin_amdgcn_kernarg_segment_ptr(); asm volatile("" : "+s"(k)); return k; }
; __device__ __forceinline__ void ret1_task(const Params& p_, int l, int task, unsigned char* lds) {
;     const Params p = *kparams(); (void)p_;
;     const int n = task & 31, h = (task >> 5) & 7, b = task >> 8;
;     const float xf = p.rl_f[l * 8 + h], xb = p.rl_b[l * 8 + h];
;     const float l2f = -log1pf(expf(-xf)) * 1.4426950408889634f, l2b = -log1pf(expf(-xb)) * 1.4426950408889634f;
; __device__ __forceinline__ void ph_mixA(const Params& p, int l, unsigned char* lds) {
;     ...
;     for (int t = bid; t < 512 * REP_R1; t += G) ret1_task(p, l, t & 511, lds);
.LBB0_368:
	v_readlane_b32 s12, v255, 38
	s_lshl_b32 s3, s12, 3
	s_mov_b32 s92, s70
	s_movk_i32 s98, 0x80
	s_cmp_lt_u32 s92, s98
	s_cselect_b32 s98, 0x200, s98
	s_cmpk_lt_i32 s92, 0x200
	s_cselect_b64 s[36:37], -1, 0
	s_cmpk_gt_i32 s92, 0x1ff
	s_mov_b32 s10, s92
	s_movk_i32 s6, 0x90
	s_mov_b32 s26, 0xbfb8aa3b
	s_mov_b32 s27, 0x42ce8ed0
	s_mov_b32 s43, 0xc2b17218
	s_mov_b32 s48, 0x7f800000
	s_mov_b32 s49, 0x3f2aaaab
	s_mov_b32 s50, 0x3f317218
	s_mov_b32 s51, 0x33800000
	s_mov_b32 s52, 0x6c00000
	s_mov_b64 s[54:55], 0xad20000
	s_mov_b64 s[56:57], 0x1c00
	s_mov_b64 s[58:59], 0x2000
	s_mov_b64 s[60:61], 0x6c00000
	v_readlane_b32 s13, v255, 39
	s_cbranch_scc1 .LBB0_370
.LBB0_369:
	s_mov_b64 s[12:13], s[0:1]
	s_load_dwordx4 s[44:47], s[12:13], 0x40
	s_load_dwordx2 s[38:39], s[12:13], 0x90
	s_bfe_u32 s41, s10, 0x30005
	s_or_b32 s24, s41, s3
	s_and_b32 s40, s10, 31
	s_bfe_u32 s42, s10, 0x10008
	s_lshl_b64 s[12:13], s[24:25], 2
	s_waitcnt lgkmcnt(0)
	s_add_u32 s44, s44, s12
	s_addc_u32 s45, s45, s13
	global_load_dword v0, v1, s[44:45]
	s_add_u32 s12, s46, s12
	s_addc_u32 s13, s47, s13
	global_load_dword v4, v1, s[12:13]
	s_mov_b64 s[12:13], s[0:1]
	s_load_dwordx2 s[12:13], s[12:13], 0x90
	s_lshl_b32 s24, s41, 7
	s_add_i32 s9, 0, 0x11800
	s_add_i32 s10, s10, s98
	s_waitcnt vmcnt(0)
	v_mul_f32_e32 v2, 0xbfb8aa3b, v0
	v_fma_f32 v3, v0, s26, -v2
	v_rndne_f32_e32 v5, v2
	v_fmac_f32_e32 v3, 0xb2a5705f, v0
	v_sub_f32_e32 v2, v2, v5
	v_add_f32_e32 v2, v2, v3
	v_exp_f32_e32 v2, v2
	v_cvt_i32_f32_e32 v3, v5
	v_cmp_nlt_f32_e32 vcc, s27, v0
	v_ldexp_f32 v2, v2, v3
	s_nop 0
	v_cndmask_b32_e32 v2, 0, v2, vcc
	v_cmp_ngt_f32_e32 vcc, s43, v0
	s_nop 1
	v_cndmask_b32_e32 v0, v182, v2, vcc
	v_add_f32_e32 v5, 1.0, v0
	v_add_f32_e32 v2, -1.0, v5
	v_sub_f32_e32 v3, v2, v5
	v_add_f32_e32 v3, 1.0, v3
	v_sub_f32_e32 v2, v0, v2
	v_add_f32_e32 v6, v2, v3
	v_frexp_mant_f32_e32 v2, v5
	v_cmp_gt_f32_e32 vcc, s49, v2
	v_cvt_f64_f32_e32 v[2:3], v5
	v_frexp_exp_i32_f64_e32 v2, v[2:3]
	v_subbrev_co_u32_e32 v2, vcc, 0, v2, vcc
	v_sub_u32_e32 v3, 0, v2
	v_ldexp_f32 v5, v5, v3
	v_ldexp_f32 v3, v6, v3
	v_add_f32_e32 v6, -1.0, v5
	v_add_f32_e32 v7, 1.0, v6
	v_sub_f32_e32 v7, v5, v7
	v_add_f32_e32 v7, v3, v7
	v_add_f32_e32 v8, v6, v7
	v_sub_f32_e32 v6, v6, v8
	v_add_f32_e32 v6, v7, v6
	v_add_f32_e32 v7, 1.0, v5
	v_add_f32_e32 v9, -1.0, v7
	v_sub_f32_e32 v5, v5, v9
	v_add_f32_e32 v3, v3, v5
	v_add_f32_e32 v5, v7, v3
	v_sub_f32_e32 v7, v7, v5
	v_add_f32_e32 v3, v3, v7
	v_rcp_f32_e32 v7, v5
	v_cvt_f32_i32_e32 v2, v2
	v_cmp_neq_f32_e32 vcc, s48, v0
	v_mul_f32_e32 v9, v8, v7
	v_mul_f32_e32 v10, v5, v9
	v_fma_f32 v11, v9, v5, -v10
	v_fmac_f32_e32 v11, v9, v3
	v_add_f32_e32 v12, v10, v11
	v_sub_f32_e32 v13, v8, v12
	v_sub_f32_e32 v8, v8, v13
	v_sub_f32_e32 v10, v12, v10
	v_sub_f32_e32 v8, v8, v12
	v_add_f32_e32 v6, v6, v8
	v_sub_f32_e32 v8, v10, v11
	v_add_f32_e32 v6, v8, v6
	v_add_f32_e32 v8, v13, v6
	v_mul_f32_e32 v10, v7, v8
	v_mul_f32_e32 v11, v5, v10
	v_fma_f32 v5, v10, v5, -v11
	v_fmac_f32_e32 v5, v10, v3
	v_sub_f32_e32 v3, v13, v8
	v_add_f32_e32 v3, v6, v3
	v_add_f32_e32 v6, v11, v5
	v_sub_f32_e32 v12, v8, v6
	v_sub_f32_e32 v8, v8, v12
	v_sub_f32_e32 v11, v6, v11
	v_sub_f32_e32 v6, v8, v6
	v_add_f32_e32 v3, v3, v6
	v_sub_f32_e32 v5, v11, v5
	v_add_f32_e32 v3, v5, v3
	v_add_f32_e32 v5, v9, v10
	v_add_f32_e32 v3, v12, v3
	v_sub_f32_e32 v6, v5, v9
	v_mul_f32_e32 v3, v7, v3
	v_sub_f32_e32 v6, v10, v6
	v_add_f32_e32 v3, v6, v3
	v_mul_f32_e32 v9, 0x3f317218, v2
	v_add_f32_e32 v6, v5, v3
	v_fma_f32 v10, v2, s50, -v9
	v_mul_f32_e32 v7, v6, v6
	v_fmac_f32_e32 v10, 0xb102e308, v2
	v_sub_f32_e32 v2, v6, v5
	v_fmamk_f32 v8, v7, 0x3e9b6dac, v180
	v_sub_f32_e32 v2, v3, v2
	v_add_f32_e32 v3, v9, v10
	v_fmaak_f32 v8, v7, v8, 0x3f2aaada
	v_sub_f32_e32 v5, v3, v9
	v_ldexp_f32 v9, v6, 1
	v_mul_f32_e32 v6, v6, v7
	v_mul_f32_e32 v6, v6, v8
	v_add_f32_e32 v7, v9, v6
	v_sub_f32_e32 v8, v7, v9
	v_ldexp_f32 v2, v2, 1
	v_sub_f32_e32 v6, v6, v8
	v_add_f32_e32 v2, v2, v6
	v_add_f32_e32 v6, v7, v2
	v_sub_f32_e32 v7, v6, v7
	v_sub_f32_e32 v2, v2, v7
	v_add_f32_e32 v7, v3, v6
	v_sub_f32_e32 v8, v7, v3
	v_sub_f32_e32 v9, v7, v8
	v_sub_f32_e32 v5, v10, v5
	v_sub_f32_e32 v3, v3, v9
	v_sub_f32_e32 v6, v6, v8
	v_add_f32_e32 v3, v6, v3
	v_add_f32_e32 v6, v5, v2
	v_sub_f32_e32 v8, v6, v5
	v_sub_f32_e32 v9, v6, v8
	v_sub_f32_e32 v5, v5, v9
	v_sub_f32_e32 v2, v2, v8
	v_add_f32_e32 v3, v6, v3
	v_add_f32_e32 v2, v2, v5
	v_add_f32_e32 v5, v7, v3
	v_sub_f32_e32 v6, v5, v7
	v_sub_f32_e32 v3, v3, v6
	v_add_f32_e32 v2, v2, v3
	v_add_f32_e32 v2, v5, v2
	v_cndmask_b32_e32 v2, v182, v2, vcc
	v_cmp_lt_f32_e64 vcc, |v0|, s51
	s_nop 1
	v_cndmask_b32_e32 v0, v2, v0, vcc
	v_mul_f32_e32 v10, 0xbfb8aa3b, v0
	v_mul_f32_e32 v0, 0xbfb8aa3b, v4
	v_fma_f32 v2, v4, s26, -v0
	v_rndne_f32_e32 v3, v0
	v_fmac_f32_e32 v2, 0xb2a5705f, v4
	v_sub_f32_e32 v0, v0, v3
	v_add_f32_e32 v0, v0, v2
	v_exp_f32_e32 v0, v0
	v_cvt_i32_f32_e32 v2, v3
	v_cmp_nlt_f32_e32 vcc, s27, v4
	v_ldexp_f32 v0, v0, v2
	s_nop 0
	v_cndmask_b32_e32 v0, 0, v0, vcc
	v_cmp_ngt_f32_e32 vcc, s43, v4
	s_nop 1
	v_cndmask_b32_e32 v0, v182, v0, vcc
	v_add_f32_e32 v4, 1.0, v0
	v_add_f32_e32 v2, -1.0, v4
	v_sub_f32_e32 v3, v2, v4
	v_add_f32_e32 v3, 1.0, v3
	v_sub_f32_e32 v2, v0, v2
	v_add_f32_e32 v5, v2, v3
	v_frexp_mant_f32_e32 v2, v4
	v_cmp_gt_f32_e32 vcc, s49, v2
	v_cvt_f64_f32_e32 v[2:3], v4
	v_frexp_exp_i32_f64_e32 v2, v[2:3]
	v_subbrev_co_u32_e32 v2, vcc, 0, v2, vcc
	v_sub_u32_e32 v3, 0, v2
	v_ldexp_f32 v4, v4, v3
	v_ldexp_f32 v3, v5, v3
	v_add_f32_e32 v5, -1.0, v4
	v_add_f32_e32 v6, 1.0, v5
	v_sub_f32_e32 v6, v4, v6
	v_add_f32_e32 v6, v3, v6
	v_add_f32_e32 v7, v5, v6
	v_sub_f32_e32 v5, v5, v7
; __device__ __forceinline__ int otid() { int t; asm volatile("v_mov_b32 %0, %1" : "=v"(t) : "v"(threadIdx.x)); return t; }
; __device__ __forceinline__ KParams kparams() { KParams k = (KParams)__builtin_amdgcn_kernarg_segment_ptr(); asm volatile("" : "+s"(k)); return k; }
; __device__ __forceinline__ float bflo(unsigned u) { return __uint_as_float(u << 16); }
; __device__ __forceinline__ float bfhi(unsigned u) { return __uint_as_float(u & 0xffff0000u); }
; template <bool R2>
; __device__ __forceinline__ void ret_stage(const Params& p_, int b, int h, int n, unsigned char* lds, float l2f, float l2b) {
;     const Params p = *kparams(); (void)p_;
;     const int tid = otid(), j = tid >> 2, c4 = tid & 3, s = n * 128 + j;
;     const bf16* Z = (const bf16*)(p.ws + WS_Z); const bf16* zr = Z + (size_t)(b * SEQ + s) * DIN;
;     const f32x4* rp = (const f32x4*)((const float2*)(p.ws + WS_ROPE) + s * 32 + c4 * 8);
;     f32x4 rr[4];
; #pragma unroll
;     for (int i = 0; i < 4; ++i) rr[i] = rp[i];
;     const u32x4 ka = *(const u32x4*)(zr + 7 * DG + h * 64 + c4 * 8), kb = *(const u32x4*)(zr + 7 * DG + h * 64 + 32 + c4 * 8);
;     const u32x4 va = *(const u32x4*)(zr + 8 * DG + h * 64 + c4 * 16), vb = *(const u32x4*)(zr + 8 * DG + h * 64 + c4 * 16 + 8);
;     u32x4 qa = ka, qb = kb;
;     if (R2) { qa = *(const u32x4*)(zr + 6 * DG + h * 64 + c4 * 8); qb = *(const u32x4*)(zr + 6 * DG + h * 64 + 32 + c4 * 8); }
;     asm volatile("" ::: "memory");
;     float cs[8], sn[8];
; #pragma unroll
;     for (int i = 0; i < 4; ++i) { const f32x4 r = rr[i]; cs[2 * i] = r[0]; sn[2 * i] = r[1]; cs[2 * i + 1] = r[2]; sn[2 * i + 1] = r[3]; }
;     bf16* KS = (bf16*)(lds + R_KS); bf16* VT = (bf16*)(lds + R_VT);
;     {
;       const unsigned kau[4] = {ka.x, ka.y, ka.z, ka.w}, kbu[4] = {kb.x, kb.y, kb.z, kb.w};
;       float k1[8], k2[8];
; #pragma unroll
;       for (int i = 0; i < 4; ++i) { const float a0 = bflo(kau[i]), a1 = bfhi(kau[i]), b0 = bflo(kbu[i]), b1 = bfhi(kbu[i]);
;           k1[2 * i] = a0 * cs[2 * i] - b0 * sn[2 * i]; k2[2 * i] = a0 * sn[2 * i] + b0 * cs[2 * i];
;           k1[2 * i + 1] = a1 * cs[2 * i + 1] - b1 * sn[2 * i + 1]; k2[2 * i + 1] = a1 * sn[2 * i + 1] + b1 * cs[2 * i + 1]; }
	v_add_f32_e32 v5, v6, v5
	v_add_f32_e32 v6, 1.0, v4
	v_add_f32_e32 v8, -1.0, v6
	v_sub_f32_e32 v4, v4, v8
	v_add_f32_e32 v3, v3, v4
	v_add_f32_e32 v4, v6, v3
	v_sub_f32_e32 v6, v6, v4
	v_add_f32_e32 v3, v3, v6
	v_rcp_f32_e32 v6, v4
	v_cvt_f32_i32_e32 v2, v2
	v_cmp_neq_f32_e32 vcc, s48, v0
	v_mul_f32_e32 v8, v7, v6
	v_mul_f32_e32 v9, v4, v8
	v_fma_f32 v11, v8, v4, -v9
	v_fmac_f32_e32 v11, v8, v3
	v_add_f32_e32 v12, v9, v11
	v_sub_f32_e32 v13, v7, v12
	v_sub_f32_e32 v7, v7, v13
	v_sub_f32_e32 v9, v12, v9
	v_sub_f32_e32 v7, v7, v12
	v_add_f32_e32 v5, v5, v7
	v_sub_f32_e32 v7, v9, v11
	v_add_f32_e32 v5, v7, v5
	v_add_f32_e32 v7, v13, v5
	v_mul_f32_e32 v9, v6, v7
	v_mul_f32_e32 v11, v4, v9
	v_fma_f32 v4, v9, v4, -v11
	v_fmac_f32_e32 v4, v9, v3
	v_sub_f32_e32 v3, v13, v7
	v_add_f32_e32 v3, v5, v3
	v_add_f32_e32 v5, v11, v4
	v_sub_f32_e32 v12, v7, v5
	v_sub_f32_e32 v7, v7, v12
	v_sub_f32_e32 v11, v5, v11
	v_sub_f32_e32 v5, v7, v5
	v_add_f32_e32 v3, v3, v5
	v_sub_f32_e32 v4, v11, v4
	v_add_f32_e32 v3, v4, v3
	v_add_f32_e32 v4, v8, v9
	v_add_f32_e32 v3, v12, v3
	v_sub_f32_e32 v5, v4, v8
	v_mul_f32_e32 v3, v6, v3
	v_sub_f32_e32 v5, v9, v5
	v_add_f32_e32 v3, v5, v3
	v_mul_f32_e32 v8, 0x3f317218, v2
	v_add_f32_e32 v5, v4, v3
	v_fma_f32 v9, v2, s50, -v8
	v_mul_f32_e32 v6, v5, v5
	v_fmac_f32_e32 v9, 0xb102e308, v2
	v_sub_f32_e32 v2, v5, v4
	v_fmamk_f32 v7, v6, 0x3e9b6dac, v180
	v_sub_f32_e32 v2, v3, v2
	v_add_f32_e32 v3, v8, v9
	v_fmaak_f32 v7, v6, v7, 0x3f2aaada
	v_sub_f32_e32 v4, v3, v8
	v_ldexp_f32 v8, v5, 1
	v_mul_f32_e32 v5, v5, v6
	v_mul_f32_e32 v5, v5, v7
	v_add_f32_e32 v6, v8, v5
	v_sub_f32_e32 v7, v6, v8
	v_ldexp_f32 v2, v2, 1
	v_sub_f32_e32 v5, v5, v7
	v_add_f32_e32 v2, v2, v5
	v_add_f32_e32 v5, v6, v2
	v_sub_f32_e32 v6, v5, v6
	v_sub_f32_e32 v2, v2, v6
	v_add_f32_e32 v6, v3, v5
	v_sub_f32_e32 v7, v6, v3
	v_sub_f32_e32 v8, v6, v7
	v_sub_f32_e32 v4, v9, v4
	v_sub_f32_e32 v3, v3, v8
	v_sub_f32_e32 v5, v5, v7
	v_add_f32_e32 v3, v5, v3
	v_add_f32_e32 v5, v4, v2
	v_sub_f32_e32 v7, v5, v4
	v_sub_f32_e32 v8, v5, v7
	v_sub_f32_e32 v4, v4, v8
	v_sub_f32_e32 v2, v2, v7
	v_add_f32_e32 v3, v5, v3
	v_add_f32_e32 v2, v2, v4
	v_add_f32_e32 v4, v6, v3
	v_sub_f32_e32 v5, v4, v6
	v_sub_f32_e32 v3, v3, v5
	v_add_f32_e32 v2, v2, v3
	v_add_f32_e32 v2, v4, v2
	v_cndmask_b32_e32 v2, v182, v2, vcc
	v_cmp_lt_f32_e64 vcc, |v0|, s51
	s_waitcnt lgkmcnt(0)
	v_mov_b64_e32 v[4:5], s[12:13]
	v_cndmask_b32_e32 v0, v2, v0, vcc
	v_mul_f32_e32 v11, 0xbfb8aa3b, v0
	v_mov_b32 v0, v147
	s_nop 0
	v_ashrrev_i32_e32 v44, 2, v0
	v_and_b32_e32 v45, 3, v0
	v_lshl_add_u32 v0, s40, 7, v44
	v_lshlrev_b32_e32 v2, 5, v0
	v_ashrrev_i32_e32 v3, 31, v2
	v_lshl_add_u32 v8, s42, 12, v0
	v_lshl_add_u64 v[2:3], v[2:3], 3, s[12:13]
	v_lshlrev_b32_e32 v0, 6, v45
	v_lshl_add_u64 v[2:3], v[2:3], 0, v[0:1]
	v_lshl_add_u64 v[6:7], v[2:3], 0, s[60:61]
	v_add_co_u32_e32 v2, vcc, s52, v2
	v_lshlrev_b32_e32 v0, 4, v45
	s_nop 0
	v_addc_co_u32_e32 v3, vcc, 0, v3, vcc
	global_load_dwordx4 v[12:15], v[2:3], off
	global_load_dwordx4 v[16:19], v[6:7], off offset:32
	global_load_dwordx4 v[20:23], v[6:7], off offset:48
	global_load_dwordx4 v[24:27], v[6:7], off offset:16
	v_mad_i64_i32 v[2:3], s[12:13], v8, s75, v[4:5]
	v_lshl_add_u64 v[2:3], v[2:3], 0, s[24:25]
	v_lshl_add_u64 v[2:3], v[2:3], 0, s[54:55]
	v_lshl_add_u64 v[4:5], v[2:3], 0, v[0:1]
	v_lshl_add_u64 v[6:7], v[4:5], 0, s[56:57]
	v_add_co_u32_e32 v4, vcc, s74, v4
	s_lshl_b32 s24, s40, 14
	s_nop 0
	v_addc_co_u32_e32 v5, vcc, 0, v5, vcc
	global_load_dwordx4 v[28:31], v[4:5], off offset:3072
	global_load_dwordx4 v[32:35], v[6:7], off offset:64
	v_lshlrev_b32_e32 v4, 5, v45
	v_mov_b32_e32 v5, v1
	v_lshl_add_u64 v[2:3], v[2:3], 0, v[4:5]
	v_lshl_add_u64 v[4:5], v[2:3], 0, s[58:59]
	v_add_co_u32_e32 v2, vcc, s97, v2
	s_cmpk_gt_i32 s10, 0x1ff
	s_nop 0
	v_addc_co_u32_e32 v3, vcc, 0, v3, vcc
	global_load_dwordx4 v[6:9], v[2:3], off
	s_nop 0
	global_load_dwordx4 v[2:5], v[4:5], off offset:16
	s_waitcnt vmcnt(7)
	v_mov_b32_e32 v40, v13
	v_mov_b32_e32 v42, v15
	s_waitcnt vmcnt(4)
	v_mov_b32_e32 v41, v25
	v_mov_b32_e32 v13, v24
	v_mov_b32_e32 v43, v27
	v_mov_b32_e32 v15, v26
	s_waitcnt vmcnt(3)
	v_lshlrev_b32_e32 v37, 16, v29
	s_waitcnt vmcnt(2)
	v_lshlrev_b32_e32 v39, 16, v33
	v_lshlrev_b32_e32 v38, 16, v32
	v_lshlrev_b32_e32 v36, 16, v28
	v_and_b32_e32 v33, 0xffff0000, v33
	v_and_b32_e32 v32, 0xffff0000, v32
	v_pk_mul_f32 v[24:25], v[12:13], v[38:39]
	v_pk_mul_f32 v[38:39], v[40:41], v[38:39]
	v_and_b32_e32 v29, 0xffff0000, v29
	v_and_b32_e32 v28, 0xffff0000, v28
	v_pk_fma_f32 v[24:25], v[40:41], v[36:37], v[24:25]
	v_pk_mul_f32 v[26:27], v[14:15], v[32:33]
	v_pk_fma_f32 v[36:37], v[12:13], v[36:37], v[38:39] neg_lo:[0,0,1] neg_hi:[0,0,1]
	v_pk_mul_f32 v[12:13], v[42:43], v[32:33]
	v_pk_fma_f32 v[26:27], v[42:43], v[28:29], v[26:27]
	v_pk_fma_f32 v[28:29], v[14:15], v[28:29], v[12:13] neg_lo:[0,0,1] neg_hi:[0,0,1]
	v_lshlrev_b32_e32 v15, 16, v35
	v_lshlrev_b32_e32 v14, 16, v34
	v_and_b32_e32 v33, 0xffff0000, v35
	v_and_b32_e32 v32, 0xffff0000, v34
	v_mov_b32_e32 v34, v17
	v_mov_b32_e32 v35, v21
	v_mov_b32_e32 v17, v20
	v_lshlrev_b32_e32 v13, 16, v31
	v_lshlrev_b32_e32 v12, 16, v30
	v_pk_mul_f32 v[20:21], v[16:17], v[14:15]
	v_mov_b32_e32 v38, v19
	v_mov_b32_e32 v39, v23
	v_mov_b32_e32 v19, v22
	v_pk_mul_f32 v[14:15], v[34:35], v[14:15]
	v_and_b32_e32 v31, 0xffff0000, v31
	v_and_b32_e32 v30, 0xffff0000, v30
	v_pk_fma_f32 v[20:21], v[34:35], v[12:13], v[20:21]
	v_pk_mul_f32 v[22:23], v[18:19], v[32:33]
	v_pk_fma_f32 v[34:35], v[16:17], v[12:13], v[14:15] neg_lo:[0,0,1] neg_hi:[0,0,1]
	v_pk_mul_f32 v[12:13], v[38:39], v[32:33]
	v_bfe_u32 v14, v29, 16, 1
; __device__ __forceinline__ unsigned f2bf(float f) { unsigned u = __float_as_uint(f); return (u + 0x7fffu + ((u >> 16) & 1u)) >> 16; }
; __device__ __forceinline__ unsigned pk2(float lo, float hi) { return f2bf(lo) | (f2bf(hi) << 16); }
; template <bool R2>
; __device__ __forceinline__ void ret_stage(const Params& p_, int b, int h, int n, unsigned char* lds, float l2f, float l2b) {
;     ...
;       u32x4 o1, o2; o1.x = pk2(k1[0], k1[1]); o1.y = pk2(k1[2], k1[3]); o1.z = pk2(k1[4], k1[5]); o1.w = pk2(k1[6], k1[7]);
;       o2.x = pk2(k2[0], k2[1]); o2.y = pk2(k2[2], k2[3]); o2.z = pk2(k2[4], k2[5]); o2.w = pk2(k2[6], k2[7]);
;       *(u32x4*)(KS + j * 72 + c4 * 8) = o1; *(u32x4*)(KS + j * 72 + 32 + c4 * 8) = o2;
;       if (!R2) { bf16* KTF = (bf16*)(lds + R_KTF); bf16* KTB = (bf16*)(lds + R_KTB);
;           const float df = exp2f(l2f * (float)(127 - j)), db = exp2f(l2b * (float)j);
; #pragma unroll
;           for (int i = 0; i < 8; ++i) { KTF[(c4 * 8 + i) * 136 + j] = (bf16)f2bf(k1[i] * df); KTF[(32 + c4 * 8 + i) * 136 + j] = (bf16)f2bf(k2[i] * df);
;               KTB[(c4 * 8 + i) * 136 + j] = (bf16)f2bf(k1[i] * db); KTB[(32 + c4 * 8 + i) * 136 + j] = (bf16)f2bf(k2[i] * db); } } }
	v_bfe_u32 v15, v28, 16, 1
	v_pk_fma_f32 v[22:23], v[38:39], v[30:31], v[22:23]
	v_pk_fma_f32 v[30:31], v[18:19], v[30:31], v[12:13] neg_lo:[0,0,1] neg_hi:[0,0,1]
	v_add3_u32 v16, v28, v15, s14
	v_add3_u32 v17, v29, v14, s14
	v_bfe_u32 v14, v36, 16, 1
	v_bfe_u32 v15, v37, 16, 1
	v_bfe_u32 v18, v34, 16, 1
	v_bfe_u32 v19, v35, 16, 1
	v_bfe_u32 v12, v31, 16, 1
	v_bfe_u32 v13, v30, 16, 1
	v_add3_u32 v19, v35, v19, s14
	v_add3_u32 v18, v34, v18, s14
	v_add3_u32 v15, v37, v15, s14
	v_add3_u32 v14, v36, v14, s14
	v_add3_u32 v13, v30, v13, s14
	v_add3_u32 v12, v31, v12, s14
	v_lshrrev_b32_e32 v32, 16, v14
	v_lshrrev_b32_e32 v33, 16, v15
	v_lshrrev_b32_e32 v14, 16, v18
	v_lshrrev_b32_e32 v15, 16, v19
	v_bfe_u32 v18, v27, 16, 1
	v_bfe_u32 v19, v26, 16, 1
	v_and_or_b32 v15, v12, s15, v15
	v_and_or_b32 v14, v13, s15, v14
	v_and_or_b32 v13, v17, s15, v33
	v_and_or_b32 v12, v16, s15, v32
	v_add3_u32 v32, v26, v19, s14
	v_add3_u32 v33, v27, v18, s14
	v_bfe_u32 v18, v24, 16, 1
	v_bfe_u32 v19, v25, 16, 1
	v_bfe_u32 v39, v21, 16, 1
	v_bfe_u32 v16, v23, 16, 1
	v_add3_u32 v39, v21, v39, s14
	v_add3_u32 v19, v25, v19, s14
	v_add3_u32 v18, v24, v18, s14
	v_add3_u32 v16, v23, v16, s14
	v_bfe_u32 v38, v20, 16, 1
	v_lshrrev_b32_e32 v40, 16, v18
	v_lshrrev_b32_e32 v41, 16, v19
	v_lshrrev_b32_e32 v19, 16, v39
	v_bfe_u32 v17, v22, 16, 1
	v_add3_u32 v38, v20, v38, s14
	v_and_or_b32 v19, v16, s15, v19
	v_and_or_b32 v16, v32, s15, v40
	v_mul_lo_u32 v32, v44, s6
	v_add3_u32 v17, v22, v17, s14
	v_lshrrev_b32_e32 v18, 16, v38
	v_add3_u32 v0, 0, v32, v0
	v_and_or_b32 v18, v17, s15, v18
	v_and_or_b32 v17, v33, s15, v41
	ds_write_b128 v0, v[12:15] offset:18432
	ds_write_b128 v0, v[16:19] offset:18496
	v_sub_u32_e32 v0, 0x7f, v44
	v_cvt_f32_i32_e32 v0, v0
	v_mul_f32_e32 v12, v10, v0
	v_cmp_gt_f32_e32 vcc, s69, v12
	s_nop 1
	v_cndmask_b32_e32 v12, 0, v183, vcc
	v_fmac_f32_e32 v12, v10, v0
	v_exp_f32_e32 v0, v12
	v_cndmask_b32_e32 v10, 0, v184, vcc
	v_ldexp_f32 v0, v0, v10
	v_cvt_f32_i32_e32 v10, v44
	v_mul_f32_e32 v12, v11, v10
	v_cmp_gt_f32_e32 vcc, s69, v12
	s_nop 1
	v_cndmask_b32_e32 v12, 0, v183, vcc
	v_fmac_f32_e32 v12, v11, v10
	v_exp_f32_e32 v10, v12
	v_mul_f32_e32 v12, v36, v0
	v_bfe_u32 v13, v12, 16, 1
	v_add3_u32 v12, v12, v13, s14
	v_mul_u32_u24_e32 v13, 0x440, v45
	v_add_lshl_u32 v14, v13, v44, 1
	v_add_u32_e32 v15, 0, v14
	ds_write_b16_d16_hi v15, v12 offset:54272
	v_mul_f32_e32 v12, v24, v0
	v_cndmask_b32_e32 v11, 0, v184, vcc
	v_bfe_u32 v16, v12, 16, 1
	v_ldexp_f32 v10, v10, v11
	v_add3_u32 v12, v12, v16, s14
	ds_write_b16_d16_hi v15, v12 offset:62976
	v_mul_f32_e32 v12, v36, v10
	v_bfe_u32 v16, v12, 16, 1
	v_add3_u32 v12, v12, v16, s14
	v_add_u32_e32 v14, s9, v14
	v_add_u32_e32 v11, 0x1100, v44
	ds_write_b16_d16_hi v14, v12
	v_mul_f32_e32 v12, v24, v10
	v_bfe_u32 v14, v12, 16, 1
	v_add_lshl_u32 v13, v11, v13, 1
	v_add3_u32 v12, v12, v14, s14
	v_add_u32_e32 v14, s9, v13
	ds_write_b16_d16_hi v14, v12
	v_mul_f32_e32 v12, v28, v0
	v_bfe_u32 v14, v12, 16, 1
	v_add3_u32 v12, v12, v14, s14
	ds_write_b16_d16_hi v15, v12 offset:54544
	v_mul_f32_e32 v12, v26, v0
	v_bfe_u32 v17, v12, 16, 1
	v_add3_u32 v12, v12, v17, s14
	v_add_u32_e32 v13, 0, v13
	v_mad_u32_u24 v14, v45, s4, v185
	ds_write_b16_d16_hi v13, v12 offset:54544
	v_mul_f32_e32 v12, v28, v10
	v_add_u32_e32 v16, v14, v44
	v_bfe_u32 v17, v12, 16, 1
	v_add3_u32 v12, v12, v17, s14
	v_lshl_add_u32 v16, v16, 1, s9
	ds_write_b16_d16_hi v16, v12
	v_mul_f32_e32 v12, v26, v10
	v_add_u32_e32 v14, v14, v11
	v_bfe_u32 v16, v12, 16, 1
	v_add3_u32 v12, v12, v16, s14
	v_lshl_add_u32 v14, v14, 1, s9
	ds_write_b16_d16_hi v14, v12
	v_mul_f32_e32 v12, v37, v0
	v_bfe_u32 v14, v12, 16, 1
	v_add3_u32 v12, v12, v14, s14
	ds_write_b16_d16_hi v15, v12 offset:54816
	v_mul_f32_e32 v12, v25, v0
	v_bfe_u32 v17, v12, 16, 1
	v_add3_u32 v12, v12, v17, s14
	v_mad_u32_u24 v14, v45, s4, v186
	ds_write_b16_d16_hi v13, v12 offset:54816
	v_mul_f32_e32 v12, v37, v10
	v_add_u32_e32 v16, v14, v44
	v_bfe_u32 v17, v12, 16, 1
	v_add3_u32 v12, v12, v17, s14
	v_lshl_add_u32 v16, v16, 1, s9
	ds_write_b16_d16_hi v16, v12
	v_mul_f32_e32 v12, v25, v10
	v_add_u32_e32 v14, v14, v11
	v_bfe_u32 v16, v12, 16, 1
	v_add3_u32 v12, v12, v16, s14
	v_lshl_add_u32 v14, v14, 1, s9
	ds_write_b16_d16_hi v14, v12
	v_mul_f32_e32 v12, v29, v0
	v_bfe_u32 v14, v12, 16, 1
	v_add3_u32 v12, v12, v14, s14
	ds_write_b16_d16_hi v15, v12 offset:55088
	v_mul_f32_e32 v12, v27, v0
	v_bfe_u32 v17, v12, 16, 1
	v_add3_u32 v12, v12, v17, s14
	v_mad_u32_u24 v14, v45, s4, v187
	ds_write_b16_d16_hi v13, v12 offset:55088
	v_mul_f32_e32 v12, v29, v10
	v_add_u32_e32 v16, v14, v44
	v_bfe_u32 v17, v12, 16, 1
	v_add3_u32 v12, v12, v17, s14
	v_lshl_add_u32 v16, v16, 1, s9
	ds_write_b16_d16_hi v16, v12
	v_mul_f32_e32 v12, v27, v10
	v_add_u32_e32 v14, v14, v11
	v_bfe_u32 v16, v12, 16, 1
	v_add3_u32 v12, v12, v16, s14
	v_lshl_add_u32 v14, v14, 1, s9
	ds_write_b16_d16_hi v14, v12
	v_mul_f32_e32 v12, v34, v0
	v_bfe_u32 v14, v12, 16, 1
	v_add3_u32 v12, v12, v14, s14
	ds_write_b16_d16_hi v15, v12 offset:55360
	v_mul_f32_e32 v12, v20, v0
	v_bfe_u32 v17, v12, 16, 1
	v_add3_u32 v12, v12, v17, s14
	v_mad_u32_u24 v14, v45, s4, v188
	ds_write_b16_d16_hi v13, v12 offset:55360
	v_mul_f32_e32 v12, v34, v10
	v_add_u32_e32 v16, v14, v44
	v_bfe_u32 v17, v12, 16, 1
	v_add3_u32 v12, v12, v17, s14
	v_lshl_add_u32 v16, v16, 1, s9
	ds_write_b16_d16_hi v16, v12
	v_mul_f32_e32 v12, v20, v10
	v_add_u32_e32 v14, v14, v11
	v_bfe_u32 v16, v12, 16, 1
	v_add3_u32 v12, v12, v16, s14
	v_lshl_add_u32 v14, v14, 1, s9
	ds_write_b16_d16_hi v14, v12
	v_mul_f32_e32 v12, v30, v0
	v_bfe_u32 v14, v12, 16, 1
	v_add3_u32 v12, v12, v14, s14
; template <bool R2>
; __device__ __forceinline__ void ret_stage(const Params& p_, int b, int h, int n, unsigned char* lds, float l2f, float l2b) {
;     ...
;           for (int i = 0; i < 8; ++i) { KTF[(c4 * 8 + i) * 136 + j] = (bf16)f2bf(k1[i] * df); KTF[(32 + c4 * 8 + i) * 136 + j] = (bf16)f2bf(k2[i] * df);
;               KTB[(c4 * 8 + i) * 136 + j] = (bf16)f2bf(k1[i] * db); KTB[(32 + c4 * 8 + i) * 136 + j] = (bf16)f2bf(k2[i] * db); } } }
;     {
;       const unsigned vu[8] = {va.x, va.y, va.z, va.w, vb.x, vb.y, vb.z, vb.w};
; #pragma unroll
;       for (int i = 0; i < 8; ++i) { VT[(c4 * 16 + 2 * i) * 136 + j] = (bf16)(vu[i] & 0xffffu); VT[(c4 * 16 + 2 * i + 1) * 136 + j] = (bf16)(vu[i] >> 16); } }
;     if (R2) { bf16* QS = (bf16*)(lds + R_QS);
;       const unsigned qau[4] = {qa.x, qa.y, qa.z, qa.w}, qbu[4] = {qb.x, qb.y, qb.z, qb.w};
;       float q1[8], q2[8];
; #pragma unroll
;       for (int i = 0; i < 4; ++i) { const float a0 = bflo(qau[i]), a1 = bfhi(qau[i]), b0 = bflo(qbu[i]), b1 = bfhi(qbu[i]);
;           q1[2 * i] = (a0 * cs[2 * i] - b0 * sn[2 * i]) * 0.125f; q2[2 * i] = (a0 * sn[2 * i] + b0 * cs[2 * i]) * 0.125f;
;           q1[2 * i + 1] = (a1 * cs[2 * i + 1] - b1 * sn[2 * i + 1]) * 0.125f; q2[2 * i + 1] = (a1 * sn[2 * i + 1] + b1 * cs[2 * i + 1]) * 0.125f; }
;       u32x4 o1, o2; o1.x = pk2(q1[0], q1[1]); o1.y = pk2(q1[2], q1[3]); o1.z = pk2(q1[4], q1[5]); o1.w = pk2(q1[6], q1[7]);
;       o2.x = pk2(q2[0], q2[1]); o2.y = pk2(q2[2], q2[3]); o2.z = pk2(q2[4], q2[5]); o2.w = pk2(q2[6], q2[7]);
;       *(u32x4*)(QS + j * 72 + c4 * 8) = o1; *(u32x4*)(QS + j * 72 + 32 + c4 * 8) = o2; }
; }
; __device__ __forceinline__ void ret1_task(const Params& p_, int l, int task, unsigned char* lds) {
;     const Params p = *kparams(); (void)p_;
;     const int n = task & 31, h = (task >> 5) & 7, b = task >> 8;
;     const float xf = p.rl_f[l * 8 + h], xb = p.rl_b[l * 8 + h];
;     const float l2f = -log1pf(expf(-xf)) * 1.4426950408889634f, l2b = -log1pf(expf(-xb)) * 1.4426950408889634f;
;     ret_stage<false>(p, b, h, n, lds, l2f, l2b);
;     __syncthreads();
;     const int tid = otid(), lane = tid & 63, w = tid >> 6, fr = lane & 15, fq = lane >> 4, dir = w >> 2, et = w & 3;
;     const bf16* VT = (const bf16*)(lds + R_VT); const bf16* KT = (const bf16*)(lds + (dir ? R_KTB : R_KTF));
;     bf16x8v a[4];
; #pragma unroll
	ds_write_b16_d16_hi v15, v12 offset:55632
	v_mul_f32_e32 v12, v22, v0
	v_bfe_u32 v17, v12, 16, 1
	v_add3_u32 v12, v12, v17, s14
	v_mad_u32_u24 v14, v45, s4, v189
	ds_write_b16_d16_hi v13, v12 offset:55632
	v_mul_f32_e32 v12, v30, v10
	v_add_u32_e32 v16, v14, v44
	v_bfe_u32 v17, v12, 16, 1
	v_add3_u32 v12, v12, v17, s14
	v_lshl_add_u32 v16, v16, 1, s9
	ds_write_b16_d16_hi v16, v12
	v_mul_f32_e32 v12, v22, v10
	v_add_u32_e32 v14, v14, v11
	v_bfe_u32 v16, v12, 16, 1
	v_add3_u32 v12, v12, v16, s14
	v_lshl_add_u32 v14, v14, 1, s9
	ds_write_b16_d16_hi v14, v12
	v_mul_f32_e32 v12, v35, v0
	v_bfe_u32 v14, v12, 16, 1
	v_add3_u32 v12, v12, v14, s14
	ds_write_b16_d16_hi v15, v12 offset:55904
	v_mul_f32_e32 v12, v21, v0
	v_bfe_u32 v17, v12, 16, 1
	v_add3_u32 v12, v12, v17, s14
	v_mad_u32_u24 v14, v45, s4, v190
	ds_write_b16_d16_hi v13, v12 offset:55904
	v_mul_f32_e32 v12, v35, v10
	v_add_u32_e32 v16, v14, v44
	v_bfe_u32 v17, v12, 16, 1
	v_add3_u32 v12, v12, v17, s14
	v_lshl_add_u32 v16, v16, 1, s9
	ds_write_b16_d16_hi v16, v12
	v_mul_f32_e32 v12, v21, v10
	v_add_u32_e32 v14, v14, v11
	v_bfe_u32 v16, v12, 16, 1
	v_add3_u32 v12, v12, v16, s14
	v_lshl_add_u32 v14, v14, 1, s9
	ds_write_b16_d16_hi v14, v12
	v_mul_f32_e32 v12, v31, v0
	v_bfe_u32 v14, v12, 16, 1
	v_add3_u32 v12, v12, v14, s14
	v_mul_f32_e32 v0, v23, v0
	ds_write_b16_d16_hi v15, v12 offset:56176
	v_bfe_u32 v12, v0, 16, 1
	v_add3_u32 v0, v0, v12, s14
	v_mad_u32_u24 v14, v45, s4, v191
	ds_write_b16_d16_hi v13, v0 offset:56176
	v_mul_f32_e32 v0, v31, v10
	v_add_u32_e32 v16, v14, v44
	v_bfe_u32 v12, v0, 16, 1
	v_add3_u32 v0, v0, v12, s14
	v_lshl_add_u32 v12, v16, 1, s9
	ds_write_b16_d16_hi v12, v0
	v_mul_f32_e32 v0, v23, v10
	v_add_u32_e32 v11, v14, v11
	v_bfe_u32 v10, v0, 16, 1
	v_add3_u32 v0, v0, v10, s14
	v_lshl_add_u32 v10, v11, 1, s9
	ds_write_b16_d16_hi v10, v0
	v_mul_u32_u24_e32 v10, 0x880, v45
	v_lshlrev_b32_e32 v0, 1, v44
	v_lshlrev_b32_e32 v10, 1, v10
	v_add3_u32 v11, 0, v0, v10
	v_add3_u32 v0, 0, v10, v0
	s_waitcnt vmcnt(1)
	ds_write_b16 v11, v6 offset:36864
	ds_write_b16_d16_hi v0, v6 offset:37136
	ds_write_b16 v11, v7 offset:37408
	ds_write_b16_d16_hi v0, v7 offset:37680
	ds_write_b16 v11, v8 offset:37952
	ds_write_b16_d16_hi v0, v8 offset:38224
	ds_write_b16 v11, v9 offset:38496
	ds_write_b16_d16_hi v0, v9 offset:38768
	s_waitcnt vmcnt(0)
	ds_write_b16 v11, v2 offset:39040
	ds_write_b16_d16_hi v0, v2 offset:39312
	ds_write_b16 v11, v3 offset:39584
	ds_write_b16_d16_hi v0, v3 offset:39856
	ds_write_b16 v11, v4 offset:40128
	ds_write_b16_d16_hi v0, v4 offset:40400
	ds_write_b16 v11, v5 offset:40672
	ds_write_b16_d16_hi v0, v5 offset:40944
	s_waitcnt lgkmcnt(0)
	s_barrier
	v_mov_b32 v18, v147
	s_movk_i32 s9, 0x100
	v_lshrrev_b32_e32 v2, 2, v18
	v_and_b32_e32 v0, 15, v18
	v_cmp_gt_u32_e32 vcc, s9, v18
	v_and_b32_e32 v21, 48, v2
	v_bfe_u32 v20, v18, 4, 2
	v_cndmask_b32_e32 v19, v192, v193, vcc
	v_or_b32_e32 v2, v21, v0
	v_mul_u32_u24_e32 v2, 0x110, v2
	v_lshlrev_b32_e32 v22, 4, v20
	v_add_u32_e32 v23, 0, v19
	v_mul_u32_u24_e32 v24, 0x110, v0
	v_add3_u32 v2, 0, v2, v22
	v_add3_u32 v22, v23, v22, v24
	ds_read_b128 v[14:17], v2 offset:36864
	ds_read_b128 v[10:13], v2 offset:36928
	ds_read_b128 v[6:9], v2 offset:36992
	ds_read_b128 v[2:5], v2 offset:37056
	ds_read_b128 v[24:27], v22
	ds_read_b128 v[28:31], v22 offset:64
	s_waitcnt lgkmcnt(1)
	v_mfma_f32_16x16x32_bf16 v[24:27], v[14:17], v[24:27], 0
	v_ashrrev_i32_e32 v18, 7, v18
	v_and_b32_e32 v18, 0x1ffffffe, v18
	v_or_b32_e32 v18, s42, v18
	s_waitcnt lgkmcnt(0)
	v_mfma_f32_16x16x32_bf16 v[24:27], v[10:13], v[28:31], v[24:27]
	ds_read_b128 v[28:31], v22 offset:128
	v_lshl_or_b32 v18, v18, 3, s41
	v_ashrrev_i32_e32 v19, 31, v18
	s_waitcnt lgkmcnt(0)
	v_mfma_f32_16x16x32_bf16 v[24:27], v[6:9], v[28:31], v[24:27]
	ds_read_b128 v[28:31], v22 offset:192
	v_lshlrev_b64 v[18:19], 19, v[18:19]
	v_lshl_add_u64 v[18:19], s[38:39], 0, v[18:19]
	s_waitcnt lgkmcnt(0)
	v_mfma_f32_16x16x32_bf16 v[24:27], v[2:5], v[28:31], v[24:27]
	v_lshlrev_b32_e32 v20, 8, v20
	v_lshlrev_b32_e32 v21, 6, v21
	v_lshl_add_u64 v[18:19], v[18:19], 0, s[24:25]
	v_or3_b32 v0, v20, v21, v0
	v_lshl_add_u64 v[18:19], v[18:19], 0, s[18:19]
	v_lshlrev_b32_e32 v0, 2, v0
	v_lshl_add_u64 v[20:21], v[18:19], 0, v[0:1]
	s_nop 0
	global_store_dword v[20:21], v24, off
	global_store_dword v[20:21], v25, off offset:256
	global_store_dword v[20:21], v26, off offset:512
	global_store_dword v[20:21], v27, off offset:768
	ds_read_b128 v[24:27], v22 offset:4352
	ds_read_b128 v[28:31], v22 offset:4416
	s_waitcnt lgkmcnt(1)
	v_mfma_f32_16x16x32_bf16 v[24:27], v[14:17], v[24:27], 0
	s_waitcnt lgkmcnt(0)
	v_mfma_f32_16x16x32_bf16 v[24:27], v[10:13], v[28:31], v[24:27]
	ds_read_b128 v[28:31], v22 offset:4480
	s_waitcnt lgkmcnt(0)
	v_mfma_f32_16x16x32_bf16 v[24:27], v[6:9], v[28:31], v[24:27]
	ds_read_b128 v[28:31], v22 offset:4544
	s_waitcnt lgkmcnt(0)
	v_mfma_f32_16x16x32_bf16 v[24:27], v[2:5], v[28:31], v[24:27]
	v_or_b32_e32 v28, 64, v0
	v_mov_b32_e32 v29, v1
	v_lshl_add_u64 v[28:29], v[18:19], 0, v[28:29]
	s_nop 4
	global_store_dword v[20:21], v24, off offset:64
	global_store_dword v[28:29], v25, off offset:256
	global_store_dword v[28:29], v26, off offset:512
	global_store_dword v[28:29], v27, off offset:768
	ds_read_b128 v[24:27], v22 offset:8704
	ds_read_b128 v[28:31], v22 offset:8768
	s_waitcnt lgkmcnt(1)
	v_mfma_f32_16x16x32_bf16 v[24:27], v[14:17], v[24:27], 0
	s_waitcnt lgkmcnt(0)
	v_mfma_f32_16x16x32_bf16 v[24:27], v[10:13], v[28:31], v[24:27]
	ds_read_b128 v[28:31], v22 offset:8832
	s_waitcnt lgkmcnt(0)
	v_mfma_f32_16x16x32_bf16 v[24:27], v[6:9], v[28:31], v[24:27]
	ds_read_b128 v[28:31], v22 offset:8896
	s_waitcnt lgkmcnt(0)
	v_mfma_f32_16x16x32_bf16 v[24:27], v[2:5], v[28:31], v[24:27]
	v_or_b32_e32 v28, 0x80, v0
	v_mov_b32_e32 v29, v1
	v_lshl_add_u64 v[28:29], v[18:19], 0, v[28:29]
	s_nop 4
	global_store_dword v[20:21], v24, off offset:128
	global_store_dword v[28:29], v25, off offset:256
	global_store_dword v[28:29], v26, off offset:512
	global_store_dword v[28:29], v27, off offset:768
	ds_read_b128 v[24:27], v22 offset:13056
	s_waitcnt lgkmcnt(0)
	v_mfma_f32_16x16x32_bf16 v[14:17], v[14:17], v[24:27], 0
	ds_read_b128 v[24:27], v22 offset:13120
	v_or_b32_e32 v0, 0xc0, v0
	s_waitcnt lgkmcnt(0)
	v_mfma_f32_16x16x32_bf16 v[10:13], v[10:13], v[24:27], v[14:17]
	s_nop 3
	ds_read_b128 v[14:17], v22 offset:13184
	s_waitcnt lgkmcnt(0)
	v_mfma_f32_16x16x32_bf16 v[6:9], v[6:9], v[14:17], v[10:13]
	s_nop 2
	ds_read_b128 v[10:13], v22 offset:13248
	s_waitcnt lgkmcnt(0)
	v_mfma_f32_16x16x32_bf16 v[2:5], v[2:5], v[10:13], v[6:9]
	s_nop 2
	v_lshl_add_u64 v[6:7], v[18:19], 0, v[0:1]
	s_nop 3
	global_store_dword v[20:21], v2, off offset:192
	global_store_dword v[6:7], v3, off offset:256
	global_store_dword v[6:7], v4, off offset:512
	global_store_dword v[6:7], v5, off offset:768
	s_barrier
	s_cbranch_scc0 .LBB0_369

; __device__ __forceinline__ void na2_task(const Params& p_, int l, int task, unsigned char* lds) {
;     ...
;     { const int pair = lane & 31, chunk = (lane >> 5) + 2 * (w & 3);
;       unsigned* VTd = (unsigned*)(VT + (size_t)hh * 64 * 520);
;       u32x4 xs[8], ys[8];
; #pragma unroll
;       for (int a = 0; a < 8; ++a) { const size_t tok = (size_t)b * SEQ + (row_start + a) * 64 + 2 * pair;
;           const bf16* src = Z + tok * DIN + 4 * DG + h * 64 + chunk * 8; xs[a] = *(const u32x4*)src; ys[a] = *(const u32x4*)(src + DIN); }
;       asm volatile("" ::: "memory");
; #pragma unroll
;       for (int a = 0; a < 8; ++a) { const unsigned xu[4] = {xs[a].x, xs[a].y, xs[a].z, xs[a].w}, yu[4] = {ys[a].x, ys[a].y, ys[a].z, ys[a].w};
; #pragma unroll
;           for (int i = 0; i < 4; ++i) { VTd[(chunk * 8 + 2 * i) * 260 + a * 32 + pair] = (xu[i] & 0xffffu) | (yu[i] << 16);
;               VTd[(chunk * 8 + 2 * i + 1) * 260 + a * 32 + pair] = (xu[i] >> 16) | (yu[i] & 0xffff0000u); } } }
;     __syncthreads();
;     const int col_start = min(max(c - 8, 0), 48);
;     const float* bi = BI + hh * 465;
;     float sc[16][4]; float mx = -1e30f;
; #pragma unroll
;     for (int hf = 0; hf < 2; ++hf) {
;         if (hf == 1) {
; #pragma unroll
;             for (int i = 0; i < 8; ++i) { const int a = 4 + i / 2, ci = i % 2;
;                 const size_t ktok = (size_t)b * SEQ + (row_start + a) * 64 + kst + 16 * ci + fr;
; #pragma unroll
;                 for (int ks = 0; ks < 2; ++ks) kfr[i][ks] = *(const bf16x8v*)(Z + ktok * DIN + 3 * DG + h * 64 + 32 * ks + 8 * fq); }
; __device__ __forceinline__ void ph_mixA(const Params& p, int l, unsigned char* lds) {
;     ...
;     const int xcd = bid & 7, slot = bid >> 3, nloc = (slot < 16) ? 1 : 3, r0 = (slot < 16) ? slot : 16 + (slot - 16) * 3;
;     if (G == 256 && REP_NA == 1) {
;         for (int i = 0; i < nloc; ++i) { const int rq = (slot < 16) ? slot : 16 + i * 16 + (slot - 16);
;             na2_task(p, l, (xcd >> 2) * 256 + rq * 4 + (xcd & 3), lds); }
.LBB0_383:
	s_and_b32 s10, s92, 7
	s_andn2_b64 vcc, exec, s[40:41]
	s_ashr_i32 s68, s92, 3
	s_cbranch_vccnz .LBB0_395
	s_cmp_gt_i32 s68, 15
	s_cselect_b64 s[56:57], -1, 0
	s_cbranch_scc0 .LBB0_394
	s_lshl_b32 s9, s10, 6
	s_and_b32 s70, s9, 0x100
	s_lshl_b32 s9, s92, 1
	s_and_b32 s71, s9, 6
	s_or_b32 s3, s71, s3
	v_readlane_b32 s12, v255, 38
	s_and_b32 s9, s92, 3
	s_mul_i32 s24, s3, 0x1d1
	v_readlane_b32 s13, v255, 39
	s_mul_i32 s3, s12, 0xe88
	s_mulk_i32 s9, 0x3a2
	s_add_i32 s12, s3, s9
	s_mov_b32 s13, s25
	s_lshl_b64 s[58:59], s[12:13], 2
	s_mov_b32 s3, 0
	s_lshl_b64 s[60:61], s[24:25], 2
	s_movk_i32 s6, 0x1ff
	s_movk_i32 s26, 0x3a2
	v_readlane_b32 s27, v255, 23
	v_readlane_b32 s67, v255, 24
	s_branch .LBB0_386
.LBB0_385:
	v_bfe_u32 v172, v86, 3, 5
	v_lshl_or_b32 v88, v172, 1, s42
	v_or_b32_e32 v81, s24, v88
	v_mov_b64_e32 v[86:87], s[40:41]
	v_and_b32_e32 v173, 7, v90
	v_lshlrev_b32_e32 v173, 3, v173
	v_mad_u64_u32 v[94:95], s[40:41], v81, s75, v[86:87]
	v_mad_i32_i24 v95, s43, v195, v95
	v_mov_b32_e32 v89, s43
	v_lshl_add_u64 v[94:95], v[94:95], 0, v[76:77]
	v_lshlrev_b32_e32 v164, 1, v173
	v_mov_b32_e32 v165, v1
	v_lshl_add_u64 v[94:95], v[94:95], 0, v[164:165]
	v_lshl_add_u64 v[102:103], v[88:89], 0, s[44:45]
	v_add_co_u32_e32 v96, vcc, s74, v94
	v_mad_u64_u32 v[104:105], s[40:41], v102, s75, v[86:87]
	s_nop 0
	v_addc_co_u32_e32 v97, vcc, 0, v95, vcc
	v_mad_i32_i24 v105, v103, s75, v105
	v_add_co_u32_e32 v98, vcc, s7, v94
	v_lshl_add_u64 v[102:103], v[104:105], 0, v[76:77]
	s_nop 0
	v_addc_co_u32_e32 v99, vcc, 0, v95, vcc
	v_lshl_add_u64 v[102:103], v[102:103], 0, v[164:165]
	global_load_dwordx4 v[94:97], v[96:97], off
	s_nop 0
	global_load_dwordx4 v[98:101], v[98:99], off offset:1024
	v_add_co_u32_e32 v104, vcc, s74, v102
	v_lshl_add_u64 v[110:111], v[88:89], 0, s[46:47]
	s_nop 0
	v_addc_co_u32_e32 v105, vcc, 0, v103, vcc
	v_add_co_u32_e32 v106, vcc, s7, v102
	v_mad_u64_u32 v[112:113], s[40:41], v110, s75, v[86:87]
	s_nop 0
	v_addc_co_u32_e32 v107, vcc, 0, v103, vcc
	global_load_dwordx4 v[102:105], v[104:105], off
	s_nop 0
	global_load_dwordx4 v[106:109], v[106:107], off offset:1024
	v_mad_i32_i24 v113, v111, s75, v113
	v_lshl_add_u64 v[110:111], v[112:113], 0, v[76:77]
	v_lshl_add_u64 v[110:111], v[110:111], 0, v[164:165]
	v_lshl_add_u64 v[118:119], v[88:89], 0, s[48:49]
	v_add_co_u32_e32 v112, vcc, s74, v110
	v_mad_u64_u32 v[120:121], s[40:41], v118, s75, v[86:87]
	s_nop 0
	v_addc_co_u32_e32 v113, vcc, 0, v111, vcc
	v_mad_i32_i24 v121, v119, s75, v121
	v_add_co_u32_e32 v114, vcc, s7, v110
	v_lshl_add_u64 v[118:119], v[120:121], 0, v[76:77]
	s_nop 0
	v_addc_co_u32_e32 v115, vcc, 0, v111, vcc
	v_lshl_add_u64 v[118:119], v[118:119], 0, v[164:165]
	v_add_co_u32_e32 v120, vcc, s74, v118
	global_load_dwordx4 v[110:113], v[112:113], off
	s_nop 0
	global_load_dwordx4 v[114:117], v[114:115], off offset:1024
	v_addc_co_u32_e32 v121, vcc, 0, v119, vcc
	v_add_co_u32_e32 v122, vcc, s7, v118
	s_add_i32 s44, s24, 0x100
	s_nop 0
	v_addc_co_u32_e32 v123, vcc, 0, v119, vcc
	global_load_dwordx4 v[118:121], v[120:121], off
	s_nop 0
	global_load_dwordx4 v[122:125], v[122:123], off offset:1024
	s_mov_b32 s45, s25
	v_lshl_add_u64 v[126:127], v[88:89], 0, s[44:45]
	v_mad_u64_u32 v[128:129], s[40:41], v126, s75, v[86:87]
	v_mad_i32_i24 v129, v127, s75, v129
	v_lshl_add_u64 v[126:127], v[128:129], 0, v[76:77]
	s_add_i32 s42, s24, 0x140
	s_mov_b32 s43, s25
	v_lshl_add_u64 v[126:127], v[126:127], 0, v[164:165]
	v_lshl_add_u64 v[134:135], v[88:89], 0, s[42:43]
	v_add_co_u32_e32 v128, vcc, s74, v126
	v_mad_u64_u32 v[136:137], s[40:41], v134, s75, v[86:87]
	s_nop 0
	v_addc_co_u32_e32 v129, vcc, 0, v127, vcc
	v_mad_i32_i24 v137, v135, s75, v137
	v_add_co_u32_e32 v130, vcc, s7, v126
	v_lshl_add_u64 v[134:135], v[136:137], 0, v[76:77]
	s_nop 0
	v_addc_co_u32_e32 v131, vcc, 0, v127, vcc
	v_lshl_add_u64 v[134:135], v[134:135], 0, v[164:165]
	v_add_co_u32_e32 v136, vcc, s74, v134
	global_load_dwordx4 v[126:129], v[128:129], off
	s_nop 0
	global_load_dwordx4 v[130:133], v[130:131], off offset:1024
	v_addc_co_u32_e32 v137, vcc, 0, v135, vcc
	v_add_co_u32_e32 v138, vcc, s7, v134
	s_add_i32 s40, s24, 0x180
	s_nop 0
	v_addc_co_u32_e32 v139, vcc, 0, v135, vcc
	global_load_dwordx4 v[134:137], v[136:137], off
	s_nop 0
	global_load_dwordx4 v[138:141], v[138:139], off offset:1024
	s_mov_b32 s41, s25
	v_lshl_add_u64 v[142:143], v[88:89], 0, s[40:41]
	v_mad_u64_u32 v[144:145], s[46:47], v142, s75, v[86:87]
	v_mad_i32_i24 v145, v143, s75, v145
	v_lshl_add_u64 v[142:143], v[144:145], 0, v[76:77]
	s_addk_i32 s24, 0x1c0
	v_lshl_add_u64 v[142:143], v[142:143], 0, v[164:165]
	v_lshl_add_u64 v[88:89], v[88:89], 0, s[24:25]
	v_add_co_u32_e32 v144, vcc, s74, v142
	v_mad_u64_u32 v[166:167], s[46:47], v88, s75, v[86:87]
	s_nop 0
	v_addc_co_u32_e32 v145, vcc, 0, v143, vcc
	v_mad_i32_i24 v167, v89, s75, v167
	v_add_co_u32_e32 v160, vcc, s7, v142
	v_lshl_add_u64 v[88:89], v[166:167], 0, v[76:77]
	s_nop 0
	v_addc_co_u32_e32 v161, vcc, 0, v143, vcc
	v_lshl_add_u64 v[88:89], v[88:89], 0, v[164:165]
	v_add_co_u32_e32 v164, vcc, s74, v88
	global_load_dwordx4 v[142:145], v[144:145], off
	s_nop 0
	global_load_dwordx4 v[160:163], v[160:161], off offset:1024
	v_addc_co_u32_e32 v165, vcc, 0, v89, vcc
	v_add_co_u32_e32 v88, vcc, s7, v88
	s_mov_b32 s13, 0x10400
	s_nop 0
	v_addc_co_u32_e32 v89, vcc, 0, v89, vcc
	global_load_dwordx4 v[164:167], v[164:165], off
	s_nop 0
	global_load_dwordx4 v[168:171], v[88:89], off offset:1024
	v_add_u32_e32 v208, s44, v82
	v_mad_u64_u32 v[206:207], s[98:99], v208, s75, v[86:87]
	v_lshl_add_u64 v[206:207], v[206:207], 0, v[76:77]
	v_lshl_add_u64 v[206:207], v[206:207], 0, v[252:253]
	global_load_dwordx4 v[210:213], v[206:207], off offset:3072
	global_load_dwordx4 v[214:217], v[206:207], off offset:3136
	v_add_u32_e32 v208, s44, v84
	v_mad_u64_u32 v[206:207], s[98:99], v208, s75, v[86:87]
	v_lshl_add_u64 v[206:207], v[206:207], 0, v[76:77]
	v_lshl_add_u64 v[206:207], v[206:207], 0, v[252:253]
	global_load_dwordx4 v[218:221], v[206:207], off offset:3072
	global_load_dwordx4 v[222:225], v[206:207], off offset:3136
	v_add_u32_e32 v208, s42, v82
	v_mad_u64_u32 v[206:207], s[98:99], v208, s75, v[86:87]
	v_lshl_add_u64 v[206:207], v[206:207], 0, v[76:77]
	v_lshl_add_u64 v[206:207], v[206:207], 0, v[252:253]
	global_load_dwordx4 v[226:229], v[206:207], off offset:3072
	global_load_dwordx4 v[230:233], v[206:207], off offset:3136
	v_add_u32_e32 v208, s42, v84
	v_mad_u64_u32 v[206:207], s[98:99], v208, s75, v[86:87]
	v_lshl_add_u64 v[206:207], v[206:207], 0, v[76:77]
	v_lshl_add_u64 v[206:207], v[206:207], 0, v[252:253]
	global_load_dwordx4 v[234:237], v[206:207], off offset:3072
	global_load_dwordx4 v[238:241], v[206:207], off offset:3136
	v_add_u32_e32 v208, s40, v82
	v_mad_u64_u32 v[206:207], s[98:99], v208, s75, v[86:87]
	v_lshl_add_u64 v[206:207], v[206:207], 0, v[76:77]
	v_lshl_add_u64 v[206:207], v[206:207], 0, v[252:253]
	global_load_dwordx4 v[242:245], v[206:207], off offset:3072
	s_waitcnt vmcnt(27)
; __device__ __forceinline__ void na2_task(const Params& p_, int l, int task, unsigned char* lds) {
;     ...
;     for (int i = 0; i < 8; ++i) { const int a = i / 2, ci = i % 2;
;         const size_t ktok = (size_t)b * SEQ + (row_start + a) * 64 + kst + 16 * ci + fr;
; #pragma unroll
;         for (int ks = 0; ks < 2; ++ks) kfr[i][ks] = *(const bf16x8v*)(Z + ktok * DIN + 3 * DG + h * 64 + 32 * ks + 8 * fq); }
;     asm volatile("" ::: "memory");
;     for (int i = tid; i < 930; i += NTHR) BI[i] = p.na_bias[(size_t)(l * 8 + hp * 2) * 465 + i];
;     { const int pair = lane & 31, chunk = (lane >> 5) + 2 * (w & 3);
;       unsigned* VTd = (unsigned*)(VT + (size_t)hh * 64 * 520);
;       u32x4 xs[8], ys[8];
; #pragma unroll
;       for (int a = 0; a < 8; ++a) { const size_t tok = (size_t)b * SEQ + (row_start + a) * 64 + 2 * pair;
;           const bf16* src = Z + tok * DIN + 4 * DG + h * 64 + chunk * 8; xs[a] = *(const u32x4*)src; ys[a] = *(const u32x4*)(src + DIN); }
;       asm volatile("" ::: "memory");
; #pragma unroll
;       for (int a = 0; a < 8; ++a) { const unsigned xu[4] = {xs[a].x, xs[a].y, xs[a].z, xs[a].w}, yu[4] = {ys[a].x, ys[a].y, ys[a].z, ys[a].w};
; #pragma unroll
;           for (int i = 0; i < 4; ++i) { VTd[(chunk * 8 + 2 * i) * 260 + a * 32 + pair] = (xu[i] & 0xffffu) | (yu[i] << 16);
;               VTd[(chunk * 8 + 2 * i + 1) * 260 + a * 32 + pair] = (xu[i] >> 16) | (yu[i] & 0xffff0000u); } } }
	ds_bpermute_b32 v70, v251, v70
	ds_bpermute_b32 v71, v251, v71
	ds_bpermute_b32 v72, v251, v72
	ds_bpermute_b32 v73, v251, v73
	ds_bpermute_b32 v66, v251, v66
	ds_bpermute_b32 v67, v251, v67
	ds_bpermute_b32 v68, v251, v68
	ds_bpermute_b32 v69, v251, v69
	ds_bpermute_b32 v62, v251, v62
	ds_bpermute_b32 v63, v251, v63
	ds_bpermute_b32 v64, v251, v64
	ds_bpermute_b32 v65, v251, v65
	ds_bpermute_b32 v58, v251, v58
	ds_bpermute_b32 v59, v251, v59
	ds_bpermute_b32 v60, v251, v60
	ds_bpermute_b32 v61, v251, v61
	ds_bpermute_b32 v18, v251, v18
	ds_bpermute_b32 v19, v251, v19
	ds_bpermute_b32 v20, v251, v20
	ds_bpermute_b32 v21, v251, v21
	ds_bpermute_b32 v10, v251, v10
	ds_bpermute_b32 v11, v251, v11
	ds_bpermute_b32 v12, v251, v12
	ds_bpermute_b32 v13, v251, v13
	ds_bpermute_b32 v38, v251, v38
	ds_bpermute_b32 v39, v251, v39
	ds_bpermute_b32 v40, v251, v40
	ds_bpermute_b32 v41, v251, v41
	ds_bpermute_b32 v22, v251, v22
	ds_bpermute_b32 v23, v251, v23
	ds_bpermute_b32 v24, v251, v24
	ds_bpermute_b32 v25, v251, v25
	ds_bpermute_b32 v54, v251, v54
	ds_bpermute_b32 v55, v251, v55
	ds_bpermute_b32 v56, v251, v56
	ds_bpermute_b32 v57, v251, v57
	ds_bpermute_b32 v42, v251, v42
	ds_bpermute_b32 v43, v251, v43
	ds_bpermute_b32 v44, v251, v44
	ds_bpermute_b32 v45, v251, v45
	ds_bpermute_b32 v46, v251, v46
	ds_bpermute_b32 v47, v251, v47
	ds_bpermute_b32 v48, v251, v48
	ds_bpermute_b32 v49, v251, v49
	ds_bpermute_b32 v30, v251, v30
	ds_bpermute_b32 v31, v251, v31
	ds_bpermute_b32 v32, v251, v32
	ds_bpermute_b32 v33, v251, v33
	ds_bpermute_b32 v26, v251, v26
	ds_bpermute_b32 v27, v251, v27
	ds_bpermute_b32 v28, v251, v28
	ds_bpermute_b32 v29, v251, v29
	ds_bpermute_b32 v14, v251, v14
	ds_bpermute_b32 v15, v251, v15
	ds_bpermute_b32 v16, v251, v16
	ds_bpermute_b32 v17, v251, v17
	ds_bpermute_b32 v50, v251, v50
	ds_bpermute_b32 v51, v251, v51
	ds_bpermute_b32 v52, v251, v52
	ds_bpermute_b32 v53, v251, v53
	ds_bpermute_b32 v34, v251, v34
	ds_bpermute_b32 v35, v251, v35
	ds_bpermute_b32 v36, v251, v36
	ds_bpermute_b32 v37, v251, v37
	s_waitcnt vmcnt(9)
	s_waitcnt lgkmcnt(0)
	v_and_b32_e32 v89, 0xffff, v94
	v_lshrrev_b32_e32 v94, 16, v94
	v_lshl_or_b32 v89, v98, 16, v89
	v_and_or_b32 v94, v98, s15, v94
	v_and_b32_e32 v98, 0xffff, v95
	v_lshrrev_b32_e32 v95, 16, v95
	v_lshl_or_b32 v98, v99, 16, v98
	v_and_or_b32 v95, v99, s15, v95
	v_and_b32_e32 v99, 0xffff, v96
	v_lshrrev_b32_e32 v96, 16, v96
	v_lshlrev_b32_e32 v88, 2, v172
	v_mul_u32_u24_e32 v172, 0x104, v173
	v_lshl_or_b32 v99, v100, 16, v99
	v_and_or_b32 v96, v100, s15, v96
	v_and_b32_e32 v100, 0xffff, v97
	v_lshrrev_b32_e32 v97, 16, v97
	v_mad_i32_i24 v81, v93, s13, 0
	v_lshlrev_b32_e32 v172, 2, v172
	v_lshl_or_b32 v100, v101, 16, v100
	v_and_or_b32 v97, v101, s15, v97
	v_and_b32_e32 v101, 0xffff, v102
	v_add3_u32 v173, v81, v88, v172
	v_lshl_or_b32 v101, v106, 16, v101
	v_add3_u32 v88, v81, v172, v88
	ds_write2_b32 v173, v89, v101 offset1:32
	v_lshrrev_b32_e32 v89, 16, v102
	v_and_or_b32 v89, v106, s15, v89
	v_add_u32_e32 v101, 0x400, v88
	ds_write2_b32 v101, v94, v89 offset0:4 offset1:36
	v_and_b32_e32 v89, 0xffff, v103
	v_lshl_or_b32 v89, v107, 16, v89
	v_add_u32_e32 v94, 0x800, v173
	ds_write2_b32 v94, v98, v89 offset0:8 offset1:40
	v_lshrrev_b32_e32 v89, 16, v103
	v_and_or_b32 v89, v107, s15, v89
	v_add_u32_e32 v98, 0xc00, v88
	ds_write2_b32 v98, v95, v89 offset0:12 offset1:44
	v_and_b32_e32 v89, 0xffff, v104
	v_lshl_or_b32 v89, v108, 16, v89
	v_add_u32_e32 v95, 0x1000, v173
	ds_write2_b32 v95, v99, v89 offset0:16 offset1:48
	v_lshrrev_b32_e32 v89, 16, v104
	v_and_or_b32 v89, v108, s15, v89
	v_add_u32_e32 v99, 0x1400, v88
	ds_write2_b32 v99, v96, v89 offset0:20 offset1:52
	v_and_b32_e32 v89, 0xffff, v105
	v_lshl_or_b32 v89, v109, 16, v89
	v_add_u32_e32 v96, 0x1800, v173
	ds_write2_b32 v96, v100, v89 offset0:24 offset1:56
	v_lshrrev_b32_e32 v89, 16, v105
	v_and_or_b32 v89, v109, s15, v89
	v_add_u32_e32 v88, 0x1c00, v88
	ds_write2_b32 v88, v97, v89 offset0:28 offset1:60
	v_and_b32_e32 v89, 0xffff, v110
	v_and_b32_e32 v107, 0xffff, v118
	v_lshl_or_b32 v89, v114, 16, v89
	v_lshl_or_b32 v107, v122, 16, v107
	v_lshrrev_b32_e32 v97, 16, v110
	ds_write2_b32 v173, v89, v107 offset0:64 offset1:96
	v_lshrrev_b32_e32 v89, 16, v118
	v_and_or_b32 v97, v114, s15, v97
	v_and_or_b32 v89, v122, s15, v89
	v_and_b32_e32 v100, 0xffff, v111
	ds_write2_b32 v101, v97, v89 offset0:68 offset1:100
	v_and_b32_e32 v89, 0xffff, v119
	v_lshl_or_b32 v100, v115, 16, v100
	v_lshl_or_b32 v89, v123, 16, v89
	v_lshrrev_b32_e32 v102, 16, v111
	ds_write2_b32 v94, v100, v89 offset0:72 offset1:104
	v_lshrrev_b32_e32 v89, 16, v119
	v_and_or_b32 v102, v115, s15, v102
	v_and_or_b32 v89, v123, s15, v89
	v_and_b32_e32 v103, 0xffff, v112
	ds_write2_b32 v98, v102, v89 offset0:76 offset1:108
	v_and_b32_e32 v89, 0xffff, v120
	v_lshl_or_b32 v103, v116, 16, v103
	v_lshl_or_b32 v89, v124, 16, v89
	v_lshrrev_b32_e32 v104, 16, v112
	ds_write2_b32 v95, v103, v89 offset0:80 offset1:112
	v_lshrrev_b32_e32 v89, 16, v120
	v_and_or_b32 v104, v116, s15, v104
	v_and_or_b32 v89, v124, s15, v89
	v_and_b32_e32 v105, 0xffff, v113
	ds_write2_b32 v99, v104, v89 offset0:84 offset1:116
	v_and_b32_e32 v89, 0xffff, v121
	v_lshl_or_b32 v105, v117, 16, v105
	v_lshl_or_b32 v89, v125, 16, v89
	v_lshrrev_b32_e32 v106, 16, v113
	ds_write2_b32 v96, v105, v89 offset0:88 offset1:120
	v_lshrrev_b32_e32 v89, 16, v121
	v_and_or_b32 v106, v117, s15, v106
	v_and_or_b32 v89, v125, s15, v89
	ds_write2_b32 v88, v106, v89 offset0:92 offset1:124
	v_and_b32_e32 v89, 0xffff, v126
	v_and_b32_e32 v107, 0xffff, v134
	v_lshl_or_b32 v89, v130, 16, v89
	v_lshl_or_b32 v107, v138, 16, v107
; #define MFMA16(a, b, c) __builtin_amdgcn_mfma_f32_16x16x32_bf16(a, b, c, 0, 0, 0)
; __device__ __forceinline__ void na2_task(const Params& p_, int l, int task, unsigned char* lds) {
;     ...
;       for (int a = 0; a < 8; ++a) { const unsigned xu[4] = {xs[a].x, xs[a].y, xs[a].z, xs[a].w}, yu[4] = {ys[a].x, ys[a].y, ys[a].z, ys[a].w};
; #pragma unroll
;           for (int i = 0; i < 4; ++i) { VTd[(chunk * 8 + 2 * i) * 260 + a * 32 + pair] = (xu[i] & 0xffffu) | (yu[i] << 16);
;               VTd[(chunk * 8 + 2 * i + 1) * 260 + a * 32 + pair] = (xu[i] >> 16) | (yu[i] & 0xffff0000u); } } }
;     __syncthreads();
;     const int col_start = min(max(c - 8, 0), 48);
;     const float* bi = BI + hh * 465;
;     float sc[16][4]; float mx = -1e30f;
; #pragma unroll
;     for (int hf = 0; hf < 2; ++hf) {
;         if (hf == 1) {
; #pragma unroll
;             for (int i = 0; i < 8; ++i) { const int a = 4 + i / 2, ci = i % 2;
;                 const size_t ktok = (size_t)b * SEQ + (row_start + a) * 64 + kst + 16 * ci + fr;
; #pragma unroll
;                 for (int ks = 0; ks < 2; ++ks) kfr[i][ks] = *(const bf16x8v*)(Z + ktok * DIN + 3 * DG + h * 64 + 32 * ks + 8 * fq); }
;             asm volatile("" ::: "memory");
;         }
; #pragma unroll
;         for (int i = 0; i < 8; ++i) { const int a = 4 * hf + i / 2, ci = i % 2, kt = a * 2 + ci;
;             f32x4 acc = {0.f, 0.f, 0.f, 0.f};
; #pragma unroll
;             for (int ks = 0; ks < 2; ++ks) acc = MFMA16(kfr[i][ks], qf[ks], acc);
;             const int dr = row_start + a - rq;
; #pragma unroll
;             for (int r = 0; r < 4; ++r) { const int kc = kst + 16 * ci + 4 * fq + r, rel = kc - col_start, dc = kc - c;
;                 float v = acc[r] * 0.125f + bi[(dr + 7) * 31 + min(max(dc + 15, 0), 30)];
;                 v = (rel >= 0 && rel < 16) ? v : -1e30f; sc[kt][r] = v; mx = fmaxf(mx, v); } }
	v_lshrrev_b32_e32 v97, 16, v126
	ds_write2_b32 v173, v89, v107 offset0:128 offset1:160
	v_lshrrev_b32_e32 v89, 16, v134
	v_and_or_b32 v97, v130, s15, v97
	v_and_or_b32 v89, v138, s15, v89
	v_and_b32_e32 v100, 0xffff, v127
	ds_write2_b32 v101, v97, v89 offset0:132 offset1:164
	v_and_b32_e32 v89, 0xffff, v135
	v_lshl_or_b32 v100, v131, 16, v100
	v_lshl_or_b32 v89, v139, 16, v89
	v_lshrrev_b32_e32 v102, 16, v127
	ds_write2_b32 v94, v100, v89 offset0:136 offset1:168
	v_lshrrev_b32_e32 v89, 16, v135
	v_and_or_b32 v102, v131, s15, v102
	v_and_or_b32 v89, v139, s15, v89
	v_and_b32_e32 v103, 0xffff, v128
	ds_write2_b32 v98, v102, v89 offset0:140 offset1:172
	v_and_b32_e32 v89, 0xffff, v136
	v_lshl_or_b32 v103, v132, 16, v103
	v_lshl_or_b32 v89, v140, 16, v89
	v_lshrrev_b32_e32 v104, 16, v128
	ds_write2_b32 v95, v103, v89 offset0:144 offset1:176
	v_lshrrev_b32_e32 v89, 16, v136
	v_and_or_b32 v104, v132, s15, v104
	v_and_or_b32 v89, v140, s15, v89
	v_and_b32_e32 v105, 0xffff, v129
	ds_write2_b32 v99, v104, v89 offset0:148 offset1:180
	v_and_b32_e32 v89, 0xffff, v137
	v_lshl_or_b32 v105, v133, 16, v105
	v_lshl_or_b32 v89, v141, 16, v89
	v_lshrrev_b32_e32 v106, 16, v129
	ds_write2_b32 v96, v105, v89 offset0:152 offset1:184
	v_lshrrev_b32_e32 v89, 16, v137
	v_and_or_b32 v106, v133, s15, v106
	v_and_or_b32 v89, v141, s15, v89
	ds_write2_b32 v88, v106, v89 offset0:156 offset1:188
	v_and_b32_e32 v89, 0xffff, v142
	v_and_b32_e32 v107, 0xffff, v164
	v_lshl_or_b32 v89, v160, 16, v89
	v_lshl_or_b32 v107, v168, 16, v107
	v_lshrrev_b32_e32 v97, 16, v142
	ds_write2_b32 v173, v89, v107 offset0:192 offset1:224
	v_lshrrev_b32_e32 v89, 16, v164
	v_and_or_b32 v97, v160, s15, v97
	v_and_or_b32 v89, v168, s15, v89
	v_and_b32_e32 v100, 0xffff, v143
	ds_write2_b32 v101, v97, v89 offset0:196 offset1:228
	v_and_b32_e32 v89, 0xffff, v165
	v_lshl_or_b32 v100, v161, 16, v100
	v_lshl_or_b32 v89, v169, 16, v89
	v_lshrrev_b32_e32 v102, 16, v143
	ds_write2_b32 v94, v100, v89 offset0:200 offset1:232
	v_lshrrev_b32_e32 v89, 16, v165
	v_and_or_b32 v102, v161, s15, v102
	v_and_or_b32 v89, v169, s15, v89
	v_and_b32_e32 v103, 0xffff, v144
	ds_write2_b32 v98, v102, v89 offset0:204 offset1:236
	v_and_b32_e32 v89, 0xffff, v166
	v_lshl_or_b32 v103, v162, 16, v103
	v_lshl_or_b32 v89, v170, 16, v89
	v_lshrrev_b32_e32 v104, 16, v144
	ds_write2_b32 v95, v103, v89 offset0:208 offset1:240
	v_lshrrev_b32_e32 v89, 16, v166
	v_and_or_b32 v104, v162, s15, v104
	v_and_or_b32 v89, v170, s15, v89
	v_and_b32_e32 v105, 0xffff, v145
	ds_write2_b32 v99, v104, v89 offset0:212 offset1:244
	v_and_b32_e32 v89, 0xffff, v167
	v_lshl_or_b32 v105, v163, 16, v105
	v_lshl_or_b32 v89, v171, 16, v89
	v_mfma_f32_16x16x32_bf16 v[62:65], v[62:65], v[6:9], 0
	v_lshrrev_b32_e32 v106, 16, v145
	ds_write2_b32 v96, v105, v89 offset0:216 offset1:248
	v_lshrrev_b32_e32 v89, 16, v167
	s_sub_i32 s9, s12, s9
	v_mfma_f32_16x16x32_bf16 v[70:73], v[70:73], v[6:9], 0
	v_lshl_add_u32 v168, v92, 2, v80
	v_and_or_b32 v106, v163, s15, v106
	v_and_or_b32 v89, v171, s15, v89
	s_mulk_i32 s9, 0x7c
	v_add_u32_e32 v169, 16, v168
	ds_write2_b32 v88, v106, v89 offset0:220 offset1:252
	s_add_i32 s9, s9, 0
	v_sub_u32_e32 v88, v169, v91
	s_add_i32 s9, s9, 0x20800
	v_mfma_f32_16x16x32_bf16 v[58:61], v[58:61], v[2:5], v[62:65]
	v_add_u32_e32 v173, 17, v168
	v_add_u32_e32 v174, 18, v168
	v_or_b32_e32 v170, 1, v168
	v_max_i32_e32 v62, -15, v88
	v_mfma_f32_16x16x32_bf16 v[94:97], v[66:69], v[2:5], v[70:73]
	v_mov_b32_e32 v66, s9
	s_movk_i32 s9, 0x744
	v_add_u32_e32 v62, 15, v62
	v_mad_i32_i24 v98, v93, s9, v66
	v_min_u32_e32 v62, 30, v62
	v_lshl_add_u32 v103, v62, 2, v98
	v_sub_u32_e32 v62, v173, v91
	v_mfma_f32_16x16x32_bf16 v[18:21], v[18:21], v[6:9], 0
	v_max_i32_e32 v62, -15, v62
	v_add_u32_e32 v62, 15, v62
	v_min_u32_e32 v62, 30, v62
	v_lshl_add_u32 v104, v62, 2, v98
	v_mfma_f32_16x16x32_bf16 v[62:65], v[10:13], v[2:5], v[18:21]
	v_sub_u32_e32 v10, v174, v91
	v_or_b32_e32 v171, 2, v168
	v_or_b32_e32 v172, 3, v168
	v_max_i32_e32 v18, -15, v10
	v_mfma_f32_16x16x32_bf16 v[10:13], v[38:41], v[6:9], 0
	v_add_u32_e32 v175, 19, v168
	v_sub_u32_e32 v66, v168, v91
	v_sub_u32_e32 v68, v170, v91
	v_mfma_f32_16x16x32_bf16 v[38:41], v[22:25], v[2:5], v[10:13]
	v_sub_u32_e32 v70, v171, v91
	v_sub_u32_e32 v72, v172, v91
	v_sub_u32_e32 v19, v175, v91
	v_mfma_f32_16x16x32_bf16 v[10:13], v[54:57], v[6:9], 0
	v_max_i32_e32 v66, -15, v66
	v_max_i32_e32 v68, -15, v68
	v_max_i32_e32 v70, -15, v70
	v_mfma_f32_16x16x32_bf16 v[42:45], v[42:45], v[2:5], v[10:13]
	v_max_i32_e32 v72, -15, v72
	v_max_i32_e32 v19, -15, v19
	v_add_u32_e32 v66, 15, v66
	v_mfma_f32_16x16x32_bf16 v[10:13], v[46:49], v[6:9], 0
	v_add_u32_e32 v68, 15, v68
	v_add_u32_e32 v70, 15, v70
	v_add_u32_e32 v72, 15, v72
	v_mfma_f32_16x16x32_bf16 v[46:49], v[30:33], v[2:5], v[10:13]
	v_add_u32_e32 v18, 15, v18
	v_add_u32_e32 v19, 15, v19
	v_lshlrev_b32_e32 v0, 3, v92
	v_mfma_f32_16x16x32_bf16 v[10:13], v[26:29], v[6:9], 0
	v_min_u32_e32 v66, 30, v66
	v_min_u32_e32 v68, 30, v68
	v_min_u32_e32 v70, 30, v70
	v_mfma_f32_16x16x32_bf16 v[54:57], v[14:17], v[2:5], v[10:13]
	v_min_u32_e32 v72, 30, v72
	v_min_u32_e32 v18, 30, v18
	v_min_u32_e32 v19, 30, v19
	v_mfma_f32_16x16x32_bf16 v[10:13], v[50:53], v[6:9], 0
	v_lshl_add_u32 v99, v66, 2, v98
	v_lshl_add_u32 v100, v68, 2, v98
	v_lshl_add_u32 v101, v70, 2, v98
	v_mfma_f32_16x16x32_bf16 v[50:53], v[34:37], v[2:5], v[10:13]
	v_lshl_add_u32 v102, v72, 2, v98
	v_lshl_add_u32 v18, v18, 2, v98
	v_lshl_add_u32 v19, v19, 2, v98
	s_nop 0
	v_lshl_add_u64 v[10:11], v[82:83], 0, s[44:45]
	v_mad_u64_u32 v[12:13], s[12:13], v10, s75, v[86:87]
	v_mov_b32_e32 v10, v13
	v_mad_u64_u32 v[10:11], s[12:13], v11, s75, v[10:11]
	v_mov_b32_e32 v13, v10
	v_lshl_add_u64 v[10:11], v[12:13], 0, v[76:77]
	v_mov_b32_e32 v12, v252
	v_mov_b32_e32 v13, v1
	v_add_u32_e32 v176, 0x400, v99
	v_add_u32_e32 v177, 0x400, v100
	v_add_u32_e32 v197, 0x400, v101
	v_add_u32_e32 v198, 0x400, v102
	v_add_u32_e32 v199, 0x400, v103
	v_add_u32_e32 v200, 0x400, v104
	v_add_u32_e32 v201, 0x400, v18
	v_add_u32_e32 v202, 0x400, v19
	v_lshl_add_u64 v[10:11], v[10:11], 0, v[12:13]
	ds_write_b32 v204, v203
	ds_write_b32 v205, v209
	s_waitcnt lgkmcnt(0)
	s_barrier
; #define MFMA16(a, b, c) __builtin_amdgcn_mfma_f32_16x16x32_bf16(a, b, c, 0, 0, 0)
; __device__ __forceinline__ void na2_task(const Params& p_, int l, int task, unsigned char* lds) {
;     ...
;     for (int hf = 0; hf < 2; ++hf) {
;         if (hf == 1) {
; #pragma unroll
;             for (int i = 0; i < 8; ++i) { const int a = 4 + i / 2, ci = i % 2;
;                 const size_t ktok = (size_t)b * SEQ + (row_start + a) * 64 + kst + 16 * ci + fr;
; #pragma unroll
;                 for (int ks = 0; ks < 2; ++ks) kfr[i][ks] = *(const bf16x8v*)(Z + ktok * DIN + 3 * DG + h * 64 + 32 * ks + 8 * fq); }
;             asm volatile("" ::: "memory");
;         }
; #pragma unroll
;         for (int i = 0; i < 8; ++i) { const int a = 4 * hf + i / 2, ci = i % 2, kt = a * 2 + ci;
;             f32x4 acc = {0.f, 0.f, 0.f, 0.f};
; #pragma unroll
;             for (int ks = 0; ks < 2; ++ks) acc = MFMA16(kfr[i][ks], qf[ks], acc);
;             const int dr = row_start + a - rq;
; #pragma unroll
;             for (int r = 0; r < 4; ++r) { const int kc = kst + 16 * ci + 4 * fq + r, rel = kc - col_start, dc = kc - c;
;                 float v = acc[r] * 0.125f + bi[(dr + 7) * 31 + min(max(dc + 15, 0), 30)];
;                 v = (rel >= 0 && rel < 16) ? v : -1e30f; sc[kt][r] = v; mx = fmaxf(mx, v); } }
	ds_read2_b32 v[66:67], v99 offset0:217 offset1:248
	ds_read2_b32 v[68:69], v100 offset0:217 offset1:248
	ds_read2_b32 v[70:71], v101 offset0:217 offset1:248
	ds_read2_b32 v[72:73], v102 offset0:217 offset1:248
	ds_read2_b32 v[88:89], v103 offset0:217 offset1:248
	ds_read2_b32 v[92:93], v104 offset0:217 offset1:248
	ds_read2_b32 v[134:135], v18 offset0:217 offset1:248
	ds_read2_b32 v[136:137], v19 offset0:217 offset1:248
	ds_read2_b32 v[138:139], v176 offset0:23 offset1:54
	ds_read2_b32 v[140:141], v177 offset0:23 offset1:54
	ds_read2_b32 v[142:143], v197 offset0:23 offset1:54
	ds_read2_b32 v[144:145], v198 offset0:23 offset1:54
	ds_read2_b32 v[160:161], v199 offset0:23 offset1:54
	ds_read2_b32 v[162:163], v200 offset0:23 offset1:54
	ds_read2_b32 v[164:165], v201 offset0:23 offset1:54
	ds_read2_b32 v[166:167], v202 offset0:23 offset1:54
	s_nop 0
	s_nop 0
	v_lshl_add_u64 v[10:11], v[84:85], 0, s[44:45]
	v_mad_u64_u32 v[14:15], s[12:13], v10, s75, v[86:87]
	v_mov_b32_e32 v10, v15
	v_mad_u64_u32 v[10:11], s[12:13], v11, s75, v[10:11]
	v_mov_b32_e32 v15, v10
	v_lshl_add_u64 v[10:11], v[14:15], 0, v[76:77]
	v_lshl_add_u64 v[10:11], v[10:11], 0, v[12:13]
	s_nop 0
	s_nop 0
	v_lshl_add_u64 v[10:11], v[82:83], 0, s[42:43]
	v_mad_u64_u32 v[14:15], s[12:13], v10, s75, v[86:87]
	v_mov_b32_e32 v10, v15
	v_mad_u64_u32 v[10:11], s[12:13], v11, s75, v[10:11]
	v_mov_b32_e32 v15, v10
	v_lshl_add_u64 v[10:11], v[14:15], 0, v[76:77]
	v_lshl_add_u64 v[10:11], v[10:11], 0, v[12:13]
	s_nop 0
	s_nop 0
	v_lshl_add_u64 v[10:11], v[84:85], 0, s[42:43]
	v_mad_u64_u32 v[14:15], s[12:13], v10, s75, v[86:87]
	v_mov_b32_e32 v10, v15
	v_mad_u64_u32 v[10:11], s[12:13], v11, s75, v[10:11]
	v_mov_b32_e32 v15, v10
	v_lshl_add_u64 v[10:11], v[14:15], 0, v[76:77]
	v_lshl_add_u64 v[10:11], v[10:11], 0, v[12:13]
	s_nop 0
	s_nop 0
	v_lshl_add_u64 v[10:11], v[82:83], 0, s[40:41]
	v_mad_u64_u32 v[14:15], s[12:13], v10, s75, v[86:87]
	v_mov_b32_e32 v10, v15
	v_mad_u64_u32 v[10:11], s[12:13], v11, s75, v[10:11]
	v_mov_b32_e32 v15, v10
	v_lshl_add_u64 v[10:11], v[14:15], 0, v[76:77]
	v_lshl_add_u64 v[10:11], v[10:11], 0, v[12:13]
	s_nop 0
	global_load_dwordx4 v[34:37], v[10:11], off offset:3136
	v_lshl_add_u64 v[10:11], v[84:85], 0, s[40:41]
	v_mad_u64_u32 v[14:15], s[12:13], v10, s75, v[86:87]
	v_mov_b32_e32 v10, v15
	v_mad_u64_u32 v[10:11], s[12:13], v11, s75, v[10:11]
	v_mov_b32_e32 v15, v10
	v_lshl_add_u64 v[10:11], v[14:15], 0, v[76:77]
	v_lshl_add_u64 v[10:11], v[10:11], 0, v[12:13]
	global_load_dwordx4 v[30:33], v[10:11], off offset:3072
	global_load_dwordx4 v[26:29], v[10:11], off offset:3136
	v_lshl_add_u64 v[10:11], v[82:83], 0, s[24:25]
	v_mad_u64_u32 v[14:15], s[12:13], v10, s75, v[86:87]
	v_mov_b32_e32 v10, v15
	v_mad_u64_u32 v[10:11], s[12:13], v11, s75, v[10:11]
	v_mov_b32_e32 v15, v10
	v_lshl_add_u64 v[10:11], v[14:15], 0, v[76:77]
	v_lshl_add_u64 v[10:11], v[10:11], 0, v[12:13]
	global_load_dwordx4 v[22:25], v[10:11], off offset:3072
	global_load_dwordx4 v[18:21], v[10:11], off offset:3136
	v_lshl_add_u64 v[10:11], v[84:85], 0, s[24:25]
	v_mad_u64_u32 v[14:15], s[12:13], v10, s75, v[86:87]
	v_mov_b32_e32 v10, v15
	v_mad_u64_u32 v[10:11], s[12:13], v11, s75, v[10:11]
	v_mov_b32_e32 v15, v10
	v_sub_u32_e64 v82, v91, 8 clamp
	v_lshl_add_u64 v[10:11], v[14:15], 0, v[76:77]
	v_min_u32_e32 v82, 48, v82
	v_lshl_add_u64 v[10:11], v[10:11], 0, v[12:13]
	v_sub_u32_e32 v84, v171, v82
	global_load_dwordx4 v[14:17], v[10:11], off offset:3072
	s_nop 0
	global_load_dwordx4 v[10:13], v[10:11], off offset:3136
	v_cmp_gt_u32_e64 s[46:47], 16, v84
	v_sub_u32_e32 v84, v172, v82
	v_sub_u32_e32 v83, v168, v82
	v_cmp_gt_u32_e64 s[42:43], 16, v84
	v_sub_u32_e32 v84, v169, v82
	v_cmp_gt_u32_e32 vcc, 16, v83
	v_sub_u32_e32 v83, v170, v82
	s_waitcnt lgkmcnt(11)
	v_fmamk_f32 v58, v58, 0x3e000000, v88
	v_cmp_gt_u32_e64 s[44:45], 16, v84
	v_fmamk_f32 v66, v94, 0x3e000000, v66
	v_fmamk_f32 v68, v95, 0x3e000000, v68
	v_cmp_gt_u32_e64 s[40:41], 16, v83
	v_cndmask_b32_e64 v84, v194, v58, s[44:45]
	v_sub_u32_e32 v58, v173, v82
	v_cndmask_b32_e32 v66, v194, v66, vcc
	v_cndmask_b32_e64 v68, v194, v68, s[40:41]
	s_mov_b32 s9, 0xf149f2ca
	v_fmamk_f32 v70, v96, 0x3e000000, v70
	v_fmamk_f32 v72, v97, 0x3e000000, v72
	s_waitcnt lgkmcnt(10)
	v_fmamk_f32 v59, v59, 0x3e000000, v92
	v_cmp_gt_u32_e64 s[48:49], 16, v58
	v_max3_f32 v83, v66, s9, v68
	v_cndmask_b32_e64 v70, v194, v70, s[46:47]
	v_cndmask_b32_e64 v72, v194, v72, s[42:43]
	v_cndmask_b32_e64 v85, v194, v59, s[48:49]
	v_sub_u32_e32 v59, v174, v82
	v_max3_f32 v83, v83, v70, v72
	s_waitcnt lgkmcnt(9)
	v_fmamk_f32 v60, v60, 0x3e000000, v134
	v_cmp_gt_u32_e64 s[50:51], 16, v59
	v_sub_u32_e32 v59, v175, v82
	v_max3_f32 v58, v83, v84, v85
	v_cndmask_b32_e64 v83, v194, v60, s[50:51]
	s_waitcnt lgkmcnt(8)
	v_fmamk_f32 v60, v61, 0x3e000000, v136
	v_cmp_gt_u32_e64 s[52:53], 16, v59
	v_fmac_f32_e32 v67, 0x3e000000, v62
	v_fmac_f32_e32 v69, 0x3e000000, v63
	v_cndmask_b32_e64 v82, v194, v60, s[52:53]
	v_fmac_f32_e32 v93, 0x3e000000, v39
	s_waitcnt lgkmcnt(7)
	v_fmamk_f32 v39, v42, 0x3e000000, v138
	v_max3_f32 v58, v58, v83, v82
	v_cndmask_b32_e32 v62, v194, v67, vcc
	v_cndmask_b32_e64 v63, v194, v69, s[40:41]
	v_fmac_f32_e32 v71, 0x3e000000, v64
	v_fmac_f32_e32 v73, 0x3e000000, v65
	v_fmac_f32_e32 v89, 0x3e000000, v38
	v_cndmask_b32_e32 v88, v194, v39, vcc
	s_waitcnt lgkmcnt(6)
	v_fmamk_f32 v39, v43, 0x3e000000, v140
	v_max3_f32 v58, v58, v62, v63
	v_cndmask_b32_e64 v67, v194, v71, s[46:47]
	v_cndmask_b32_e64 v69, v194, v73, s[42:43]
	v_cndmask_b32_e64 v71, v194, v89, s[44:45]
	v_cndmask_b32_e64 v89, v194, v39, s[40:41]
	s_waitcnt lgkmcnt(5)
; #define MFMA16(a, b, c) __builtin_amdgcn_mfma_f32_16x16x32_bf16(a, b, c, 0, 0, 0)
; __device__ __forceinline__ void na2_task(const Params& p_, int l, int task, unsigned char* lds) {
;     ...
;     for (int hf = 0; hf < 2; ++hf) {
;         if (hf == 1) {
; #pragma unroll
;             for (int i = 0; i < 8; ++i) { const int a = 4 + i / 2, ci = i % 2;
;                 const size_t ktok = (size_t)b * SEQ + (row_start + a) * 64 + kst + 16 * ci + fr;
; #pragma unroll
;                 for (int ks = 0; ks < 2; ++ks) kfr[i][ks] = *(const bf16x8v*)(Z + ktok * DIN + 3 * DG + h * 64 + 32 * ks + 8 * fq); }
;             asm volatile("" ::: "memory");
;         }
; #pragma unroll
;         for (int i = 0; i < 8; ++i) { const int a = 4 * hf + i / 2, ci = i % 2, kt = a * 2 + ci;
;             f32x4 acc = {0.f, 0.f, 0.f, 0.f};
; #pragma unroll
;             for (int ks = 0; ks < 2; ++ks) acc = MFMA16(kfr[i][ks], qf[ks], acc);
;             const int dr = row_start + a - rq;
; #pragma unroll
;             for (int r = 0; r < 4; ++r) { const int kc = kst + 16 * ci + 4 * fq + r, rel = kc - col_start, dc = kc - c;
;                 float v = acc[r] * 0.125f + bi[(dr + 7) * 31 + min(max(dc + 15, 0), 30)];
;                 v = (rel >= 0 && rel < 16) ? v : -1e30f; sc[kt][r] = v; mx = fmaxf(mx, v); } }
	v_fmamk_f32 v39, v44, 0x3e000000, v142
	v_max3_f32 v58, v58, v67, v69
	v_cndmask_b32_e64 v73, v194, v93, s[48:49]
	v_fmac_f32_e32 v135, 0x3e000000, v40
	v_fmac_f32_e32 v137, 0x3e000000, v41
	v_cndmask_b32_e64 v91, v194, v39, s[46:47]
	s_waitcnt lgkmcnt(4)
	v_fmamk_f32 v39, v45, 0x3e000000, v144
	v_max3_f32 v38, v58, v71, v73
	v_cndmask_b32_e64 v86, v194, v135, s[50:51]
	v_cndmask_b32_e64 v87, v194, v137, s[52:53]
	v_cndmask_b32_e64 v92, v194, v39, s[42:43]
	s_waitcnt lgkmcnt(3)
	v_fmamk_f32 v39, v46, 0x3e000000, v160
	v_max3_f32 v38, v38, v86, v87
	v_cndmask_b32_e64 v93, v194, v39, s[44:45]
	s_waitcnt lgkmcnt(2)
	v_fmamk_f32 v39, v47, 0x3e000000, v162
	v_max3_f32 v38, v38, v88, v89
	v_cndmask_b32_e64 v94, v194, v39, s[48:49]
	s_waitcnt lgkmcnt(1)
	v_fmamk_f32 v39, v48, 0x3e000000, v164
	v_max3_f32 v38, v38, v91, v92
	v_cndmask_b32_e64 v95, v194, v39, s[50:51]
	s_waitcnt lgkmcnt(0)
	v_fmamk_f32 v39, v49, 0x3e000000, v166
	v_max3_f32 v38, v38, v93, v94
	v_cndmask_b32_e64 v96, v194, v39, s[52:53]
	v_fmac_f32_e32 v139, 0x3e000000, v54
	v_fmac_f32_e32 v141, 0x3e000000, v55
	v_max3_f32 v38, v38, v95, v96
	v_cndmask_b32_e32 v97, v194, v139, vcc
	v_cndmask_b32_e64 v134, v194, v141, s[40:41]
	v_fmac_f32_e32 v143, 0x3e000000, v56
	v_fmac_f32_e32 v145, 0x3e000000, v57
	v_max3_f32 v38, v38, v97, v134
	v_cndmask_b32_e64 v135, v194, v143, s[46:47]
	v_cndmask_b32_e64 v136, v194, v145, s[42:43]
	v_fmac_f32_e32 v161, 0x3e000000, v50
	v_fmac_f32_e32 v163, 0x3e000000, v51
	v_max3_f32 v38, v38, v135, v136
	v_cndmask_b32_e64 v137, v194, v161, s[44:45]
	v_cndmask_b32_e64 v138, v194, v163, s[48:49]
	v_max3_f32 v42, v38, v137, v138
	s_waitcnt vmcnt(0)
	ds_bpermute_b32 v98, v251, v210
	ds_bpermute_b32 v99, v251, v211
	ds_bpermute_b32 v100, v251, v212
	ds_bpermute_b32 v101, v251, v213
	ds_bpermute_b32 v102, v251, v214
	ds_bpermute_b32 v103, v251, v215
	ds_bpermute_b32 v104, v251, v216
	ds_bpermute_b32 v105, v251, v217
	ds_bpermute_b32 v106, v251, v218
	ds_bpermute_b32 v107, v251, v219
	ds_bpermute_b32 v108, v251, v220
	ds_bpermute_b32 v109, v251, v221
	ds_bpermute_b32 v110, v251, v222
	ds_bpermute_b32 v111, v251, v223
	ds_bpermute_b32 v112, v251, v224
	ds_bpermute_b32 v113, v251, v225
	ds_bpermute_b32 v114, v251, v226
	ds_bpermute_b32 v115, v251, v227
	ds_bpermute_b32 v116, v251, v228
	ds_bpermute_b32 v117, v251, v229
	ds_bpermute_b32 v118, v251, v230
	ds_bpermute_b32 v119, v251, v231
	ds_bpermute_b32 v120, v251, v232
	ds_bpermute_b32 v121, v251, v233
	ds_bpermute_b32 v122, v251, v234
	ds_bpermute_b32 v123, v251, v235
	ds_bpermute_b32 v124, v251, v236
	ds_bpermute_b32 v125, v251, v237
	ds_bpermute_b32 v126, v251, v238
	ds_bpermute_b32 v127, v251, v239
	ds_bpermute_b32 v128, v251, v240
	ds_bpermute_b32 v129, v251, v241
	ds_bpermute_b32 v130, v251, v242
	ds_bpermute_b32 v131, v251, v243
	ds_bpermute_b32 v132, v251, v244
	ds_bpermute_b32 v133, v251, v245
	ds_bpermute_b32 v34, v251, v34
	ds_bpermute_b32 v35, v251, v35
	ds_bpermute_b32 v36, v251, v36
	ds_bpermute_b32 v37, v251, v37
	ds_bpermute_b32 v30, v251, v30
	ds_bpermute_b32 v31, v251, v31
	ds_bpermute_b32 v32, v251, v32
	ds_bpermute_b32 v33, v251, v33
	ds_bpermute_b32 v26, v251, v26
	ds_bpermute_b32 v27, v251, v27
	ds_bpermute_b32 v28, v251, v28
	ds_bpermute_b32 v29, v251, v29
	ds_bpermute_b32 v22, v251, v22
	ds_bpermute_b32 v23, v251, v23
	ds_bpermute_b32 v24, v251, v24
	ds_bpermute_b32 v25, v251, v25
	ds_bpermute_b32 v18, v251, v18
	ds_bpermute_b32 v19, v251, v19
	ds_bpermute_b32 v20, v251, v20
	ds_bpermute_b32 v21, v251, v21
	ds_bpermute_b32 v14, v251, v14
	ds_bpermute_b32 v15, v251, v15
	ds_bpermute_b32 v16, v251, v16
	ds_bpermute_b32 v17, v251, v17
	ds_bpermute_b32 v10, v251, v10
	ds_bpermute_b32 v11, v251, v11
	ds_bpermute_b32 v12, v251, v12
	ds_bpermute_b32 v13, v251, v13
	s_waitcnt lgkmcnt(0)
	v_mfma_f32_16x16x32_bf16 v[38:41], v[98:101], v[6:9], 0
	ds_read2_b32 v[46:47], v176 offset0:85 offset1:116
	ds_read2_b32 v[48:49], v177 offset0:85 offset1:116
	ds_read2_b32 v[50:51], v197 offset0:85 offset1:116
	s_waitcnt vmcnt(14)
	v_mfma_f32_16x16x32_bf16 v[38:41], v[102:105], v[2:5], v[38:41]
	v_fmac_f32_e32 v165, 0x3e000000, v52
	v_fmac_f32_e32 v167, 0x3e000000, v53
	ds_read2_b32 v[52:53], v198 offset0:85 offset1:116
	ds_read2_b32 v[54:55], v199 offset0:85 offset1:116
	ds_read2_b32 v[56:57], v200 offset0:85 offset1:116
	s_waitcnt lgkmcnt(5)
	s_nop 1
	v_fmamk_f32 v38, v38, 0x3e000000, v46
	v_cndmask_b32_e32 v98, v194, v38, vcc
	s_waitcnt lgkmcnt(4)
	v_fmamk_f32 v38, v39, 0x3e000000, v48
	v_cndmask_b32_e64 v48, v194, v38, s[40:41]
	s_waitcnt lgkmcnt(3)
	v_fmamk_f32 v38, v40, 0x3e000000, v50
	v_cndmask_b32_e64 v50, v194, v38, s[46:47]
	s_waitcnt lgkmcnt(2)
	v_fmamk_f32 v38, v41, 0x3e000000, v52
	v_cndmask_b32_e64 v52, v194, v38, s[42:43]
	s_waitcnt vmcnt(13)
	v_mfma_f32_16x16x32_bf16 v[38:41], v[106:109], v[6:9], 0
	v_cndmask_b32_e64 v139, v194, v165, s[50:51]
	v_cndmask_b32_e64 v140, v194, v167, s[52:53]
	ds_read2_b32 v[58:59], v201 offset0:85 offset1:116
	s_waitcnt vmcnt(12)
	v_mfma_f32_16x16x32_bf16 v[38:41], v[110:113], v[2:5], v[38:41]
	v_max3_f32 v42, v42, v139, v140
	ds_read2_b32 v[60:61], v202 offset0:85 offset1:116
	v_max3_f32 v42, v42, v98, v48
	v_max3_f32 v42, v42, v50, v52
	s_waitcnt vmcnt(5)
	v_mfma_f32_16x16x32_bf16 v[30:33], v[30:33], v[6:9], 0
	s_waitcnt lgkmcnt(3)
	s_nop 0
	v_fmamk_f32 v38, v38, 0x3e000000, v54
	v_cndmask_b32_e64 v54, v194, v38, s[44:45]
	s_waitcnt lgkmcnt(2)
	v_fmamk_f32 v38, v39, 0x3e000000, v56
	v_cndmask_b32_e64 v99, v194, v38, s[48:49]
	v_max3_f32 v38, v42, v54, v99
	v_mfma_f32_16x16x32_bf16 v[42:45], v[114:117], v[6:9], 0
	s_waitcnt lgkmcnt(1)
; #define MFMA16(a, b, c) __builtin_amdgcn_mfma_f32_16x16x32_bf16(a, b, c, 0, 0, 0)
; __device__ __forceinline__ void na2_task(const Params& p_, int l, int task, unsigned char* lds) {
;     ...
;         for (int i = 0; i < 8; ++i) { const int a = 4 * hf + i / 2, ci = i % 2, kt = a * 2 + ci;
;             f32x4 acc = {0.f, 0.f, 0.f, 0.f};
; #pragma unroll
;             for (int ks = 0; ks < 2; ++ks) acc = MFMA16(kfr[i][ks], qf[ks], acc);
;             const int dr = row_start + a - rq;
; #pragma unroll
;             for (int r = 0; r < 4; ++r) { const int kc = kst + 16 * ci + 4 * fq + r, rel = kc - col_start, dc = kc - c;
;                 float v = acc[r] * 0.125f + bi[(dr + 7) * 31 + min(max(dc + 15, 0), 30)];
;                 v = (rel >= 0 && rel < 16) ? v : -1e30f; sc[kt][r] = v; mx = fmaxf(mx, v); } }
;     }
;     mx = fmaxf(mx, __shfl_xor(mx, 16)); mx = fmaxf(mx, __shfl_xor(mx, 32));
	v_fmamk_f32 v39, v40, 0x3e000000, v58
	v_cndmask_b32_e64 v100, v194, v39, s[50:51]
	s_waitcnt lgkmcnt(0)
	v_fmamk_f32 v39, v41, 0x3e000000, v60
	v_cndmask_b32_e64 v101, v194, v39, s[52:53]
	v_max3_f32 v46, v38, v100, v101
	v_mfma_f32_16x16x32_bf16 v[38:41], v[118:121], v[2:5], v[42:45]
	v_lshl_add_u64 v[78:79], v[78:79], 0, v[0:1]
	s_mov_b32 s9, 0x12d20000
	v_mfma_f32_16x16x32_bf16 v[42:45], v[122:125], v[6:9], 0
	s_waitcnt vmcnt(4)
	v_mfma_f32_16x16x32_bf16 v[26:29], v[26:29], v[2:5], v[30:33]
	s_nop 2
	v_fmac_f32_e32 v47, 0x3e000000, v38
	v_fmac_f32_e32 v49, 0x3e000000, v39
	v_cndmask_b32_e32 v102, v194, v47, vcc
	v_cndmask_b32_e64 v49, v194, v49, s[40:41]
	v_fmac_f32_e32 v51, 0x3e000000, v40
	v_fmac_f32_e32 v53, 0x3e000000, v41
	v_max3_f32 v38, v46, v102, v49
	v_cndmask_b32_e64 v51, v194, v51, s[46:47]
	v_cndmask_b32_e64 v53, v194, v53, s[42:43]
	v_max3_f32 v46, v38, v51, v53
	v_mfma_f32_16x16x32_bf16 v[38:41], v[126:129], v[2:5], v[42:45]
	s_waitcnt vmcnt(3)
	v_mfma_f32_16x16x32_bf16 v[22:25], v[22:25], v[6:9], 0
	s_waitcnt vmcnt(2)
	v_mfma_f32_16x16x32_bf16 v[18:21], v[18:21], v[2:5], v[22:25]
	s_nop 3
	v_fmac_f32_e32 v55, 0x3e000000, v38
	v_fmac_f32_e32 v57, 0x3e000000, v39
	v_fmac_f32_e32 v59, 0x3e000000, v40
	v_fmac_f32_e32 v61, 0x3e000000, v41
	v_mfma_f32_16x16x32_bf16 v[38:41], v[130:133], v[6:9], 0
	v_cndmask_b32_e64 v55, v194, v55, s[44:45]
	v_cndmask_b32_e64 v103, v194, v57, s[48:49]
	v_max3_f32 v42, v46, v55, v103
	v_cndmask_b32_e64 v104, v194, v59, s[50:51]
	v_cndmask_b32_e64 v105, v194, v61, s[52:53]
	v_max3_f32 v46, v42, v104, v105
	ds_read2_b32 v[42:43], v176 offset0:147 offset1:178
	ds_read2_b32 v[44:45], v177 offset0:147 offset1:178
	v_mfma_f32_16x16x32_bf16 v[34:37], v[34:37], v[2:5], v[38:41]
	s_waitcnt lgkmcnt(1)
	v_fmac_f32_e32 v43, 0x3e000000, v18
	s_nop 0
	ds_read2_b32 v[38:39], v197 offset0:147 offset1:178
	s_waitcnt vmcnt(1)
	v_mfma_f32_16x16x32_bf16 v[6:9], v[14:17], v[6:9], 0
	s_nop 1
	v_fmamk_f32 v34, v34, 0x3e000000, v42
	v_cndmask_b32_e32 v42, v194, v34, vcc
	s_waitcnt lgkmcnt(1)
	v_fmamk_f32 v40, v35, 0x3e000000, v44
	ds_read2_b32 v[34:35], v198 offset0:147 offset1:178
	v_cndmask_b32_e64 v44, v194, v40, s[40:41]
	s_waitcnt lgkmcnt(1)
	v_fmamk_f32 v36, v36, 0x3e000000, v38
	v_max3_f32 v40, v46, v42, v44
	v_cndmask_b32_e64 v38, v194, v36, s[46:47]
	s_waitcnt lgkmcnt(0)
	v_fmamk_f32 v34, v37, 0x3e000000, v34
	v_cndmask_b32_e64 v34, v194, v34, s[42:43]
	v_max3_f32 v46, v40, v38, v34
	ds_read2_b32 v[36:37], v199 offset0:147 offset1:178
	ds_read2_b32 v[40:41], v200 offset0:147 offset1:178
	ds_read2_b32 v[30:31], v201 offset0:147 offset1:178
	s_waitcnt vmcnt(0)
	v_mfma_f32_16x16x32_bf16 v[2:5], v[10:13], v[2:5], v[6:9]
	v_fmac_f32_e32 v45, 0x3e000000, v19
	s_waitcnt lgkmcnt(2)
	v_fmamk_f32 v26, v26, 0x3e000000, v36
	v_cndmask_b32_e64 v36, v194, v26, s[44:45]
	s_waitcnt lgkmcnt(1)
	v_fmamk_f32 v26, v27, 0x3e000000, v40
	v_cndmask_b32_e64 v40, v194, v26, s[48:49]
	ds_read2_b32 v[26:27], v202 offset0:147 offset1:178
	s_waitcnt lgkmcnt(1)
	v_fmamk_f32 v28, v28, 0x3e000000, v30
	v_max3_f32 v32, v46, v36, v40
	v_cndmask_b32_e64 v106, v194, v28, s[50:51]
	v_cndmask_b32_e32 v43, v194, v43, vcc
	s_waitcnt lgkmcnt(0)
	v_fmamk_f32 v26, v29, 0x3e000000, v26
	v_cndmask_b32_e64 v107, v194, v26, s[52:53]
	v_max3_f32 v26, v32, v106, v107
	v_cndmask_b32_e64 v45, v194, v45, s[40:41]
	v_fmac_f32_e32 v39, 0x3e000000, v20
	v_fmac_f32_e32 v35, 0x3e000000, v21
	v_fmac_f32_e32 v31, 0x3e000000, v4
	v_and_b32_e32 v4, 64, v178
	v_max3_f32 v18, v26, v43, v45
	v_cndmask_b32_e64 v39, v194, v39, s[46:47]
	v_cndmask_b32_e64 v108, v194, v35, s[42:43]
	v_fmac_f32_e32 v37, 0x3e000000, v2
	v_fmac_f32_e32 v41, 0x3e000000, v3
	v_xor_b32_e32 v3, 16, v178
	v_add_u32_e32 v4, 64, v4
	v_max3_f32 v14, v18, v39, v108
	v_cndmask_b32_e64 v109, v194, v37, s[44:45]
	v_cndmask_b32_e64 v41, v194, v41, s[48:49]
	v_fmac_f32_e32 v27, 0x3e000000, v5
	v_cmp_lt_i32_e32 vcc, v3, v4
	v_max3_f32 v2, v14, v109, v41
	v_cndmask_b32_e64 v110, v194, v31, s[50:51]
	v_cndmask_b32_e64 v111, v194, v27, s[52:53]
	v_cndmask_b32_e32 v3, v178, v3, vcc
	v_max3_f32 v2, v2, v110, v111
	v_lshlrev_b32_e32 v112, 2, v3
	ds_bpermute_b32 v3, v112, v2
	s_waitcnt lgkmcnt(0)
	v_max_f32_e32 v3, v3, v3
	v_max_f32_e32 v2, v2, v3
	v_xor_b32_e32 v3, 32, v178
	v_cmp_lt_i32_e32 vcc, v3, v4
	s_nop 1
	v_cndmask_b32_e32 v3, v178, v3, vcc
	v_lshlrev_b32_e32 v113, 2, v3
	ds_bpermute_b32 v3, v113, v2
	s_waitcnt lgkmcnt(0)
; __device__ __forceinline__ unsigned pk2(float lo, float hi) { return f2bf(lo) | (f2bf(hi) << 16); }
; __device__ __forceinline__ void na2_task(const Params& p_, int l, int task, unsigned char* lds) {
;     ...
;     mx = fmaxf(mx, __shfl_xor(mx, 16)); mx = fmaxf(mx, __shfl_xor(mx, 32));
;     float sum = 0.f; unsigned pp[16][2];
; #pragma unroll
;     for (int kt = 0; kt < 16; ++kt) { const float e0 = __expf(sc[kt][0] - mx), e1 = __expf(sc[kt][1] - mx), e2 = __expf(sc[kt][2] - mx), e3 = __expf(sc[kt][3] - mx);
;         sum += (e0 + e1) + (e2 + e3); pp[kt][0] = pk2(e0, e1); pp[kt][1] = pk2(e2, e3); }
;     sum += __shfl_xor(sum, 16); sum += __shfl_xor(sum, 32);
;     const float inv = 1.f / sum;
	v_max_f32_e32 v3, v3, v3
	v_max_f32_e32 v114, v2, v3
	v_sub_f32_e32 v6, v84, v114
	v_mul_f32_e32 v6, 0x3fb8aa3b, v6
	v_sub_f32_e32 v3, v68, v114
	v_exp_f32_e32 v60, v6
	v_sub_f32_e32 v6, v85, v114
	v_mul_f32_e32 v3, 0x3fb8aa3b, v3
	v_mul_f32_e32 v6, 0x3fb8aa3b, v6
	v_sub_f32_e32 v2, v66, v114
	v_exp_f32_e32 v4, v3
	v_sub_f32_e32 v3, v70, v114
	v_sub_f32_e32 v5, v72, v114
	v_exp_f32_e32 v64, v6
	v_sub_f32_e32 v6, v83, v114
	v_mul_f32_e32 v2, 0x3fb8aa3b, v2
	v_mul_f32_e32 v3, 0x3fb8aa3b, v3
	v_mul_f32_e32 v5, 0x3fb8aa3b, v5
	v_mul_f32_e32 v6, 0x3fb8aa3b, v6
	v_exp_f32_e32 v2, v2
	v_exp_f32_e32 v3, v3
	v_exp_f32_e32 v5, v5
	v_exp_f32_e32 v61, v6
	v_sub_f32_e32 v6, v82, v114
	v_mul_f32_e32 v6, 0x3fb8aa3b, v6
	v_exp_f32_e32 v65, v6
	v_pk_add_f32 v[6:7], v[2:3], v[4:5]
	v_sub_f32_e32 v8, v87, v114
	v_add_f32_e32 v6, v6, v7
	v_add_f32_e32 v9, 0, v6
	v_pk_add_f32 v[6:7], v[60:61], v[64:65]
	v_mul_f32_e32 v8, 0x3fb8aa3b, v8
	v_pk_add_f32 v[6:7], v[6:7], v[6:7] op_sel_hi:[0,1]
	v_sub_f32_e32 v6, v62, v114
	v_mul_f32_e32 v6, 0x3fb8aa3b, v6
	v_exp_f32_e32 v84, v6
	v_sub_f32_e32 v6, v63, v114
	v_mul_f32_e32 v6, 0x3fb8aa3b, v6
	v_exp_f32_e32 v85, v6
	v_sub_f32_e32 v6, v67, v114
	v_mul_f32_e32 v6, 0x3fb8aa3b, v6
	v_exp_f32_e32 v115, v6
	v_sub_f32_e32 v6, v69, v114
	v_mul_f32_e32 v6, 0x3fb8aa3b, v6
	v_exp_f32_e32 v116, v6
	v_sub_f32_e32 v6, v71, v114
	v_mul_f32_e32 v6, 0x3fb8aa3b, v6
	v_exp_f32_e32 v12, v6
	v_sub_f32_e32 v6, v73, v114
	v_mul_f32_e32 v6, 0x3fb8aa3b, v6
	v_exp_f32_e32 v62, v6
	v_sub_f32_e32 v6, v86, v114
	v_mul_f32_e32 v6, 0x3fb8aa3b, v6
	v_exp_f32_e32 v6, v6
	v_exp_f32_e32 v8, v8
	v_add_f32_e32 v13, v84, v85
	v_add_f32_e32 v63, v115, v116
	v_pk_add_f32 v[10:11], v[12:13], v[62:63]
	v_pk_add_f32 v[14:15], v[6:7], v[8:9]
	v_sub_f32_e32 v7, v88, v114
	v_pk_add_f32 v[10:11], v[10:11], v[14:15]
	v_mul_f32_e32 v7, 0x3fb8aa3b, v7
	v_pk_add_f32 v[14:15], v[10:11], v[10:11] op_sel_hi:[0,1]
	v_exp_f32_e32 v10, v7
	v_sub_f32_e32 v7, v89, v114
	v_mul_f32_e32 v7, 0x3fb8aa3b, v7
	v_exp_f32_e32 v58, v7
	v_sub_f32_e32 v7, v91, v114
	v_mul_f32_e32 v7, 0x3fb8aa3b, v7
	v_exp_f32_e32 v11, v7
	v_sub_f32_e32 v7, v92, v114
	v_mul_f32_e32 v7, 0x3fb8aa3b, v7
	v_exp_f32_e32 v59, v7
	v_sub_f32_e32 v7, v93, v114
	v_mul_f32_e32 v7, 0x3fb8aa3b, v7
	v_exp_f32_e32 v13, v7
	v_sub_f32_e32 v7, v94, v114
	v_mul_f32_e32 v7, 0x3fb8aa3b, v7
	v_exp_f32_e32 v86, v7
	v_sub_f32_e32 v7, v95, v114
	v_mul_f32_e32 v7, 0x3fb8aa3b, v7
	v_exp_f32_e32 v87, v7
	v_sub_f32_e32 v7, v96, v114
	v_mul_f32_e32 v7, 0x3fb8aa3b, v7
	v_exp_f32_e32 v88, v7
	v_sub_f32_e32 v7, v97, v114
	v_pk_add_f32 v[16:17], v[10:11], v[58:59]
	v_mul_f32_e32 v7, 0x3fb8aa3b, v7
	v_pk_add_f32 v[18:19], v[16:17], v[16:17] op_sel_hi:[0,1]
	v_exp_f32_e32 v16, v7
	v_sub_f32_e32 v7, v134, v114
	v_mul_f32_e32 v7, 0x3fb8aa3b, v7
	v_exp_f32_e32 v20, v7
	v_sub_f32_e32 v7, v135, v114
	v_mul_f32_e32 v7, 0x3fb8aa3b, v7
	v_exp_f32_e32 v18, v7
	v_sub_f32_e32 v7, v136, v114
	v_mul_f32_e32 v7, 0x3fb8aa3b, v7
	v_exp_f32_e32 v14, v7
	v_sub_f32_e32 v7, v137, v114
	v_mul_f32_e32 v7, 0x3fb8aa3b, v7
	v_exp_f32_e32 v68, v7
	v_sub_f32_e32 v7, v138, v114
	v_mul_f32_e32 v7, 0x3fb8aa3b, v7
	v_exp_f32_e32 v72, v7
	v_sub_f32_e32 v7, v139, v114
	v_mul_f32_e32 v7, 0x3fb8aa3b, v7
	v_exp_f32_e32 v69, v7
	v_sub_f32_e32 v7, v140, v114
	v_mul_f32_e32 v7, 0x3fb8aa3b, v7
	v_exp_f32_e32 v73, v7
	v_sub_f32_e32 v7, v98, v114
	v_mul_f32_e32 v7, 0x3fb8aa3b, v7
	v_pk_add_f32 v[24:25], v[18:19], v[14:15]
	v_exp_f32_e32 v19, v7
	v_sub_f32_e32 v7, v48, v114
	v_add_f32_e32 v17, v13, v86
	v_add_f32_e32 v21, v87, v88
	v_mul_f32_e32 v7, 0x3fb8aa3b, v7
	v_pk_add_f32 v[22:23], v[16:17], v[20:21]
	v_exp_f32_e32 v21, v7
	v_sub_f32_e32 v7, v50, v114
	v_mul_f32_e32 v7, 0x3fb8aa3b, v7
	v_exp_f32_e32 v89, v7
	v_sub_f32_e32 v7, v52, v114
	v_mul_f32_e32 v7, 0x3fb8aa3b, v7
	v_exp_f32_e32 v91, v7
	v_sub_f32_e32 v7, v54, v114
	v_mul_f32_e32 v7, 0x3fb8aa3b, v7
	v_exp_f32_e32 v66, v7
	v_sub_f32_e32 v7, v99, v114
	v_pk_add_f32 v[22:23], v[22:23], v[24:25]
	v_mul_f32_e32 v7, 0x3fb8aa3b, v7
	v_pk_add_f32 v[56:57], v[22:23], v[22:23] op_sel_hi:[0,1]
	v_pk_add_f32 v[22:23], v[68:69], v[72:73]
	v_exp_f32_e32 v70, v7
	v_sub_f32_e32 v7, v100, v114
	v_pk_add_f32 v[46:47], v[22:23], v[22:23] op_sel_hi:[0,1]
	v_mul_f32_e32 v7, 0x3fb8aa3b, v7
	v_exp_f32_e32 v46, v7
	v_sub_f32_e32 v7, v101, v114
	v_mul_f32_e32 v7, 0x3fb8aa3b, v7
	v_exp_f32_e32 v56, v7
	v_add_f32_e32 v67, v19, v21
	v_add_f32_e32 v71, v89, v91
	v_pk_add_f32 v[22:23], v[66:67], v[70:71]
	v_pk_add_f32 v[24:25], v[46:47], v[56:57]
	v_sub_f32_e32 v7, v102, v114
	v_pk_add_f32 v[22:23], v[22:23], v[24:25]
	v_mul_f32_e32 v7, 0x3fb8aa3b, v7
	v_pk_add_f32 v[26:27], v[22:23], v[22:23] op_sel_hi:[0,1]
	v_exp_f32_e32 v22, v7
	v_sub_f32_e32 v7, v49, v114
	v_mul_f32_e32 v7, 0x3fb8aa3b, v7
	v_exp_f32_e32 v24, v7
	v_sub_f32_e32 v7, v51, v114
	v_mul_f32_e32 v7, 0x3fb8aa3b, v7
	v_exp_f32_e32 v23, v7
	v_sub_f32_e32 v7, v53, v114
	v_mul_f32_e32 v7, 0x3fb8aa3b, v7
	v_exp_f32_e32 v25, v7
	v_sub_f32_e32 v7, v55, v114
	v_mul_f32_e32 v7, 0x3fb8aa3b, v7
	v_exp_f32_e32 v67, v7
	v_sub_f32_e32 v7, v103, v114
	v_mul_f32_e32 v7, 0x3fb8aa3b, v7
	v_exp_f32_e32 v71, v7
	v_sub_f32_e32 v7, v104, v114
	v_mul_f32_e32 v7, 0x3fb8aa3b, v7
	v_exp_f32_e32 v92, v7
	v_sub_f32_e32 v7, v105, v114
	v_mul_f32_e32 v7, 0x3fb8aa3b, v7
	v_exp_f32_e32 v93, v7
	v_sub_f32_e32 v7, v42, v114
	v_pk_add_f32 v[28:29], v[22:23], v[24:25]
	v_mul_f32_e32 v7, 0x3fb8aa3b, v7
	v_pk_add_f32 v[30:31], v[28:29], v[28:29] op_sel_hi:[0,1]
	v_exp_f32_e32 v28, v7
	v_sub_f32_e32 v7, v44, v114
	v_mul_f32_e32 v7, 0x3fb8aa3b, v7
	v_exp_f32_e32 v32, v7
	v_sub_f32_e32 v7, v38, v114
	v_mul_f32_e32 v7, 0x3fb8aa3b, v7
; __device__ __forceinline__ unsigned pk2(float lo, float hi) { return f2bf(lo) | (f2bf(hi) << 16); }
; __device__ __forceinline__ float bflo(unsigned u) { return __uint_as_float(u << 16); }
; __device__ __forceinline__ float bfhi(unsigned u) { return __uint_as_float(u & 0xffff0000u); }
; __device__ __forceinline__ float silu_f(float v) { return v / (1.f + __expf(-v)); }
; #define MFMA16(a, b, c) __builtin_amdgcn_mfma_f32_16x16x32_bf16(a, b, c, 0, 0, 0)
; __device__ __forceinline__ void na2_task(const Params& p_, int l, int task, unsigned char* lds) {
;     ...
;     float sum = 0.f; unsigned pp[16][2];
; #pragma unroll
;     for (int kt = 0; kt < 16; ++kt) { const float e0 = __expf(sc[kt][0] - mx), e1 = __expf(sc[kt][1] - mx), e2 = __expf(sc[kt][2] - mx), e3 = __expf(sc[kt][3] - mx);
;         sum += (e0 + e1) + (e2 + e3); pp[kt][0] = pk2(e0, e1); pp[kt][1] = pk2(e2, e3); }
;     sum += __shfl_xor(sum, 16); sum += __shfl_xor(sum, 32);
;     const float inv = 1.f / sum;
;     const bf16* VTh = VT + (size_t)hh * 64 * 520;
; #pragma unroll
;     for (int dt = 0; dt < 4; ++dt) { f32x4 o = {0.f, 0.f, 0.f, 0.f};
; #pragma unroll
;         for (int t = 0; t < 8; ++t) { const int k0 = 2 * t, k1 = 2 * t + 1, a0 = k0 / 2, c0 = k0 % 2, a1 = k1 / 2, c1 = k1 % 2;
;             const u32x2 vlo = *(const u32x2*)(VTh + (16 * dt + fr) * 520 + a0 * 64 + kst + 16 * c0 + 4 * fq), vhi = *(const u32x2*)(VTh + (16 * dt + fr) * 520 + a1 * 64 + kst + 16 * c1 + 4 * fq);
;             o = MFMA16(mk8(vlo.x, vlo.y, vhi.x, vhi.y), mk8(pp[k0][0], pp[k0][1], pp[k1][0], pp[k1][1]), o); }
;         const u32x2 gz = *(const u32x2*)(Z + qtok * DIN + 5 * DG + h * 64 + 16 * dt + 4 * fq); u32x2 ov;
;         ov.x = pk2(o[0] * inv * silu_f(bflo(gz.x)), o[1] * inv * silu_f(bfhi(gz.x))); ov.y = pk2(o[2] * inv * silu_f(bflo(gz.y)), o[3] * inv * silu_f(bfhi(gz.y)));
;         *(u32x2*)(CAT + qtok * DM + 512 + h * 64 + 16 * dt + 4 * fq) = ov; }
	v_exp_f32_e32 v30, v7
	v_sub_f32_e32 v7, v34, v114
	v_mul_f32_e32 v7, 0x3fb8aa3b, v7
	v_exp_f32_e32 v26, v7
	v_sub_f32_e32 v7, v36, v114
	v_mul_f32_e32 v7, 0x3fb8aa3b, v7
	v_exp_f32_e32 v48, v7
	v_sub_f32_e32 v7, v40, v114
	v_mul_f32_e32 v7, 0x3fb8aa3b, v7
	v_exp_f32_e32 v52, v7
	v_sub_f32_e32 v7, v106, v114
	v_mul_f32_e32 v7, 0x3fb8aa3b, v7
	v_exp_f32_e32 v49, v7
	v_sub_f32_e32 v7, v107, v114
	v_mul_f32_e32 v7, 0x3fb8aa3b, v7
	v_exp_f32_e32 v53, v7
	v_sub_f32_e32 v7, v43, v114
	v_mul_f32_e32 v7, 0x3fb8aa3b, v7
	v_pk_add_f32 v[36:37], v[30:31], v[26:27]
	v_exp_f32_e32 v31, v7
	v_sub_f32_e32 v7, v45, v114
	v_add_f32_e32 v29, v67, v71
	v_add_f32_e32 v33, v92, v93
	v_mul_f32_e32 v7, 0x3fb8aa3b, v7
	v_pk_add_f32 v[34:35], v[28:29], v[32:33]
	v_exp_f32_e32 v33, v7
	v_sub_f32_e32 v7, v39, v114
	v_mul_f32_e32 v7, 0x3fb8aa3b, v7
	v_exp_f32_e32 v94, v7
	v_sub_f32_e32 v7, v108, v114
	v_mul_f32_e32 v7, 0x3fb8aa3b, v7
	v_exp_f32_e32 v95, v7
	v_sub_f32_e32 v7, v109, v114
	v_mul_f32_e32 v7, 0x3fb8aa3b, v7
	v_exp_f32_e32 v50, v7
	v_sub_f32_e32 v7, v41, v114
	v_pk_add_f32 v[34:35], v[34:35], v[36:37]
	v_mul_f32_e32 v7, 0x3fb8aa3b, v7
	v_pk_add_f32 v[36:37], v[34:35], v[34:35] op_sel_hi:[0,1]
	v_pk_add_f32 v[34:35], v[48:49], v[52:53]
	v_exp_f32_e32 v54, v7
	v_sub_f32_e32 v7, v110, v114
	v_pk_add_f32 v[34:35], v[34:35], v[34:35] op_sel_hi:[0,1]
	v_mul_f32_e32 v7, 0x3fb8aa3b, v7
	v_exp_f32_e32 v34, v7
	v_sub_f32_e32 v7, v111, v114
	v_mul_f32_e32 v7, 0x3fb8aa3b, v7
	v_exp_f32_e32 v36, v7
	v_add_f32_e32 v51, v31, v33
	v_add_f32_e32 v55, v94, v95
	v_pk_add_f32 v[38:39], v[50:51], v[54:55]
	v_pk_add_f32 v[40:41], v[34:35], v[36:37]
	v_bfe_u32 v35, v12, 16, 1
	v_pk_add_f32 v[38:39], v[38:39], v[40:41]
	v_bfe_u32 v37, v13, 16, 1
	v_add_f32_e32 v7, v38, v39
	ds_bpermute_b32 v9, v112, v7
	v_lshlrev_b64 v[38:39], 12, v[74:75]
	v_lshl_add_u64 v[38:39], s[62:63], 0, v[38:39]
	v_lshl_add_u64 v[38:39], v[38:39], 0, v[76:77]
	v_lshl_add_u64 v[42:43], v[38:39], 0, v[0:1]
	s_waitcnt lgkmcnt(0)
	v_add_f32_e32 v7, v7, v9
	ds_bpermute_b32 v9, v113, v7
	v_bfe_u32 v41, v87, 16, 1
	v_add3_u32 v41, v87, v41, s14
	v_add3_u32 v13, v13, v37, s14
	v_bfe_u32 v37, v69, 16, 1
	s_waitcnt lgkmcnt(0)
	v_add_f32_e32 v7, v7, v9
	v_div_scale_f32 v9, s[12:13], v7, v7, 1.0
	v_rcp_f32_e32 v15, v9
	v_bfe_u32 v51, v92, 16, 1
	v_add3_u32 v51, v92, v51, s14
	s_mov_b64 s[12:13], 0x1400
	v_fma_f32 v17, -v9, v15, 1.0
	v_fmac_f32_e32 v15, v17, v15
	v_div_scale_f32 v17, vcc, 1.0, v7, 1.0
	v_mul_f32_e32 v27, v17, v15
	v_fma_f32 v29, -v9, v27, v17
	v_fmac_f32_e32 v27, v29, v15
	v_fma_f32 v9, -v9, v27, v17
	v_div_fmas_f32 v9, v9, v15, v27
	v_div_fixup_f32 v40, v9, v7, 1.0
	v_lshl_add_u32 v7, v80, 1, v81
	v_mul_u32_u24_e32 v9, 0x410, v90
	v_add3_u32 v0, v7, v9, v0
	v_bfe_u32 v7, v65, 16, 1
	v_bfe_u32 v9, v64, 16, 1
	v_bfe_u32 v15, v5, 16, 1
	v_bfe_u32 v17, v4, 16, 1
	v_bfe_u32 v27, v60, 16, 1
	v_bfe_u32 v29, v61, 16, 1
	v_add3_u32 v17, v4, v17, s14
	v_add3_u32 v15, v5, v15, s14
	v_add3_u32 v4, v64, v9, s14
	v_add3_u32 v5, v65, v7, s14
	v_bfe_u32 v7, v2, 16, 1
	v_bfe_u32 v9, v3, 16, 1
	v_add3_u32 v29, v61, v29, s14
	v_add3_u32 v27, v60, v27, s14
	v_add3_u32 v3, v3, v9, s14
	v_add3_u32 v2, v2, v7, s14
	v_lshrrev_b32_e32 v7, 16, v27
	v_lshrrev_b32_e32 v9, 16, v29
	v_and_or_b32 v5, v5, s15, v9
	v_and_or_b32 v4, v4, s15, v7
	v_bfe_u32 v7, v8, 16, 1
	v_bfe_u32 v9, v62, 16, 1
	v_lshrrev_b32_e32 v3, 16, v3
	v_add3_u32 v7, v8, v7, s14
	v_add3_u32 v8, v62, v9, s14
	v_bfe_u32 v9, v6, 16, 1
	v_bfe_u32 v29, v115, 16, 1
	v_and_or_b32 v3, v15, s15, v3
	v_bfe_u32 v15, v116, 16, 1
	v_add3_u32 v6, v6, v9, s14
	v_add3_u32 v9, v12, v35, s14
	v_add3_u32 v12, v115, v29, s14
	v_add3_u32 v15, v116, v15, s14
	v_lshrrev_b32_e32 v6, 16, v6
	v_lshrrev_b32_e32 v12, 16, v12
	v_lshrrev_b32_e32 v29, 16, v9
	v_and_or_b32 v9, v7, s15, v6
	v_and_or_b32 v8, v8, s15, v29
	v_and_or_b32 v7, v15, s15, v12
	v_bfe_u32 v12, v88, 16, 1
	v_bfe_u32 v15, v86, 16, 1
	v_bfe_u32 v29, v10, 16, 1
	v_add3_u32 v15, v86, v15, s14
	v_add3_u32 v12, v88, v12, s14
	v_add3_u32 v10, v10, v29, s14
	v_lshrrev_b32_e32 v29, 16, v13
	v_lshrrev_b32_e32 v13, 16, v41
	v_and_or_b32 v13, v12, s15, v13
	v_and_or_b32 v12, v15, s15, v29
	v_bfe_u32 v15, v14, 16, 1
	v_bfe_u32 v29, v20, 16, 1
	v_add3_u32 v14, v14, v15, s14
	v_add3_u32 v20, v20, v29, s14
	v_bfe_u32 v15, v18, 16, 1
	v_bfe_u32 v29, v16, 16, 1
	v_add3_u32 v15, v18, v15, s14
	v_add3_u32 v16, v16, v29, s14
	v_lshrrev_b32_e32 v15, 16, v15
	v_lshrrev_b32_e32 v29, 16, v16
	v_and_or_b32 v15, v14, s15, v15
	v_and_or_b32 v14, v20, s15, v29
	v_bfe_u32 v29, v21, 16, 1
	v_add3_u32 v29, v21, v29, s14
	v_bfe_u32 v21, v46, 16, 1
	v_add3_u32 v21, v46, v21, s14
	v_add_co_u32_e32 v46, vcc, s74, v78
	ds_read2_b64 v[74:77], v0 offset1:4
	s_nop 0
	v_addc_co_u32_e32 v47, vcc, 0, v79, vcc
	global_load_dwordx2 v[46:47], v[46:47], off offset:1024
	ds_read2_b64 v[80:83], v0 offset0:16 offset1:20
	v_lshrrev_b32_e32 v2, 16, v2
	v_and_or_b32 v2, v17, s15, v2
	v_bfe_u32 v27, v84, 16, 1
	v_bfe_u32 v17, v85, 16, 1
	s_waitcnt lgkmcnt(1)
	v_mfma_f32_16x16x32_bf16 v[74:77], v[74:77], v[2:5], 0
	v_add3_u32 v27, v84, v27, s14
	v_add3_u32 v17, v85, v17, s14
	v_lshrrev_b32_e32 v27, 16, v27
	v_and_or_b32 v6, v17, s15, v27
	v_bfe_u32 v35, v11, 16, 1
	v_bfe_u32 v17, v59, 16, 1
	s_waitcnt lgkmcnt(0)
	v_mfma_f32_16x16x32_bf16 v[60:63], v[80:83], v[6:9], v[74:77]
	v_bfe_u32 v27, v58, 16, 1
	v_add3_u32 v11, v11, v35, s14
	v_add3_u32 v27, v58, v27, s14
	ds_read2_b64 v[74:77], v0 offset0:32 offset1:36
	v_add3_u32 v17, v59, v17, s14
	v_lshrrev_b32_e32 v10, 16, v10
	v_lshrrev_b32_e32 v11, 16, v11
	v_and_or_b32 v11, v17, s15, v11
	v_and_or_b32 v10, v27, s15, v10
	v_bfe_u32 v35, v68, 16, 1
	v_bfe_u32 v17, v73, 16, 1
	s_waitcnt lgkmcnt(0)
; __device__ __forceinline__ unsigned pk2(float lo, float hi) { return f2bf(lo) | (f2bf(hi) << 16); }
; __device__ __forceinline__ float bflo(unsigned u) { return __uint_as_float(u << 16); }
; __device__ __forceinline__ float bfhi(unsigned u) { return __uint_as_float(u & 0xffff0000u); }
; __device__ __forceinline__ float silu_f(float v) { return v / (1.f + __expf(-v)); }
; #define MFMA16(a, b, c) __builtin_amdgcn_mfma_f32_16x16x32_bf16(a, b, c, 0, 0, 0)
; __device__ __forceinline__ void na2_task(const Params& p_, int l, int task, unsigned char* lds) {
;     ...
; #pragma unroll
;     for (int dt = 0; dt < 4; ++dt) { f32x4 o = {0.f, 0.f, 0.f, 0.f};
; #pragma unroll
;         for (int t = 0; t < 8; ++t) { const int k0 = 2 * t, k1 = 2 * t + 1, a0 = k0 / 2, c0 = k0 % 2, a1 = k1 / 2, c1 = k1 % 2;
;             const u32x2 vlo = *(const u32x2*)(VTh + (16 * dt + fr) * 520 + a0 * 64 + kst + 16 * c0 + 4 * fq), vhi = *(const u32x2*)(VTh + (16 * dt + fr) * 520 + a1 * 64 + kst + 16 * c1 + 4 * fq);
;             o = MFMA16(mk8(vlo.x, vlo.y, vhi.x, vhi.y), mk8(pp[k0][0], pp[k0][1], pp[k1][0], pp[k1][1]), o); }
;         const u32x2 gz = *(const u32x2*)(Z + qtok * DIN + 5 * DG + h * 64 + 16 * dt + 4 * fq); u32x2 ov;
;         ov.x = pk2(o[0] * inv * silu_f(bflo(gz.x)), o[1] * inv * silu_f(bfhi(gz.x))); ov.y = pk2(o[2] * inv * silu_f(bflo(gz.y)), o[3] * inv * silu_f(bfhi(gz.y)));
;         *(u32x2*)(CAT + qtok * DM + 512 + h * 64 + 16 * dt + 4 * fq) = ov; }
	v_mfma_f32_16x16x32_bf16 v[58:61], v[74:77], v[10:13], v[60:63]
	v_bfe_u32 v27, v72, 16, 1
	v_add3_u32 v18, v69, v37, s14
	s_nop 0
	ds_read2_b64 v[62:65], v0 offset0:48 offset1:52
	v_add3_u32 v35, v68, v35, s14
	v_add3_u32 v27, v72, v27, s14
	v_add3_u32 v17, v73, v17, s14
	v_lshrrev_b32_e32 v16, 16, v35
	v_lshrrev_b32_e32 v18, 16, v18
	v_and_or_b32 v17, v17, s15, v18
	v_and_or_b32 v16, v27, s15, v16
	v_bfe_u32 v35, v19, 16, 1
	v_bfe_u32 v37, v89, 16, 1
	s_waitcnt lgkmcnt(0)
	v_mfma_f32_16x16x32_bf16 v[58:61], v[62:65], v[14:17], v[58:61]
	ds_read2_b64 v[62:65], v0 offset0:64 offset1:68
	v_bfe_u32 v41, v66, 16, 1
	v_bfe_u32 v18, v56, 16, 1
	v_bfe_u32 v20, v70, 16, 1
	v_bfe_u32 v27, v91, 16, 1
	v_add3_u32 v41, v66, v41, s14
	v_add3_u32 v37, v89, v37, s14
	v_add3_u32 v19, v19, v35, s14
	v_add3_u32 v18, v56, v18, s14
	v_add3_u32 v27, v91, v27, s14
	v_add3_u32 v20, v70, v20, s14
	v_lshrrev_b32_e32 v21, 16, v21
	v_lshrrev_b32_e32 v35, 16, v19
	v_lshrrev_b32_e32 v19, 16, v37
	v_lshrrev_b32_e32 v37, 16, v41
	v_and_or_b32 v21, v18, s15, v21
	v_and_or_b32 v20, v20, s15, v37
	v_and_or_b32 v19, v27, s15, v19
	v_and_or_b32 v18, v29, s15, v35
	v_bfe_u32 v27, v93, 16, 1
	v_bfe_u32 v29, v71, 16, 1
	s_waitcnt lgkmcnt(0)
	v_mfma_f32_16x16x32_bf16 v[56:59], v[62:65], v[18:21], v[58:61]
	v_bfe_u32 v35, v25, 16, 1
	v_bfe_u32 v37, v24, 16, 1
	v_add3_u32 v37, v24, v37, s14
	ds_read2_b64 v[60:63], v0 offset0:80 offset1:84
	v_add3_u32 v35, v25, v35, s14
	v_add3_u32 v24, v71, v29, s14
	v_add3_u32 v25, v93, v27, s14
	v_bfe_u32 v27, v22, 16, 1
	v_bfe_u32 v29, v23, 16, 1
	v_bfe_u32 v41, v67, 16, 1
	v_add3_u32 v41, v67, v41, s14
	v_add3_u32 v23, v23, v29, s14
	v_add3_u32 v22, v22, v27, s14
	v_lshrrev_b32_e32 v22, 16, v22
	v_lshrrev_b32_e32 v23, 16, v23
	v_lshrrev_b32_e32 v27, 16, v41
	v_lshrrev_b32_e32 v29, 16, v51
	v_and_or_b32 v25, v25, s15, v29
	v_and_or_b32 v24, v24, s15, v27
	v_and_or_b32 v23, v35, s15, v23
	v_and_or_b32 v22, v37, s15, v22
	v_bfe_u32 v27, v26, 16, 1
	v_bfe_u32 v37, v32, 16, 1
	s_waitcnt lgkmcnt(0)
	v_mfma_f32_16x16x32_bf16 v[56:59], v[60:63], v[22:25], v[56:59]
	ds_read2_b64 v[60:63], v0 offset0:96 offset1:100
	v_add3_u32 v26, v26, v27, s14
	v_add3_u32 v32, v32, v37, s14
	v_bfe_u32 v27, v30, 16, 1
	v_bfe_u32 v37, v28, 16, 1
	v_bfe_u32 v41, v48, 16, 1
	v_bfe_u32 v51, v49, 16, 1
	v_bfe_u32 v29, v53, 16, 1
	v_bfe_u32 v35, v52, 16, 1
	v_add3_u32 v27, v30, v27, s14
	v_add3_u32 v30, v49, v51, s14
	v_add3_u32 v41, v48, v41, s14
	v_add3_u32 v28, v28, v37, s14
	v_add3_u32 v35, v52, v35, s14
	v_add3_u32 v29, v53, v29, s14
	v_lshrrev_b32_e32 v27, 16, v27
	v_lshrrev_b32_e32 v37, 16, v28
	v_lshrrev_b32_e32 v28, 16, v41
	v_lshrrev_b32_e32 v30, 16, v30
	v_and_or_b32 v27, v26, s15, v27
	v_and_or_b32 v29, v29, s15, v30
	v_and_or_b32 v28, v35, s15, v28
	v_and_or_b32 v26, v32, s15, v37
	v_bfe_u32 v30, v36, 16, 1
	v_bfe_u32 v37, v33, 16, 1
	s_waitcnt lgkmcnt(0)
	v_mfma_f32_16x16x32_bf16 v[56:59], v[60:63], v[26:29], v[56:59]
	ds_read2_b64 v[60:63], v0 offset0:112 offset1:116
	v_add3_u32 v30, v36, v30, s14
	v_add3_u32 v36, v33, v37, s14
	v_bfe_u32 v33, v34, 16, 1
	v_bfe_u32 v37, v31, 16, 1
	v_bfe_u32 v41, v94, 16, 1
	v_bfe_u32 v48, v50, 16, 1
	v_bfe_u32 v32, v54, 16, 1
	v_bfe_u32 v35, v95, 16, 1
	v_add3_u32 v33, v34, v33, s14
	v_add3_u32 v34, v50, v48, s14
	v_add3_u32 v41, v94, v41, s14
	v_add3_u32 v31, v31, v37, s14
	v_add3_u32 v35, v95, v35, s14
	v_add3_u32 v32, v54, v32, s14
	v_lshrrev_b32_e32 v33, 16, v33
	v_lshrrev_b32_e32 v37, 16, v31
	v_lshrrev_b32_e32 v31, 16, v41
	v_lshrrev_b32_e32 v34, 16, v34
	v_and_or_b32 v33, v30, s15, v33
	v_and_or_b32 v32, v32, s15, v34
	v_and_or_b32 v31, v35, s15, v31
	v_and_or_b32 v30, v36, s15, v37
	s_waitcnt vmcnt(0)
	v_lshlrev_b32_e32 v41, 16, v47
	v_lshl_add_u64 v[44:45], v[78:79], 0, s[12:13]
	s_waitcnt lgkmcnt(0)
	v_mfma_f32_16x16x32_bf16 v[34:37], v[60:63], v[30:33], v[56:59]
	global_load_dwordx2 v[48:49], v[44:45], off offset:32
	global_load_dwordx2 v[50:51], v[44:45], off offset:64
	s_nop 0
	global_load_dwordx2 v[44:45], v[44:45], off offset:96
	v_lshlrev_b32_e32 v56, 16, v46
	v_mul_f32_e32 v52, 0xbfb8aa3b, v56
	v_and_b32_e32 v57, 0xffff0000, v47
	v_mul_f32_e32 v47, 0xbfb8aa3b, v41
	v_exp_f32_e32 v52, v52
	v_exp_f32_e32 v53, v47
	s_mov_b64 s[12:13], 0x12d20400
	v_lshl_add_u64 v[38:39], v[42:43], 0, s[12:13]
	v_mov_b32_e32 v54, v34
	v_pk_add_f32 v[52:53], v[52:53], 1.0 op_sel_hi:[1,0]
	v_mov_b32_e32 v55, v36
	v_div_scale_f32 v47, s[12:13], v53, v53, v41
	v_rcp_f32_e32 v59, v47
	v_and_b32_e32 v58, 0xffff0000, v46
	v_pk_mul_f32 v[54:55], v[40:41], v[54:55] op_sel_hi:[0,1]
	v_mul_f32_e32 v46, 0xbfb8aa3b, v58
	v_fma_f32 v34, -v47, v59, 1.0
	v_fmac_f32_e32 v59, v34, v59
	v_div_scale_f32 v34, vcc, v41, v53, v41
	v_mul_f32_e32 v36, v34, v59
	v_fma_f32 v60, -v47, v36, v34
	v_fmac_f32_e32 v36, v60, v59
	v_fma_f32 v34, -v47, v36, v34
	v_div_scale_f32 v47, s[12:13], v52, v52, v56
	v_rcp_f32_e32 v60, v47
	v_div_fmas_f32 v34, v34, v59, v36
	v_div_fixup_f32 v53, v34, v53, v41
	v_exp_f32_e32 v46, v46
	v_fma_f32 v34, -v47, v60, 1.0
	v_fmac_f32_e32 v60, v34, v60
	v_div_scale_f32 v34, vcc, v56, v52, v56
	v_mul_f32_e32 v36, v34, v60
	v_fma_f32 v41, -v47, v36, v34
	v_fmac_f32_e32 v36, v41, v60
	v_mul_f32_e32 v41, 0xbfb8aa3b, v57
	v_fma_f32 v34, -v47, v36, v34
	v_exp_f32_e32 v47, v41
	v_div_fmas_f32 v34, v34, v60, v36
	v_div_fixup_f32 v52, v34, v52, v56
	v_mov_b32_e32 v36, v35
	v_pk_add_f32 v[46:47], v[46:47], 1.0 op_sel_hi:[1,0]
	v_pk_mul_f32 v[64:65], v[54:55], v[52:53]
	v_div_scale_f32 v34, s[12:13], v47, v47, v57
	v_rcp_f32_e32 v41, v34
	v_div_scale_f32 v52, s[12:13], v46, v46, v58
	v_rcp_f32_e32 v56, v52
	v_fma_f32 v35, -v34, v41, 1.0
	v_pk_mul_f32 v[60:61], v[40:41], v[36:37] op_sel_hi:[0,1]
	v_fmac_f32_e32 v41, v35, v41
	v_div_scale_f32 v35, vcc, v57, v47, v57
	v_mul_f32_e32 v36, v35, v41
	v_fma_f32 v37, -v34, v36, v35
	v_fmac_f32_e32 v36, v37, v41
	v_fma_f32 v34, -v34, v36, v35
	v_div_fmas_f32 v34, v34, v41, v36
	v_div_fixup_f32 v47, v34, v47, v57
	v_fma_f32 v34, -v52, v56, 1.0
	v_add_u32_e32 v66, 0x4000, v0
	v_fmac_f32_e32 v56, v34, v56
	v_div_scale_f32 v41, vcc, v58, v46, v58
	ds_read2_b64 v[34:37], v66 offset0:32 offset1:36
	v_mul_f32_e32 v57, v41, v56
	v_fma_f32 v53, -v52, v57, v41
	v_fmac_f32_e32 v57, v53, v56
	v_fma_f32 v41, -v52, v57, v41
	ds_read2_b64 v[52:55], v66 offset0:48 offset1:52
	v_div_fmas_f32 v41, v41, v56, v57
	v_div_fixup_f32 v46, v41, v46, v58
	ds_read2_b64 v[56:59], v66 offset0:64 offset1:68
	s_waitcnt lgkmcnt(2)
; __device__ __forceinline__ unsigned pk2(float lo, float hi) { return f2bf(lo) | (f2bf(hi) << 16); }
; __device__ __forceinline__ float bflo(unsigned u) { return __uint_as_float(u << 16); }
; __device__ __forceinline__ float bfhi(unsigned u) { return __uint_as_float(u & 0xffff0000u); }
; __device__ __forceinline__ float silu_f(float v) { return v / (1.f + __expf(-v)); }
; #define MFMA16(a, b, c) __builtin_amdgcn_mfma_f32_16x16x32_bf16(a, b, c, 0, 0, 0)
; __device__ __forceinline__ void na2_task(const Params& p_, int l, int task, unsigned char* lds) {
;     ...
; #pragma unroll
;     for (int dt = 0; dt < 4; ++dt) { f32x4 o = {0.f, 0.f, 0.f, 0.f};
; #pragma unroll
;         for (int t = 0; t < 8; ++t) { const int k0 = 2 * t, k1 = 2 * t + 1, a0 = k0 / 2, c0 = k0 % 2, a1 = k1 / 2, c1 = k1 % 2;
;             const u32x2 vlo = *(const u32x2*)(VTh + (16 * dt + fr) * 520 + a0 * 64 + kst + 16 * c0 + 4 * fq), vhi = *(const u32x2*)(VTh + (16 * dt + fr) * 520 + a1 * 64 + kst + 16 * c1 + 4 * fq);
;             o = MFMA16(mk8(vlo.x, vlo.y, vhi.x, vhi.y), mk8(pp[k0][0], pp[k0][1], pp[k1][0], pp[k1][1]), o); }
;         const u32x2 gz = *(const u32x2*)(Z + qtok * DIN + 5 * DG + h * 64 + 16 * dt + 4 * fq); u32x2 ov;
;         ov.x = pk2(o[0] * inv * silu_f(bflo(gz.x)), o[1] * inv * silu_f(bfhi(gz.x))); ov.y = pk2(o[2] * inv * silu_f(bflo(gz.y)), o[3] * inv * silu_f(bfhi(gz.y)));
;         *(u32x2*)(CAT + qtok * DM + 512 + h * 64 + 16 * dt + 4 * fq) = ov; }
	v_mfma_f32_16x16x32_bf16 v[34:37], v[34:37], v[2:5], 0
	v_mul_f32_e64 v46, v60, v46
	v_mul_f32_e64 v47, v61, v47
	ds_read2_b64 v[60:63], v66 offset0:80 offset1:84
	v_and_b32_sdwa v41, v65, v179 dst_sel:DWORD dst_unused:UNUSED_PAD src0_sel:WORD_1 src1_sel:DWORD
	s_waitcnt lgkmcnt(2)
	v_mfma_f32_16x16x32_bf16 v[34:37], v[52:55], v[6:9], v[34:37]
	v_and_b32_sdwa v52, v64, v179 dst_sel:DWORD dst_unused:UNUSED_PAD src0_sel:WORD_1 src1_sel:DWORD
	v_add3_u32 v64, v64, v52, s14
	ds_read2_b64 v[52:55], v66 offset0:96 offset1:100
	s_waitcnt lgkmcnt(2)
	v_mfma_f32_16x16x32_bf16 v[34:37], v[56:59], v[10:13], v[34:37]
	ds_read2_b64 v[56:59], v66 offset0:112 offset1:116
	v_add3_u32 v41, v65, v41, s14
	v_and_b32_sdwa v65, v47, v179 dst_sel:DWORD dst_unused:UNUSED_PAD src0_sel:WORD_1 src1_sel:DWORD
	s_waitcnt lgkmcnt(2)
	v_mfma_f32_16x16x32_bf16 v[34:37], v[60:63], v[14:17], v[34:37]
	ds_read2_b64 v[60:63], v66 offset0:128 offset1:132
	v_and_b32_sdwa v67, v46, v179 dst_sel:DWORD dst_unused:UNUSED_PAD src0_sel:WORD_1 src1_sel:DWORD
	v_add3_u32 v47, v47, v65, s14
	s_waitcnt lgkmcnt(2)
	v_mfma_f32_16x16x32_bf16 v[34:37], v[52:55], v[18:21], v[34:37]
	ds_read2_b64 v[52:55], v66 offset0:144 offset1:148
	v_add3_u32 v46, v46, v67, s14
	v_and_b32_e32 v47, 0xffff0000, v47
	s_waitcnt lgkmcnt(2)
	v_mfma_f32_16x16x32_bf16 v[34:37], v[56:59], v[22:25], v[34:37]
	v_and_b32_e32 v46, 0xffff0000, v46
	v_add_co_u32_e32 v42, vcc, s9, v42
	s_waitcnt lgkmcnt(1)
	v_mfma_f32_16x16x32_bf16 v[34:37], v[60:63], v[26:29], v[34:37]
	v_or_b32_sdwa v47, v47, v41 dst_sel:DWORD dst_unused:UNUSED_PAD src0_sel:DWORD src1_sel:WORD_1
	v_or_b32_sdwa v46, v46, v64 dst_sel:DWORD dst_unused:UNUSED_PAD src0_sel:DWORD src1_sel:WORD_1
	v_addc_co_u32_e32 v43, vcc, 0, v43, vcc
	s_waitcnt lgkmcnt(0)
	v_mfma_f32_16x16x32_bf16 v[34:37], v[52:55], v[30:33], v[34:37]
	s_waitcnt vmcnt(2)
	v_lshlrev_b32_e32 v41, 16, v49
	v_lshlrev_b32_e32 v52, 16, v48
	global_store_dwordx2 v[42:43], v[46:47], off offset:1024
	v_mul_f32_e32 v42, 0xbfb8aa3b, v52
	v_mul_f32_e32 v43, 0xbfb8aa3b, v41
	v_exp_f32_e32 v42, v42
	v_exp_f32_e32 v43, v43
	v_and_b32_e32 v58, 0xffff0000, v48
	v_mov_b32_e32 v48, v34
	v_and_b32_e32 v53, 0xffff0000, v49
	v_pk_add_f32 v[42:43], v[42:43], 1.0 op_sel_hi:[1,0]
	v_mov_b32_e32 v49, v36
	v_div_scale_f32 v47, s[12:13], v43, v43, v41
	v_rcp_f32_e32 v54, v47
	v_pk_mul_f32 v[48:49], v[40:41], v[48:49] op_sel_hi:[0,1]
	v_mul_f32_e32 v46, 0xbfb8aa3b, v58
	v_exp_f32_e32 v46, v46
	v_fma_f32 v34, -v47, v54, 1.0
	v_fmac_f32_e32 v54, v34, v54
	v_div_scale_f32 v34, vcc, v41, v43, v41
	v_mul_f32_e32 v36, v34, v54
	v_fma_f32 v55, -v47, v36, v34
	v_fmac_f32_e32 v36, v55, v54
	v_fma_f32 v34, -v47, v36, v34
	v_div_scale_f32 v47, s[12:13], v42, v42, v52
	v_rcp_f32_e32 v55, v47
	v_div_fmas_f32 v34, v34, v54, v36
	v_div_fixup_f32 v43, v34, v43, v41
	v_add_u32_e32 v64, 0x8000, v0
	v_fma_f32 v34, -v47, v55, 1.0
	v_fmac_f32_e32 v55, v34, v55
	v_div_scale_f32 v34, vcc, v52, v42, v52
	v_mul_f32_e32 v36, v34, v55
	v_fma_f32 v41, -v47, v36, v34
	v_fmac_f32_e32 v36, v41, v55
	v_mul_f32_e32 v41, 0xbfb8aa3b, v53
	v_fma_f32 v34, -v47, v36, v34
	v_exp_f32_e32 v47, v41
	v_div_fmas_f32 v34, v34, v55, v36
	v_div_fixup_f32 v42, v34, v42, v52
	v_mov_b32_e32 v36, v35
	v_pk_add_f32 v[56:57], v[46:47], 1.0 op_sel_hi:[1,0]
	v_pk_mul_f32 v[42:43], v[48:49], v[42:43]
	v_div_scale_f32 v34, s[12:13], v57, v57, v53
	v_rcp_f32_e32 v41, v34
	v_div_scale_f32 v52, s[12:13], v56, v56, v58
	v_rcp_f32_e32 v59, v52
	v_fma_f32 v35, -v34, v41, 1.0
	v_pk_mul_f32 v[60:61], v[40:41], v[36:37] op_sel_hi:[0,1]
	v_fmac_f32_e32 v41, v35, v41
	v_div_scale_f32 v35, vcc, v53, v57, v53
	v_mul_f32_e32 v36, v35, v41
	v_fma_f32 v37, -v34, v36, v35
	v_fmac_f32_e32 v36, v37, v41
	v_fma_f32 v34, -v34, v36, v35
	v_div_fmas_f32 v34, v34, v41, v36
	v_div_fixup_f32 v63, v34, v57, v53
	ds_read2_b64 v[34:37], v64 offset0:64 offset1:68
	v_fma_f32 v41, -v52, v59, 1.0
	v_fmac_f32_e32 v59, v41, v59
	v_div_scale_f32 v41, vcc, v58, v56, v58
	ds_read2_b64 v[46:49], v64 offset0:80 offset1:84
	v_mul_f32_e32 v57, v41, v59
	v_fma_f32 v53, -v52, v57, v41
	v_fmac_f32_e32 v57, v53, v59
	v_fma_f32 v41, -v52, v57, v41
	ds_read2_b64 v[52:55], v64 offset0:96 offset1:100
	s_waitcnt lgkmcnt(2)
	v_mfma_f32_16x16x32_bf16 v[34:37], v[34:37], v[2:5], 0
	v_div_fmas_f32 v41, v41, v59, v57
	v_div_fixup_f32 v62, v41, v56, v58
	ds_read2_b64 v[56:59], v64 offset0:112 offset1:116
	s_waitcnt lgkmcnt(2)
	v_mfma_f32_16x16x32_bf16 v[34:37], v[46:49], v[6:9], v[34:37]
	ds_read2_b64 v[46:49], v64 offset0:128 offset1:132
	v_pk_mul_f32 v[60:61], v[60:61], v[62:63]
	v_and_b32_sdwa v41, v43, v179 dst_sel:DWORD dst_unused:UNUSED_PAD src0_sel:WORD_1 src1_sel:DWORD
	s_waitcnt lgkmcnt(2)
	v_mfma_f32_16x16x32_bf16 v[34:37], v[52:55], v[10:13], v[34:37]
	v_and_b32_sdwa v52, v42, v179 dst_sel:DWORD dst_unused:UNUSED_PAD src0_sel:WORD_1 src1_sel:DWORD
	v_add3_u32 v42, v42, v52, s14
	ds_read2_b64 v[52:55], v64 offset0:144 offset1:148
	s_waitcnt lgkmcnt(2)
	v_mfma_f32_16x16x32_bf16 v[34:37], v[56:59], v[14:17], v[34:37]
	ds_read2_b64 v[56:59], v64 offset0:160 offset1:164
	v_add3_u32 v41, v43, v41, s14
	v_and_b32_sdwa v43, v61, v179 dst_sel:DWORD dst_unused:UNUSED_PAD src0_sel:WORD_1 src1_sel:DWORD
	s_waitcnt lgkmcnt(2)
	v_mfma_f32_16x16x32_bf16 v[34:37], v[46:49], v[18:21], v[34:37]
	v_and_b32_sdwa v62, v60, v179 dst_sel:DWORD dst_unused:UNUSED_PAD src0_sel:WORD_1 src1_sel:DWORD
	v_add3_u32 v43, v61, v43, s14
	ds_read2_b64 v[46:49], v64 offset0:176 offset1:180
	s_waitcnt lgkmcnt(2)
; __device__ __forceinline__ unsigned pk2(float lo, float hi) { return f2bf(lo) | (f2bf(hi) << 16); }
; __device__ __forceinline__ float bflo(unsigned u) { return __uint_as_float(u << 16); }
; __device__ __forceinline__ float bfhi(unsigned u) { return __uint_as_float(u & 0xffff0000u); }
; __device__ __forceinline__ float silu_f(float v) { return v / (1.f + __expf(-v)); }
; #define MFMA16(a, b, c) __builtin_amdgcn_mfma_f32_16x16x32_bf16(a, b, c, 0, 0, 0)
; __device__ __forceinline__ void na2_task(const Params& p_, int l, int task, unsigned char* lds) {
;     ...
; #pragma unroll
;     for (int dt = 0; dt < 4; ++dt) { f32x4 o = {0.f, 0.f, 0.f, 0.f};
; #pragma unroll
;         for (int t = 0; t < 8; ++t) { const int k0 = 2 * t, k1 = 2 * t + 1, a0 = k0 / 2, c0 = k0 % 2, a1 = k1 / 2, c1 = k1 % 2;
;             const u32x2 vlo = *(const u32x2*)(VTh + (16 * dt + fr) * 520 + a0 * 64 + kst + 16 * c0 + 4 * fq), vhi = *(const u32x2*)(VTh + (16 * dt + fr) * 520 + a1 * 64 + kst + 16 * c1 + 4 * fq);
;             o = MFMA16(mk8(vlo.x, vlo.y, vhi.x, vhi.y), mk8(pp[k0][0], pp[k0][1], pp[k1][0], pp[k1][1]), o); }
;         const u32x2 gz = *(const u32x2*)(Z + qtok * DIN + 5 * DG + h * 64 + 16 * dt + 4 * fq); u32x2 ov;
;         ov.x = pk2(o[0] * inv * silu_f(bflo(gz.x)), o[1] * inv * silu_f(bfhi(gz.x))); ov.y = pk2(o[2] * inv * silu_f(bflo(gz.y)), o[3] * inv * silu_f(bfhi(gz.y)));
;         *(u32x2*)(CAT + qtok * DM + 512 + h * 64 + 16 * dt + 4 * fq) = ov; }
	v_mfma_f32_16x16x32_bf16 v[34:37], v[52:55], v[22:25], v[34:37]
	v_add3_u32 v52, v60, v62, s14
	v_and_b32_e32 v43, 0xffff0000, v43
	v_and_b32_e32 v52, 0xffff0000, v52
	v_or_b32_sdwa v43, v43, v41 dst_sel:DWORD dst_unused:UNUSED_PAD src0_sel:DWORD src1_sel:WORD_1
	v_or_b32_sdwa v42, v52, v42 dst_sel:DWORD dst_unused:UNUSED_PAD src0_sel:DWORD src1_sel:WORD_1
	s_waitcnt vmcnt(2)
	v_lshlrev_b32_e32 v41, 16, v51
	v_lshlrev_b32_e32 v52, 16, v50
	global_store_dwordx2 v[38:39], v[42:43], off offset:32
	v_mul_f32_e32 v42, 0xbfb8aa3b, v52
	v_mul_f32_e32 v43, 0xbfb8aa3b, v41
	v_exp_f32_e32 v42, v42
	v_exp_f32_e32 v43, v43
	s_waitcnt lgkmcnt(1)
	v_mfma_f32_16x16x32_bf16 v[34:37], v[56:59], v[26:29], v[34:37]
	v_and_b32_e32 v56, 0xffff0000, v50
	v_and_b32_e32 v53, 0xffff0000, v51
	v_pk_add_f32 v[42:43], v[42:43], 1.0 op_sel_hi:[1,0]
	s_waitcnt lgkmcnt(0)
	v_mfma_f32_16x16x32_bf16 v[34:37], v[46:49], v[30:33], v[34:37]
	v_div_scale_f32 v47, s[12:13], v43, v43, v41
	v_rcp_f32_e32 v50, v47
	v_mul_f32_e32 v46, 0xbfb8aa3b, v56
	v_exp_f32_e32 v46, v46
	s_nop 3
	v_mov_b32_e32 v48, v34
	v_fma_f32 v34, -v47, v50, 1.0
	v_fmac_f32_e32 v50, v34, v50
	v_div_scale_f32 v34, vcc, v41, v43, v41
	v_mov_b32_e32 v49, v36
	v_mul_f32_e32 v36, v34, v50
	v_fma_f32 v51, -v47, v36, v34
	v_fmac_f32_e32 v36, v51, v50
	v_fma_f32 v34, -v47, v36, v34
	v_div_scale_f32 v47, s[12:13], v42, v42, v52
	v_rcp_f32_e32 v51, v47
	v_div_fmas_f32 v34, v34, v50, v36
	v_div_fixup_f32 v43, v34, v43, v41
	v_pk_mul_f32 v[48:49], v[40:41], v[48:49] op_sel_hi:[0,1]
	v_fma_f32 v34, -v47, v51, 1.0
	v_fmac_f32_e32 v51, v34, v51
	v_div_scale_f32 v34, vcc, v52, v42, v52
	v_mul_f32_e32 v36, v34, v51
	v_fma_f32 v41, -v47, v36, v34
	v_fmac_f32_e32 v36, v41, v51
	v_mul_f32_e32 v41, 0xbfb8aa3b, v53
	v_fma_f32 v34, -v47, v36, v34
	v_exp_f32_e32 v47, v41
	v_div_fmas_f32 v34, v34, v51, v36
	v_div_fixup_f32 v42, v34, v42, v52
	v_mov_b32_e32 v36, v35
	v_pk_add_f32 v[50:51], v[46:47], 1.0 op_sel_hi:[1,0]
	v_add_u32_e32 v0, 0xc000, v0
	v_div_scale_f32 v34, s[12:13], v51, v51, v53
	v_rcp_f32_e32 v41, v34
	v_div_scale_f32 v52, s[12:13], v50, v50, v56
	v_rcp_f32_e32 v58, v52
	v_fma_f32 v35, -v34, v41, 1.0
	v_pk_mul_f32 v[54:55], v[40:41], v[36:37] op_sel_hi:[0,1]
	v_fmac_f32_e32 v41, v35, v41
	v_div_scale_f32 v35, vcc, v53, v51, v53
	v_mul_f32_e32 v36, v35, v41
	v_fma_f32 v37, -v34, v36, v35
	v_fmac_f32_e32 v36, v37, v41
	v_fma_f32 v34, -v34, v36, v35
	v_div_fmas_f32 v34, v34, v41, v36
	v_div_fixup_f32 v57, v34, v51, v53
	ds_read2_b64 v[34:37], v0 offset0:96 offset1:100
	v_pk_mul_f32 v[42:43], v[48:49], v[42:43]
	ds_read2_b64 v[46:49], v0 offset0:112 offset1:116
	v_fma_f32 v41, -v52, v58, 1.0
	v_fmac_f32_e32 v58, v41, v58
	v_div_scale_f32 v41, vcc, v56, v50, v56
	v_mul_f32_e32 v51, v41, v58
	v_fma_f32 v53, -v52, v51, v41
	s_waitcnt lgkmcnt(1)
	v_mfma_f32_16x16x32_bf16 v[2:5], v[34:37], v[2:5], 0
	ds_read2_b64 v[34:37], v0 offset0:128 offset1:132
	v_fmac_f32_e32 v51, v53, v58
	v_fma_f32 v41, -v52, v51, v41
	v_div_fmas_f32 v41, v41, v58, v51
	v_div_fixup_f32 v56, v41, v50, v56
	ds_read2_b64 v[50:53], v0 offset0:144 offset1:148
	s_waitcnt lgkmcnt(2)
	v_mfma_f32_16x16x32_bf16 v[2:5], v[46:49], v[6:9], v[2:5]
	ds_read2_b64 v[6:9], v0 offset0:160 offset1:164
	v_pk_mul_f32 v[46:47], v[54:55], v[56:57]
	v_and_b32_sdwa v41, v43, v179 dst_sel:DWORD dst_unused:UNUSED_PAD src0_sel:WORD_1 src1_sel:DWORD
	s_waitcnt lgkmcnt(2)
	v_mfma_f32_16x16x32_bf16 v[2:5], v[34:37], v[10:13], v[2:5]
	v_and_b32_sdwa v10, v42, v179 dst_sel:DWORD dst_unused:UNUSED_PAD src0_sel:WORD_1 src1_sel:DWORD
	v_add3_u32 v34, v42, v10, s14
	ds_read2_b64 v[10:13], v0 offset0:176 offset1:180
	s_waitcnt lgkmcnt(2)
	v_mfma_f32_16x16x32_bf16 v[2:5], v[50:53], v[14:17], v[2:5]
	ds_read2_b64 v[14:17], v0 offset0:192 offset1:196
	v_and_b32_sdwa v36, v47, v179 dst_sel:DWORD dst_unused:UNUSED_PAD src0_sel:WORD_1 src1_sel:DWORD
	v_add3_u32 v35, v43, v41, s14
	s_waitcnt lgkmcnt(2)
	v_mfma_f32_16x16x32_bf16 v[2:5], v[6:9], v[18:21], v[2:5]
	ds_read2_b64 v[6:9], v0 offset0:208 offset1:212
	v_and_b32_sdwa v18, v46, v179 dst_sel:DWORD dst_unused:UNUSED_PAD src0_sel:WORD_1 src1_sel:DWORD
	v_add3_u32 v19, v47, v36, s14
	s_waitcnt lgkmcnt(2)
	v_mfma_f32_16x16x32_bf16 v[2:5], v[10:13], v[22:25], v[2:5]
	v_add3_u32 v0, v46, v18, s14
	v_and_b32_e32 v10, 0xffff0000, v19
	v_and_b32_e32 v0, 0xffff0000, v0
	s_waitcnt lgkmcnt(1)
	v_mfma_f32_16x16x32_bf16 v[2:5], v[14:17], v[26:29], v[2:5]
	v_or_b32_sdwa v11, v10, v35 dst_sel:DWORD dst_unused:UNUSED_PAD src0_sel:DWORD src1_sel:WORD_1
	v_or_b32_sdwa v10, v0, v34 dst_sel:DWORD dst_unused:UNUSED_PAD src0_sel:DWORD src1_sel:WORD_1
	s_waitcnt vmcnt(2)
	v_lshlrev_b32_e32 v0, 16, v45
	v_lshlrev_b32_e32 v12, 16, v44
	s_waitcnt lgkmcnt(0)
; __device__ __forceinline__ unsigned pk2(float lo, float hi) { return f2bf(lo) | (f2bf(hi) << 16); }
; __device__ __forceinline__ float bflo(unsigned u) { return __uint_as_float(u << 16); }
; __device__ __forceinline__ float bfhi(unsigned u) { return __uint_as_float(u & 0xffff0000u); }
; __device__ __forceinline__ float silu_f(float v) { return v / (1.f + __expf(-v)); }
; #define MFMA16(a, b, c) __builtin_amdgcn_mfma_f32_16x16x32_bf16(a, b, c, 0, 0, 0)
; __device__ __forceinline__ void na2_task(const Params& p_, int l, int task, unsigned char* lds) {
;     ...
; #pragma unroll
;     for (int dt = 0; dt < 4; ++dt) { f32x4 o = {0.f, 0.f, 0.f, 0.f};
; #pragma unroll
;         for (int t = 0; t < 8; ++t) { const int k0 = 2 * t, k1 = 2 * t + 1, a0 = k0 / 2, c0 = k0 % 2, a1 = k1 / 2, c1 = k1 % 2;
;             const u32x2 vlo = *(const u32x2*)(VTh + (16 * dt + fr) * 520 + a0 * 64 + kst + 16 * c0 + 4 * fq), vhi = *(const u32x2*)(VTh + (16 * dt + fr) * 520 + a1 * 64 + kst + 16 * c1 + 4 * fq);
;             o = MFMA16(mk8(vlo.x, vlo.y, vhi.x, vhi.y), mk8(pp[k0][0], pp[k0][1], pp[k1][0], pp[k1][1]), o); }
;         const u32x2 gz = *(const u32x2*)(Z + qtok * DIN + 5 * DG + h * 64 + 16 * dt + 4 * fq); u32x2 ov;
;         ov.x = pk2(o[0] * inv * silu_f(bflo(gz.x)), o[1] * inv * silu_f(bfhi(gz.x))); ov.y = pk2(o[2] * inv * silu_f(bflo(gz.y)), o[3] * inv * silu_f(bfhi(gz.y)));
;         *(u32x2*)(CAT + qtok * DM + 512 + h * 64 + 16 * dt + 4 * fq) = ov; }
;     __syncthreads();
; __device__ __forceinline__ void ph_mixA(const Params& p, int l, unsigned char* lds) {
;     ...
;         for (int i = 0; i < nloc; ++i) { const int rq = (slot < 16) ? slot : 16 + i * 16 + (slot - 16);
;             na2_task(p, l, (xcd >> 2) * 256 + rq * 4 + (xcd & 3), lds); }
	v_mfma_f32_16x16x32_bf16 v[2:5], v[6:9], v[30:33], v[2:5]
	v_mul_f32_e32 v6, 0xbfb8aa3b, v12
	v_mul_f32_e32 v7, 0xbfb8aa3b, v0
	v_exp_f32_e32 v6, v6
	v_exp_f32_e32 v7, v7
	global_store_dwordx2 v[38:39], v[10:11], off offset:64
	s_nop 2
	v_mov_b32_e32 v10, v2
	v_mov_b32_e32 v11, v4
	v_pk_add_f32 v[6:7], v[6:7], 1.0 op_sel_hi:[1,0]
	v_and_b32_e32 v13, 0xffff0000, v45
	v_div_scale_f32 v9, s[12:13], v7, v7, v0
	v_rcp_f32_e32 v15, v9
	v_and_b32_e32 v14, 0xffff0000, v44
	v_mul_f32_e32 v8, 0xbfb8aa3b, v14
	v_exp_f32_e32 v8, v8
	v_fma_f32 v2, -v9, v15, 1.0
	v_fmac_f32_e32 v15, v2, v15
	v_div_scale_f32 v2, vcc, v0, v7, v0
	v_mul_f32_e32 v4, v2, v15
	v_fma_f32 v16, -v9, v4, v2
	v_fmac_f32_e32 v4, v16, v15
	v_fma_f32 v2, -v9, v4, v2
	v_div_scale_f32 v9, s[12:13], v6, v6, v12
	v_rcp_f32_e32 v16, v9
	v_div_fmas_f32 v2, v2, v15, v4
	v_div_fixup_f32 v7, v2, v7, v0
	v_pk_mul_f32 v[10:11], v[40:41], v[10:11] op_sel_hi:[0,1]
	v_fma_f32 v0, -v9, v16, 1.0
	v_fmac_f32_e32 v16, v0, v16
	v_div_scale_f32 v0, vcc, v12, v6, v12
	v_mul_f32_e32 v2, v0, v16
	v_fma_f32 v4, -v9, v2, v0
	v_fmac_f32_e32 v2, v4, v16
	v_mul_f32_e32 v4, 0xbfb8aa3b, v13
	v_fma_f32 v0, -v9, v2, v0
	v_exp_f32_e32 v9, v4
	v_div_fmas_f32 v0, v0, v16, v2
	v_div_fixup_f32 v6, v0, v6, v12
	v_mov_b32_e32 v4, v3
	v_pk_add_f32 v[8:9], v[8:9], 1.0 op_sel_hi:[1,0]
	v_pk_mul_f32 v[2:3], v[40:41], v[4:5] op_sel_hi:[0,1]
	v_div_scale_f32 v0, s[12:13], v9, v9, v13
	v_rcp_f32_e32 v12, v0
	v_pk_mul_f32 v[6:7], v[10:11], v[6:7]
	s_add_i32 s9, s3, 1
	s_cmp_lt_u32 s3, 3
	v_fma_f32 v4, -v0, v12, 1.0
	v_fmac_f32_e32 v12, v4, v12
	v_div_scale_f32 v4, vcc, v13, v9, v13
	v_mul_f32_e32 v5, v4, v12
	v_fma_f32 v10, -v0, v5, v4
	v_fmac_f32_e32 v5, v10, v12
	v_fma_f32 v0, -v0, v5, v4
	v_div_scale_f32 v4, s[12:13], v8, v8, v14
	v_rcp_f32_e32 v10, v4
	v_div_fmas_f32 v0, v0, v12, v5
	v_div_fixup_f32 v5, v0, v9, v13
	s_cselect_b64 s[12:13], -1, 0
	v_fma_f32 v0, -v4, v10, 1.0
	v_fmac_f32_e32 v10, v0, v10
	v_div_scale_f32 v0, vcc, v14, v8, v14
	v_mul_f32_e32 v9, v0, v10
	v_fma_f32 v11, -v4, v9, v0
	v_fmac_f32_e32 v9, v11, v10
	v_fma_f32 v0, -v4, v9, v0
	v_div_fmas_f32 v0, v0, v10, v9
	v_div_fixup_f32 v4, v0, v8, v14
	v_pk_mul_f32 v[2:3], v[2:3], v[4:5]
	v_and_b32_sdwa v4, v6, v179 dst_sel:DWORD dst_unused:UNUSED_PAD src0_sel:WORD_1 src1_sel:DWORD
	v_add3_u32 v4, v6, v4, s14
	v_and_b32_sdwa v5, v3, v179 dst_sel:DWORD dst_unused:UNUSED_PAD src0_sel:WORD_1 src1_sel:DWORD
	v_and_b32_sdwa v6, v2, v179 dst_sel:DWORD dst_unused:UNUSED_PAD src0_sel:WORD_1 src1_sel:DWORD
	v_and_b32_sdwa v0, v7, v179 dst_sel:DWORD dst_unused:UNUSED_PAD src0_sel:WORD_1 src1_sel:DWORD
	v_add3_u32 v3, v3, v5, s14
	v_add3_u32 v2, v2, v6, s14
	v_add3_u32 v0, v7, v0, s14
	v_and_b32_e32 v3, 0xffff0000, v3
	v_and_b32_e32 v2, 0xffff0000, v2
	s_and_b64 s[12:13], s[56:57], s[12:13]
	v_or_b32_sdwa v3, v3, v0 dst_sel:DWORD dst_unused:UNUSED_PAD src0_sel:DWORD src1_sel:WORD_1
	v_or_b32_sdwa v2, v2, v4 dst_sel:DWORD dst_unused:UNUSED_PAD src0_sel:DWORD src1_sel:WORD_1
	s_andn2_b64 vcc, exec, s[12:13]
	s_mov_b32 s3, s9
	global_store_dwordx2 v[38:39], v[2:3], off offset:96
	s_barrier
	s_cbranch_vccnz .LBB0_394
; __device__ __forceinline__ void na2_task(const Params& p_, int l, int task, unsigned char* lds) {
;     ...
;     const int hp = task & 3, rq = (task >> 2) & 63, b = task >> 8;
;     const int row_start = min(max(rq - 4, 0), 56);
;     const bf16* Z = (const bf16*)(p.ws + WS_Z); bf16* CAT = (bf16*)(p.ws + WS_CAT);
;     bf16* VT = (bf16*)lds; float* BI = (float*)(lds + 133120);
;     const int hh = w >> 2, h = hp * 2 + hh, qb = w & 3, kst = min(max(16 * qb - 8, 0), 32);
;     const int c = 16 * qb + fr; const size_t qtok = (size_t)b * SEQ + rq * 64 + c;
;     bf16x8v qf[2], kfr[8][2];
; #pragma unroll
;     for (int ks = 0; ks < 2; ++ks) qf[ks] = *(const bf16x8v*)(Z + qtok * DIN + 2 * DG + h * 64 + 32 * ks + 8 * fq);
; #pragma unroll
;     for (int i = 0; i < 8; ++i) { const int a = i / 2, ci = i % 2;
;         const size_t ktok = (size_t)b * SEQ + (row_start + a) * 64 + kst + 16 * ci + fr;
; #pragma unroll
;         for (int ks = 0; ks < 2; ++ks) kfr[i][ks] = *(const bf16x8v*)(Z + ktok * DIN + 3 * DG + h * 64 + 32 * ks + 8 * fq); }
;     asm volatile("" ::: "memory");
;     for (int i = tid; i < 930; i += NTHR) BI[i] = p.na_bias[(size_t)(l * 8 + hp * 2) * 465 + i];
;     { const int pair = lane & 31, chunk = (lane >> 5) + 2 * (w & 3);
;       unsigned* VTd = (unsigned*)(VT + (size_t)hh * 64 * 520);
;       u32x4 xs[8], ys[8];
; #pragma unroll
;       for (int a = 0; a < 8; ++a) { const size_t tok = (size_t)b * SEQ + (row_start + a) * 64 + 2 * pair;
;           const bf16* src = Z + tok * DIN + 4 * DG + h * 64 + chunk * 8; xs[a] = *(const u32x4*)src; ys[a] = *(const u32x4*)(src + DIN); }
; __device__ __forceinline__ void ph_mixA(const Params& p, int l, unsigned char* lds) {
;     ...
;         for (int i = 0; i < nloc; ++i) { const int rq = (slot < 16) ? slot : 16 + i * 16 + (slot - 16);
;             na2_task(p, l, (xcd >> 2) * 256 + rq * 4 + (xcd & 3), lds); }
.LBB0_386:
	s_lshl_b32 s9, s3, 4
	s_and_b64 s[12:13], s[56:57], exec
	s_mov_b64 s[50:51], s[0:1]
	s_cselect_b32 s9, s9, 0
	s_load_dwordx2 s[62:63], s[50:51], 0x90
	s_add_i32 s9, s9, s68
	s_sub_i32 s9, s9, 16
	s_lshl_b32 s12, s9, 2
	s_add_i32 s12, s12, s70
	v_mov_b32 v86, v147
	s_and_b32 s9, s9, 63
	s_ashr_i32 s12, s12, 8
	v_lshrrev_b32_e32 v94, 2, v86
	v_and_b32_e32 v90, 15, v86
	v_and_b32_e32 v250, 15, v94
	v_and_b32_e32 v252, 3, v86
	v_lshlrev_b32_e32 v252, 4, v252
	v_mov_b32_e32 v253, 0
	v_lshlrev_b32_e32 v251, 4, v90
	v_bfe_u32 v249, v86, 4, 2
	v_lshl_or_b32 v251, v249, 2, v251
	s_waitcnt lgkmcnt(0)
	s_add_u32 s40, s62, 0xad20000
	v_and_b32_e32 v0, 48, v94
	s_addc_u32 s41, s63, 0
	v_or_b32_e32 v91, v0, v90
	s_ashr_i32 s13, s12, 31
	v_sub_u32_e64 v11, v0, 8 clamp
	s_lshl_b64 s[42:43], s[12:13], 12
	v_lshl_or_b32 v0, s9, 6, v91
	v_or_b32_e32 v74, s42, v0
	v_mov_b64_e32 v[34:35], s[40:41]
	v_sub_u32_e64 v10, s9, 4 clamp
	v_mad_u64_u32 v[2:3], s[12:13], v74, s75, v[34:35]
	v_readfirstlane_b32 s12, v10
	s_min_u32 s12, s12, 56
	v_min_u32_e32 v80, 32, v11
	v_mov_b32_e32 v81, v1
	v_or_b32_e32 v10, s42, v250
	v_mov_b32_e32 v11, s43
	v_ashrrev_i32_e32 v93, 8, v86
	v_lshl_add_u64 v[82:83], v[10:11], 0, v[80:81]
	s_lshl_b32 s24, s12, 6
	v_add_lshl_u32 v4, v93, s71, 6
	v_lshl_add_u64 v[10:11], v[82:83], 0, s[24:25]
	v_ashrrev_i32_e32 v5, 31, v4
	v_mad_u64_u32 v[12:13], s[44:45], v10, s75, v[34:35]
	v_bfe_u32 v92, v86, 4, 2
	v_mad_i32_i24 v3, s43, v195, v3
	v_lshlrev_b64 v[76:77], 1, v[4:5]
	v_mad_i32_i24 v13, v11, s75, v13
	v_lshl_add_u64 v[78:79], v[2:3], 0, v[76:77]
	v_lshlrev_b32_e32 v0, 4, v92
	v_lshl_add_u64 v[10:11], v[12:13], 0, v[76:77]
	v_lshl_add_u64 v[2:3], v[78:79], 0, v[0:1]
	v_lshl_add_u64 v[10:11], v[10:11], 0, v[252:253]
	v_lshl_add_u64 v[84:85], v[82:83], 0, 16
	global_load_dwordx4 v[6:9], v[2:3], off offset:2048
	s_nop 0
	global_load_dwordx4 v[2:5], v[2:3], off offset:2112
	s_nop 0
	global_load_dwordx4 v[70:73], v[10:11], off offset:3072
	global_load_dwordx4 v[66:69], v[10:11], off offset:3136
	v_lshl_add_u64 v[10:11], v[84:85], 0, s[24:25]
	v_mad_u64_u32 v[12:13], s[44:45], v10, s75, v[34:35]
	v_mov_b32_e32 v10, v13
	v_mad_u64_u32 v[10:11], s[44:45], v11, s75, v[10:11]
	v_mov_b32_e32 v13, v10
	s_add_i32 s44, s24, 64
	s_mov_b32 s45, s25
	v_lshl_add_u64 v[10:11], v[12:13], 0, v[76:77]
	v_lshl_add_u64 v[14:15], v[84:85], 0, s[44:45]
	v_lshl_add_u64 v[10:11], v[10:11], 0, v[252:253]
	v_mad_u64_u32 v[16:17], s[46:47], v14, s75, v[34:35]
	global_load_dwordx4 v[62:65], v[10:11], off offset:3072
	global_load_dwordx4 v[58:61], v[10:11], off offset:3136
	v_lshl_add_u64 v[10:11], v[82:83], 0, s[44:45]
	v_mov_b32_e32 v14, v17
	v_mad_u64_u32 v[12:13], s[46:47], v10, s75, v[34:35]
	v_mad_u64_u32 v[14:15], s[46:47], v15, s75, v[14:15]
	v_mad_i32_i24 v13, v11, s75, v13
	v_mov_b32_e32 v17, v14
	v_lshl_add_u64 v[10:11], v[12:13], 0, v[76:77]
	v_lshl_add_u64 v[14:15], v[16:17], 0, v[76:77]
	v_lshl_add_u64 v[10:11], v[10:11], 0, v[252:253]
	v_lshl_add_u64 v[14:15], v[14:15], 0, v[252:253]
	s_add_i32 s46, s24, 0x80
	s_mov_b32 s47, s25
	global_load_dwordx4 v[18:21], v[10:11], off offset:3072
	s_nop 0
	global_load_dwordx4 v[10:13], v[10:11], off offset:3136
	s_nop 0
	global_load_dwordx4 v[38:41], v[14:15], off offset:3072
	global_load_dwordx4 v[22:25], v[14:15], off offset:3136
	v_lshl_add_u64 v[14:15], v[82:83], 0, s[46:47]
	v_mad_u64_u32 v[16:17], s[48:49], v14, s75, v[34:35]
	v_mad_i32_i24 v17, v15, s75, v17
	v_lshl_add_u64 v[14:15], v[16:17], 0, v[76:77]
	v_lshl_add_u64 v[14:15], v[14:15], 0, v[252:253]
	global_load_dwordx4 v[54:57], v[14:15], off offset:3072
	global_load_dwordx4 v[42:45], v[14:15], off offset:3136
	v_lshl_add_u64 v[14:15], v[84:85], 0, s[46:47]
	v_mad_u64_u32 v[16:17], s[48:49], v14, s75, v[34:35]
	v_mov_b32_e32 v14, v17
	v_mad_u64_u32 v[14:15], s[48:49], v15, s75, v[14:15]
	v_mov_b32_e32 v17, v14
	v_lshl_add_u64 v[14:15], v[16:17], 0, v[76:77]
	v_lshl_add_u64 v[14:15], v[14:15], 0, v[252:253]
	s_add_i32 s48, s24, 0xc0
	s_mov_b32 s49, s25
	global_load_dwordx4 v[46:49], v[14:15], off offset:3072
	global_load_dwordx4 v[30:33], v[14:15], off offset:3136
	v_lshl_add_u64 v[14:15], v[82:83], 0, s[48:49]
	v_lshl_add_u64 v[36:37], v[84:85], 0, s[48:49]
	v_mad_u64_u32 v[16:17], s[52:53], v14, s75, v[34:35]
	v_mad_u64_u32 v[34:35], s[52:53], v36, s75, v[34:35]
	v_mov_b32_e32 v36, v35
	v_mad_u64_u32 v[36:37], s[52:53], v37, s75, v[36:37]
	v_mad_i32_i24 v17, v15, s75, v17
	v_mov_b32_e32 v35, v36
	v_lshl_add_u64 v[14:15], v[16:17], 0, v[76:77]
	v_lshl_add_u64 v[34:35], v[34:35], 0, v[76:77]
	v_lshl_add_u64 v[14:15], v[14:15], 0, v[252:253]
	v_lshl_add_u64 v[34:35], v[34:35], 0, v[252:253]
	global_load_dwordx4 v[26:29], v[14:15], off offset:3072
	s_nop 0
	global_load_dwordx4 v[14:17], v[14:15], off offset:3136
	s_nop 0
	global_load_dwordx4 v[50:53], v[34:35], off offset:3072
	s_nop 0
	global_load_dwordx4 v[34:37], v[34:35], off offset:3136
	v_mov_b32_e32 v75, s43
	s_load_dwordx2 s[98:99], s[0:1], 0x38
	v_add_u32_e32 v205, 0x200, v147
	v_min_u32_e32 v205, 0x3a1, v205
	v_lshlrev_b32_e32 v204, 2, v147
	v_lshlrev_b32_e32 v205, 2, v205
	s_waitcnt lgkmcnt(0)
	s_add_u32 s98, s98, s60
	s_addc_u32 s99, s99, s61
	global_load_dword v203, v204, s[98:99]
	global_load_dword v209, v205, s[98:99]
	v_add_u32_e32 v204, s67, v204
	v_add_u32_e32 v205, s67, v205
	v_readlane_b32 s94, v255, 32
	s_movk_i32 s97, 0x2000
	s_movk_i32 s93, 0x6000
	s_mov_b32 s96, 0xa000
	v_readlane_b32 s95, v255, 33
	s_branch .LBB0_385

; __device__ __forceinline__ void conv_task(const Params& p_, int l, int task, unsigned char* lds) {
;     ...
;     float w[31];
; #pragma unroll
;     for (int k = 0; k < 31; ++k) w[k] = p.conv_w[(size_t)(l * 31 + k) * DG + tid];
;     const float cb = p.conv_b[l * DG + tid];
;     __syncthreads();
;     { float y[16];
; #pragma unroll
;       for (int t = 0; t < 16; ++t) y[t] = cb;
; #pragma unroll
;       for (int j = 0; j < 46; ++j) { const float u = us[j * 512 + tid];
; #pragma unroll
;           for (int t = 0; t < 16; ++t) { const int k = j - t; if (k >= 0 && k < 31) y[t] += w[k] * u; } }
; __device__ __forceinline__ void ph_mixA(const Params& p, int l, unsigned char* lds) {
;     ...
;     if (G == 256 && REP_CV == 1) {
;         for (int i = 0; i < 2; ++i) conv_task(p, l, xcd * 64 + i * 32 + slot, lds);
;     } else for (int t = bid; t < 512 * REP_CV; t += G) conv_task(p, l, t & 511, lds);
.LBB0_424:
	s_andn2_b64 vcc, exec, s[38:39]
	s_mov_b32 s92, 0x800000
	s_cbranch_vccnz .LBB0_451
	s_lshl_b32 s10, s10, 10
	s_lshl_b32 s9, s68, 4
	s_add_i32 s10, s10, s9
	s_mov_b32 s26, 3
	s_cmp_lt_u32 s68, 16
	s_cbranch_scc1 .Lcv_bal
	s_mov_b32 s26, 1
.Lcv_bal:
	s_mov_b32 s27, 0
	s_mov_b32 s9, 0
	s_mov_b64 s[48:49], -1
	s_branch .LBB0_427
.LBB0_426:
	s_or_b64 exec, exec, s[38:39]
	s_waitcnt vmcnt(0) lgkmcnt(0)
	v_mov_b32_e32 v2, s56
	v_mov_b32_e32 v3, s57
	v_ashrrev_i32_e32 v55, 31, v54
	v_lshl_add_u64 v[2:3], v[54:55], 2, v[2:3]
	v_lshl_add_u64 v[2:3], s[24:25], 2, v[2:3]
	v_add_co_u32_e32 v6, vcc, s74, v2
	s_movk_i32 s6, 0x5000
	s_nop 0
	v_addc_co_u32_e32 v7, vcc, 0, v3, vcc
	v_add_co_u32_e32 v8, vcc, s97, v2
	global_load_dword v33, v[2:3], off
	global_load_dword v0, v[2:3], off offset:2048
	global_load_dword v32, v[6:7], off offset:2048
	v_addc_co_u32_e32 v9, vcc, 0, v3, vcc
	v_add_co_u32_e32 v6, vcc, s5, v2
	v_add_u32_e32 v24, s3, v54
	s_nop 0
	v_addc_co_u32_e32 v7, vcc, 0, v3, vcc
	v_add_co_u32_e32 v10, vcc, s7, v2
	v_mov_b32_e32 v4, s58
	s_nop 0
	v_addc_co_u32_e32 v11, vcc, 0, v3, vcc
	v_add_co_u32_e32 v12, vcc, s6, v2
	s_movk_i32 s6, 0x7000
	s_nop 0
	v_addc_co_u32_e32 v13, vcc, 0, v3, vcc
	v_add_co_u32_e32 v14, vcc, s93, v2
	v_mov_b32_e32 v5, s59
	s_nop 0
	v_addc_co_u32_e32 v15, vcc, 0, v3, vcc
	global_load_dword v41, v[8:9], off offset:-4096
	global_load_dword v40, v[8:9], off
	global_load_dword v39, v[8:9], off offset:2048
	global_load_dword v38, v[10:11], off offset:-4096
	global_load_dword v36, v[10:11], off
	global_load_dword v35, v[10:11], off offset:2048
	global_load_dword v37, v[14:15], off offset:-4096
	global_load_dword v34, v[14:15], off
	v_add_co_u32_e32 v8, vcc, s6, v2
	s_mov_b32 s6, 0x8000
	s_nop 0
	v_addc_co_u32_e32 v9, vcc, 0, v3, vcc
	v_add_co_u32_e32 v10, vcc, s6, v2
	s_mov_b32 s6, 0x9000
	s_nop 0
	v_addc_co_u32_e32 v11, vcc, 0, v3, vcc
	v_add_co_u32_e32 v16, vcc, s6, v2
	s_mov_b32 s6, 0xb000
	s_nop 0
	v_addc_co_u32_e32 v17, vcc, 0, v3, vcc
	v_add_co_u32_e32 v18, vcc, s96, v2
	v_ashrrev_i32_e32 v25, 31, v24
	s_nop 0
	v_addc_co_u32_e32 v19, vcc, 0, v3, vcc
	v_add_co_u32_e32 v20, vcc, s6, v2
	s_mov_b32 s6, 0xc000
	s_nop 0
	v_addc_co_u32_e32 v21, vcc, 0, v3, vcc
	v_add_co_u32_e32 v22, vcc, s6, v2
	v_lshl_add_u64 v[4:5], v[24:25], 2, v[4:5]
	s_nop 0
	v_addc_co_u32_e32 v23, vcc, 0, v3, vcc
	global_load_dword v42, v[4:5], off
	global_load_dword v61, v[14:15], off offset:2048
	global_load_dword v57, v[10:11], off offset:-4096
	global_load_dword v52, v[10:11], off
	global_load_dword v50, v[10:11], off offset:2048
	global_load_dword v48, v[18:19], off offset:-4096
	global_load_dword v45, v[18:19], off
	global_load_dword v44, v[18:19], off offset:2048
	global_load_dword v43, v[22:23], off offset:-4096
	global_load_dword v65, v[6:7], off offset:2048
	global_load_dword v64, v[12:13], off offset:2048
	global_load_dword v63, v[8:9], off offset:2048
	global_load_dword v58, v[16:17], off offset:2048
	global_load_dword v46, v[20:21], off offset:2048
	s_mov_b32 s6, 0xd000
	v_add_co_u32_e32 v4, vcc, s6, v2
	s_mov_b32 s6, 0xe000
	s_nop 0
	v_addc_co_u32_e32 v5, vcc, 0, v3, vcc
	v_add_co_u32_e32 v6, vcc, s6, v2
	s_mov_b32 s6, 0xf000
	s_nop 0
	v_addc_co_u32_e32 v7, vcc, 0, v3, vcc
	global_load_dword v47, v[4:5], off offset:2048
	global_load_dword v62, v[22:23], off
	global_load_dword v59, v[22:23], off offset:2048
	global_load_dword v53, v[6:7], off offset:-4096
	global_load_dword v51, v[6:7], off
	global_load_dword v49, v[6:7], off offset:2048
	v_add_co_u32_e32 v2, vcc, s6, v2
	v_lshlrev_b32_e32 v60, 2, v54
	s_nop 0
	v_addc_co_u32_e32 v3, vcc, 0, v3, vcc
	global_load_dword v55, v[2:3], off
	v_add_u32_e32 v66, 0, v60
	s_barrier
	ds_read2st64_b32 v[80:81], v66 offset1:8
	ds_read2st64_b32 v[30:31], v66 offset0:16 offset1:24
	ds_read2st64_b32 v[28:29], v66 offset0:32 offset1:40
	ds_read2st64_b32 v[26:27], v66 offset0:48 offset1:56
	ds_read2st64_b32 v[24:25], v66 offset0:64 offset1:72
	ds_read2st64_b32 v[22:23], v66 offset0:80 offset1:88
	ds_read2st64_b32 v[20:21], v66 offset0:96 offset1:104
	ds_read2st64_b32 v[18:19], v66 offset0:112 offset1:120
	ds_read2st64_b32 v[16:17], v66 offset0:128 offset1:136
	ds_read2st64_b32 v[14:15], v66 offset0:144 offset1:152
	ds_read2st64_b32 v[12:13], v66 offset0:160 offset1:168
	ds_read2st64_b32 v[10:11], v66 offset0:176 offset1:184
	ds_read2st64_b32 v[8:9], v66 offset0:192 offset1:200
	ds_read2st64_b32 v[6:7], v66 offset0:208 offset1:216
	ds_read2st64_b32 v[4:5], v66 offset0:224 offset1:232
	ds_read2st64_b32 v[2:3], v66 offset0:240 offset1:248
	v_add_u32_e32 v67, 0x10000, v66
	v_add_u32_e32 v68, 0x10800, v66
	v_add_u32_e32 v69, 0x11000, v66
	v_add_u32_e32 v70, 0x11800, v66
	v_add_u32_e32 v74, 0x12000, v66
	v_add_u32_e32 v76, 0x12800, v66
	v_add_u32_e32 v77, 0x13000, v66
	v_add_u32_e32 v78, 0x13800, v66
	ds_read_b32 v75, v67
	ds_read_b32 v73, v68
	ds_read_b32 v72, v69
	ds_read_b32 v71, v70
	ds_read_b32 v70, v74
	ds_read_b32 v69, v76
	ds_read_b32 v68, v77
	ds_read_b32 v67, v78
	v_add_u32_e32 v74, 0x14000, v66
	v_add_u32_e32 v76, 0x14800, v66
	v_add_u32_e32 v77, 0x15000, v66
	v_add_u32_e32 v82, 0x15800, v66
	v_add_u32_e32 v83, 0x16000, v66
	v_add_u32_e32 v66, 0x16800, v66
	ds_read_b32 v79, v74
	ds_read_b32 v78, v76
	ds_read_b32 v77, v77
	ds_read_b32 v76, v82
	ds_read_b32 v74, v83
	ds_read_b32 v82, v66
	v_readlane_b32 s6, v255, 25
	s_add_i32 s26, s26, -1
	s_cmp_eq_u32 s26, 0
	s_cselect_b64 s[38:39], -1, 0
	s_add_u32 s40, s50, 0x12520000
	s_addc_u32 s41, s51, 0
	s_add_i32 s27, s27, 0x100
	s_max_u32 s27, s27, 0x200
	s_mov_b32 s9, s27
	s_mov_b64 s[48:49], 0
	s_waitcnt vmcnt(20) lgkmcnt(14)
; __device__ __forceinline__ void conv_task(const Params& p_, int l, int task, unsigned char* lds) {
;     ...
;     { float y[16];
; #pragma unroll
;       for (int t = 0; t < 16; ++t) y[t] = cb;
; #pragma unroll
;       for (int j = 0; j < 46; ++j) { const float u = us[j * 512 + tid];
; #pragma unroll
;           for (int t = 0; t < 16; ++t) { const int k = j - t; if (k >= 0 && k < 31) y[t] += w[k] * u; } }
; #pragma unroll
	v_fma_f32 v80, v33, v80, v42
	v_fmac_f32_e32 v80, v0, v81
	v_fma_f32 v81, v33, v81, v42
	v_fmac_f32_e32 v80, v41, v30
	v_fmac_f32_e32 v81, v0, v30
	v_fma_f32 v30, v33, v30, v42
	v_fmac_f32_e32 v80, v32, v31
	v_fmac_f32_e32 v81, v41, v31
	v_fmac_f32_e32 v30, v0, v31
	v_fma_f32 v31, v33, v31, v42
	v_fmac_f32_e32 v80, v40, v28
	v_fmac_f32_e32 v81, v32, v28
	v_fmac_f32_e32 v30, v41, v28
	v_fmac_f32_e32 v31, v0, v28
	v_fma_f32 v28, v33, v28, v42
	v_fmac_f32_e32 v80, v39, v29
	v_fmac_f32_e32 v81, v40, v29
	v_fmac_f32_e32 v30, v32, v29
	v_fmac_f32_e32 v31, v41, v29
	v_fmac_f32_e32 v28, v0, v29
	v_fma_f32 v29, v33, v29, v42
	v_fmac_f32_e32 v80, v38, v26
	v_fmac_f32_e32 v81, v39, v26
	v_fmac_f32_e32 v30, v40, v26
	v_fmac_f32_e32 v31, v32, v26
	v_fmac_f32_e32 v28, v41, v26
	v_fmac_f32_e32 v29, v0, v26
	v_fma_f32 v26, v33, v26, v42
	s_waitcnt vmcnt(11)
	v_fmac_f32_e32 v80, v65, v27
	v_fmac_f32_e32 v81, v38, v27
	v_fmac_f32_e32 v30, v39, v27
	v_fmac_f32_e32 v31, v40, v27
	v_fmac_f32_e32 v28, v32, v27
	v_fmac_f32_e32 v29, v41, v27
	v_fmac_f32_e32 v26, v0, v27
	v_fma_f32 v27, v33, v27, v42
	v_fmac_f32_e32 v80, v36, v24
	v_fmac_f32_e32 v81, v65, v24
	v_fmac_f32_e32 v30, v38, v24
	v_fmac_f32_e32 v31, v39, v24
	v_fmac_f32_e32 v28, v40, v24
	v_fmac_f32_e32 v29, v32, v24
	v_fmac_f32_e32 v26, v41, v24
	v_fmac_f32_e32 v27, v0, v24
	v_fma_f32 v24, v33, v24, v42
	v_fmac_f32_e32 v80, v35, v25
	v_fmac_f32_e32 v81, v36, v25
	v_fmac_f32_e32 v30, v65, v25
	v_fmac_f32_e32 v31, v38, v25
	v_fmac_f32_e32 v28, v39, v25
	v_fmac_f32_e32 v29, v40, v25
	v_fmac_f32_e32 v26, v32, v25
	v_fmac_f32_e32 v27, v41, v25
	v_fmac_f32_e32 v24, v0, v25
	v_fma_f32 v25, v33, v25, v42
	v_fmac_f32_e32 v80, v37, v22
	v_fmac_f32_e32 v81, v35, v22
	v_fmac_f32_e32 v30, v36, v22
	v_fmac_f32_e32 v31, v65, v22
	v_fmac_f32_e32 v28, v38, v22
	v_fmac_f32_e32 v29, v39, v22
	v_fmac_f32_e32 v26, v40, v22
	v_fmac_f32_e32 v27, v32, v22
	v_fmac_f32_e32 v24, v41, v22
	v_fmac_f32_e32 v25, v0, v22
	v_fma_f32 v22, v33, v22, v42
	s_waitcnt vmcnt(10)
	v_fmac_f32_e32 v80, v64, v23
	v_fmac_f32_e32 v81, v37, v23
	v_fmac_f32_e32 v30, v35, v23
	v_fmac_f32_e32 v31, v36, v23
	v_fmac_f32_e32 v28, v65, v23
	v_fmac_f32_e32 v29, v38, v23
	v_fmac_f32_e32 v26, v39, v23
	v_fmac_f32_e32 v27, v40, v23
	v_fmac_f32_e32 v24, v32, v23
	v_fmac_f32_e32 v25, v41, v23
	v_fmac_f32_e32 v22, v0, v23
	v_fma_f32 v23, v33, v23, v42
	v_fmac_f32_e32 v80, v34, v20
	v_fmac_f32_e32 v81, v64, v20
	v_fmac_f32_e32 v30, v37, v20
	v_fmac_f32_e32 v31, v35, v20
	v_fmac_f32_e32 v28, v36, v20
	v_fmac_f32_e32 v29, v65, v20
	v_fmac_f32_e32 v26, v38, v20
	v_fmac_f32_e32 v27, v39, v20
	v_fmac_f32_e32 v24, v40, v20
	v_fmac_f32_e32 v25, v32, v20
	v_fmac_f32_e32 v22, v41, v20
	v_fmac_f32_e32 v23, v0, v20
	v_fma_f32 v20, v33, v20, v42
	v_fma_f32 v66, v33, v19, v42
	v_fmac_f32_e32 v80, v61, v21
	v_fmac_f32_e32 v81, v34, v21
	v_fmac_f32_e32 v30, v64, v21
	v_fmac_f32_e32 v31, v37, v21
	v_fmac_f32_e32 v28, v35, v21
	v_fmac_f32_e32 v29, v36, v21
	v_fmac_f32_e32 v26, v65, v21
	v_fmac_f32_e32 v27, v38, v21
	v_fmac_f32_e32 v24, v39, v21
	v_fmac_f32_e32 v25, v40, v21
	v_fmac_f32_e32 v22, v32, v21
	v_fmac_f32_e32 v23, v41, v21
	v_fmac_f32_e32 v20, v0, v21
	v_fma_f32 v21, v33, v21, v42
	v_fmac_f32_e32 v42, v33, v18
	v_fmac_f32_e32 v66, v0, v16
	v_fmac_f32_e32 v21, v0, v18
	v_fmac_f32_e32 v42, v0, v19
	v_fmac_f32_e32 v66, v41, v17
	v_fmac_f32_e32 v20, v41, v18
	v_fmac_f32_e32 v21, v41, v19
	v_fmac_f32_e32 v42, v41, v16
	v_fmac_f32_e32 v66, v32, v14
	v_fmac_f32_e32 v80, v57, v18
	v_fmac_f32_e32 v81, v61, v18
	v_fmac_f32_e32 v30, v34, v18
	v_fmac_f32_e32 v31, v64, v18
	v_fmac_f32_e32 v28, v37, v18
	v_fmac_f32_e32 v29, v35, v18
	v_fmac_f32_e32 v26, v36, v18
	v_fmac_f32_e32 v27, v65, v18
	v_fmac_f32_e32 v24, v38, v18
	v_fmac_f32_e32 v25, v39, v18
	v_fmac_f32_e32 v22, v40, v18
	v_fmac_f32_e32 v23, v32, v18
	v_fmac_f32_e32 v20, v32, v19
	v_fmac_f32_e32 v21, v32, v16
	v_fmac_f32_e32 v42, v32, v17
	v_fmac_f32_e32 v66, v40, v15
	s_waitcnt vmcnt(9)
	v_fmac_f32_e32 v80, v63, v19
	v_fmac_f32_e32 v81, v57, v19
	v_fmac_f32_e32 v30, v61, v19
	v_fmac_f32_e32 v31, v34, v19
	v_fmac_f32_e32 v28, v64, v19
	v_fmac_f32_e32 v29, v37, v19
	v_fmac_f32_e32 v26, v35, v19
	v_fmac_f32_e32 v27, v36, v19
	v_fmac_f32_e32 v24, v65, v19
	v_fmac_f32_e32 v25, v38, v19
	v_fmac_f32_e32 v22, v39, v19
	v_fmac_f32_e32 v23, v40, v19
	v_fmac_f32_e32 v20, v40, v16
	v_fmac_f32_e32 v21, v40, v17
	v_fmac_f32_e32 v42, v40, v14
	v_fmac_f32_e32 v66, v39, v12
	v_fmac_f32_e32 v80, v52, v16
	v_fmac_f32_e32 v81, v63, v16
	v_fmac_f32_e32 v30, v57, v16
	v_fmac_f32_e32 v31, v61, v16
	v_fmac_f32_e32 v28, v34, v16
	v_fmac_f32_e32 v29, v64, v16
	v_fmac_f32_e32 v26, v37, v16
	v_fmac_f32_e32 v27, v35, v16
	v_fmac_f32_e32 v24, v36, v16
	v_fmac_f32_e32 v25, v65, v16
	v_fmac_f32_e32 v22, v38, v16
	v_fmac_f32_e32 v23, v39, v16
	v_fmac_f32_e32 v20, v39, v17
	v_fmac_f32_e32 v21, v39, v14
	v_fmac_f32_e32 v42, v39, v15
	v_fmac_f32_e32 v66, v38, v13
	v_fmac_f32_e32 v80, v50, v17
	v_fmac_f32_e32 v81, v52, v17
	v_fmac_f32_e32 v30, v63, v17
	v_fmac_f32_e32 v31, v57, v17
	v_fmac_f32_e32 v28, v61, v17
	v_fmac_f32_e32 v29, v34, v17
	v_fmac_f32_e32 v26, v64, v17
	v_fmac_f32_e32 v27, v37, v17
	v_fmac_f32_e32 v24, v35, v17
	v_fmac_f32_e32 v25, v36, v17
	v_fmac_f32_e32 v22, v65, v17
	v_fmac_f32_e32 v23, v38, v17
	v_fmac_f32_e32 v20, v38, v14
	v_fmac_f32_e32 v21, v38, v15
	v_fmac_f32_e32 v42, v38, v12
	v_fmac_f32_e32 v66, v65, v10
	v_fmac_f32_e32 v80, v48, v14
	v_fmac_f32_e32 v81, v50, v14
	v_fmac_f32_e32 v30, v52, v14
	v_fmac_f32_e32 v31, v63, v14
	v_fmac_f32_e32 v28, v57, v14
	v_fmac_f32_e32 v29, v61, v14
	v_fmac_f32_e32 v26, v34, v14
	v_fmac_f32_e32 v27, v64, v14
	v_fmac_f32_e32 v24, v37, v14
	v_fmac_f32_e32 v25, v35, v14
	v_fmac_f32_e32 v22, v36, v14
	v_fmac_f32_e32 v23, v65, v14
	v_fmac_f32_e32 v20, v65, v15
	v_fmac_f32_e32 v21, v65, v12
	v_fmac_f32_e32 v42, v65, v13
	v_fmac_f32_e32 v66, v36, v11
	s_waitcnt vmcnt(8)
; __device__ __forceinline__ void conv_task(const Params& p_, int l, int task, unsigned char* lds) {
;     ...
;     { float y[16];
; #pragma unroll
;       for (int t = 0; t < 16; ++t) y[t] = cb;
; #pragma unroll
;       for (int j = 0; j < 46; ++j) { const float u = us[j * 512 + tid];
; #pragma unroll
;           for (int t = 0; t < 16; ++t) { const int k = j - t; if (k >= 0 && k < 31) y[t] += w[k] * u; } }
; #pragma unroll
	v_fmac_f32_e32 v80, v58, v15
	v_fmac_f32_e32 v81, v48, v15
	v_fmac_f32_e32 v30, v50, v15
	v_fmac_f32_e32 v31, v52, v15
	v_fmac_f32_e32 v28, v63, v15
	v_fmac_f32_e32 v29, v57, v15
	v_fmac_f32_e32 v26, v61, v15
	v_fmac_f32_e32 v27, v34, v15
	v_fmac_f32_e32 v24, v64, v15
	v_fmac_f32_e32 v25, v37, v15
	v_fmac_f32_e32 v22, v35, v15
	v_fmac_f32_e32 v23, v36, v15
	v_fmac_f32_e32 v20, v36, v12
	v_fmac_f32_e32 v21, v36, v13
	v_fmac_f32_e32 v42, v36, v10
	v_fmac_f32_e32 v66, v35, v8
	v_fmac_f32_e32 v80, v45, v12
	v_fmac_f32_e32 v81, v58, v12
	v_fmac_f32_e32 v30, v48, v12
	v_fmac_f32_e32 v31, v50, v12
	v_fmac_f32_e32 v28, v52, v12
	v_fmac_f32_e32 v29, v63, v12
	v_fmac_f32_e32 v26, v57, v12
	v_fmac_f32_e32 v27, v61, v12
	v_fmac_f32_e32 v24, v34, v12
	v_fmac_f32_e32 v25, v64, v12
	v_fmac_f32_e32 v22, v37, v12
	v_fmac_f32_e32 v23, v35, v12
	v_fmac_f32_e32 v20, v35, v13
	v_fmac_f32_e32 v21, v35, v10
	v_fmac_f32_e32 v42, v35, v11
	v_fmac_f32_e32 v66, v37, v9
	v_fmac_f32_e32 v80, v44, v13
	v_fmac_f32_e32 v81, v45, v13
	v_fmac_f32_e32 v30, v58, v13
	v_fmac_f32_e32 v31, v48, v13
	v_fmac_f32_e32 v28, v50, v13
	v_fmac_f32_e32 v29, v52, v13
	v_fmac_f32_e32 v26, v63, v13
	v_fmac_f32_e32 v27, v57, v13
	v_fmac_f32_e32 v24, v61, v13
	v_fmac_f32_e32 v25, v34, v13
	v_fmac_f32_e32 v22, v64, v13
	v_fmac_f32_e32 v23, v37, v13
	v_fmac_f32_e32 v20, v37, v10
	v_fmac_f32_e32 v21, v37, v11
	v_fmac_f32_e32 v42, v37, v8
	v_fmac_f32_e32 v66, v64, v6
	v_fmac_f32_e32 v80, v43, v10
	v_fmac_f32_e32 v81, v44, v10
	v_fmac_f32_e32 v30, v45, v10
	v_fmac_f32_e32 v31, v58, v10
	v_fmac_f32_e32 v28, v48, v10
	v_fmac_f32_e32 v29, v50, v10
	v_fmac_f32_e32 v26, v52, v10
	v_fmac_f32_e32 v27, v63, v10
	v_fmac_f32_e32 v24, v57, v10
	v_fmac_f32_e32 v25, v61, v10
	v_fmac_f32_e32 v22, v34, v10
	v_fmac_f32_e32 v23, v64, v10
	v_fmac_f32_e32 v20, v64, v11
	v_fmac_f32_e32 v21, v64, v8
	v_fmac_f32_e32 v42, v64, v9
	v_fmac_f32_e32 v66, v34, v7
	s_waitcnt vmcnt(7)
	v_fmac_f32_e32 v80, v46, v11
	v_fmac_f32_e32 v81, v43, v11
	v_fmac_f32_e32 v30, v44, v11
	v_fmac_f32_e32 v31, v45, v11
	v_fmac_f32_e32 v28, v58, v11
	v_fmac_f32_e32 v29, v48, v11
	v_fmac_f32_e32 v26, v50, v11
	v_fmac_f32_e32 v27, v52, v11
	v_fmac_f32_e32 v24, v63, v11
	v_fmac_f32_e32 v25, v57, v11
	v_fmac_f32_e32 v22, v61, v11
	v_fmac_f32_e32 v23, v34, v11
	v_fmac_f32_e32 v20, v34, v8
	v_fmac_f32_e32 v21, v34, v9
	v_fmac_f32_e32 v42, v34, v6
	v_fmac_f32_e32 v66, v61, v4
	s_waitcnt vmcnt(5)
	v_fmac_f32_e32 v80, v62, v8
	v_fmac_f32_e32 v81, v46, v8
	v_fmac_f32_e32 v30, v43, v8
	v_fmac_f32_e32 v31, v44, v8
	v_fmac_f32_e32 v28, v45, v8
	v_fmac_f32_e32 v29, v58, v8
	v_fmac_f32_e32 v26, v48, v8
	v_fmac_f32_e32 v27, v50, v8
	v_fmac_f32_e32 v24, v52, v8
	v_fmac_f32_e32 v25, v63, v8
	v_fmac_f32_e32 v22, v57, v8
	v_fmac_f32_e32 v23, v61, v8
	v_fmac_f32_e32 v20, v61, v9
	v_fmac_f32_e32 v21, v61, v6
	v_fmac_f32_e32 v42, v61, v7
	v_fmac_f32_e32 v66, v57, v5
	s_waitcnt vmcnt(4)
	v_fmac_f32_e32 v80, v59, v9
	v_fmac_f32_e32 v81, v62, v9
	v_fmac_f32_e32 v30, v46, v9
	v_fmac_f32_e32 v31, v43, v9
	v_fmac_f32_e32 v28, v44, v9
	v_fmac_f32_e32 v29, v45, v9
	v_fmac_f32_e32 v26, v58, v9
	v_fmac_f32_e32 v27, v48, v9
	v_fmac_f32_e32 v24, v50, v9
	v_fmac_f32_e32 v25, v52, v9
	v_fmac_f32_e32 v22, v63, v9
	v_fmac_f32_e32 v23, v57, v9
	v_fmac_f32_e32 v20, v57, v6
	v_fmac_f32_e32 v21, v57, v7
	v_fmac_f32_e32 v42, v57, v4
	v_fmac_f32_e32 v66, v63, v2
	s_waitcnt vmcnt(3)
	v_fmac_f32_e32 v80, v53, v6
	v_fmac_f32_e32 v81, v59, v6
	v_fmac_f32_e32 v30, v62, v6
	v_fmac_f32_e32 v31, v46, v6
	v_fmac_f32_e32 v28, v43, v6
	v_fmac_f32_e32 v29, v44, v6
	v_fmac_f32_e32 v26, v45, v6
	v_fmac_f32_e32 v27, v58, v6
	v_fmac_f32_e32 v24, v48, v6
	v_fmac_f32_e32 v25, v50, v6
	v_fmac_f32_e32 v22, v52, v6
	v_fmac_f32_e32 v23, v63, v6
	v_fmac_f32_e32 v20, v63, v7
	v_fmac_f32_e32 v21, v63, v4
	v_fmac_f32_e32 v42, v63, v5
	v_fmac_f32_e32 v66, v52, v3
	v_fmac_f32_e32 v80, v47, v7
	v_fmac_f32_e32 v81, v53, v7
	v_fmac_f32_e32 v30, v59, v7
	v_fmac_f32_e32 v31, v62, v7
	v_fmac_f32_e32 v28, v46, v7
	v_fmac_f32_e32 v29, v43, v7
	v_fmac_f32_e32 v26, v44, v7
	v_fmac_f32_e32 v27, v45, v7
	v_fmac_f32_e32 v24, v58, v7
	v_fmac_f32_e32 v25, v48, v7
	v_fmac_f32_e32 v22, v50, v7
	v_fmac_f32_e32 v23, v52, v7
	v_fmac_f32_e32 v20, v52, v4
	v_fmac_f32_e32 v21, v52, v5
	v_fmac_f32_e32 v42, v52, v2
	s_waitcnt lgkmcnt(13)
	v_fmac_f32_e32 v66, v50, v75
	s_waitcnt vmcnt(2)
	v_fmac_f32_e32 v80, v51, v4
	v_fmac_f32_e32 v81, v47, v4
	v_fmac_f32_e32 v30, v53, v4
	v_fmac_f32_e32 v31, v59, v4
	v_fmac_f32_e32 v28, v62, v4
	v_fmac_f32_e32 v29, v46, v4
	v_fmac_f32_e32 v26, v43, v4
	v_fmac_f32_e32 v27, v44, v4
	v_fmac_f32_e32 v24, v45, v4
	v_fmac_f32_e32 v25, v58, v4
	v_fmac_f32_e32 v22, v48, v4
	v_fmac_f32_e32 v23, v50, v4
	v_fmac_f32_e32 v20, v50, v5
	v_fmac_f32_e32 v21, v50, v2
	v_fmac_f32_e32 v42, v50, v3
	s_waitcnt lgkmcnt(12)
	v_fmac_f32_e32 v66, v48, v73
	s_waitcnt vmcnt(1)
	v_fmac_f32_e32 v80, v49, v5
	v_fmac_f32_e32 v81, v51, v5
	v_fmac_f32_e32 v30, v47, v5
	v_fmac_f32_e32 v31, v53, v5
	v_fmac_f32_e32 v28, v59, v5
	v_fmac_f32_e32 v29, v62, v5
	v_fmac_f32_e32 v26, v46, v5
	v_fmac_f32_e32 v27, v43, v5
	v_fmac_f32_e32 v24, v44, v5
	v_fmac_f32_e32 v25, v45, v5
	v_fmac_f32_e32 v22, v58, v5
	v_fmac_f32_e32 v23, v48, v5
	v_fmac_f32_e32 v20, v48, v2
	v_fmac_f32_e32 v21, v48, v3
	v_fmac_f32_e32 v42, v48, v75
	s_waitcnt lgkmcnt(11)
	v_fmac_f32_e32 v66, v58, v72
	s_waitcnt vmcnt(0)
	v_fmac_f32_e32 v80, v55, v2
	v_fmac_f32_e32 v81, v49, v2
	v_fmac_f32_e32 v30, v51, v2
	v_fmac_f32_e32 v31, v47, v2
	v_fmac_f32_e32 v28, v53, v2
	v_fmac_f32_e32 v29, v59, v2
	v_fmac_f32_e32 v26, v62, v2
	v_fmac_f32_e32 v27, v46, v2
	v_fmac_f32_e32 v24, v43, v2
	v_fmac_f32_e32 v25, v44, v2
	v_fmac_f32_e32 v22, v45, v2
	v_fmac_f32_e32 v23, v58, v2
	v_fmac_f32_e32 v20, v58, v3
	v_fmac_f32_e32 v21, v58, v75
	v_fmac_f32_e32 v42, v58, v73
	v_and_b32_e32 v2, 64, v178
	s_waitcnt lgkmcnt(10)
; __device__ __forceinline__ void conv_task(const Params& p_, int l, int task, unsigned char* lds) {
;     ...
;       for (int j = 0; j < 46; ++j) { const float u = us[j * 512 + tid];
; #pragma unroll
;           for (int t = 0; t < 16; ++t) { const int k = j - t; if (k >= 0 && k < 31) y[t] += w[k] * u; } }
; #pragma unroll
;       for (int t = 0; t < 16; ++t) ys[t * 512 + tid] = y[t]; }
;     __syncthreads();
	v_fmac_f32_e32 v66, v45, v71
	v_fmac_f32_e32 v23, v45, v3
	v_fmac_f32_e32 v20, v45, v75
	v_fmac_f32_e32 v21, v45, v73
	v_fmac_f32_e32 v42, v45, v72
	v_add_u32_e32 v8, 64, v2
	v_xor_b32_e32 v2, 1, v178
	s_waitcnt lgkmcnt(9)
	v_fmac_f32_e32 v66, v44, v70
	v_fmac_f32_e32 v22, v44, v3
	v_fmac_f32_e32 v23, v44, v75
	v_fmac_f32_e32 v20, v44, v73
	v_fmac_f32_e32 v21, v44, v72
	v_fmac_f32_e32 v42, v44, v71
	v_cmp_lt_i32_e32 vcc, v2, v8
	s_waitcnt lgkmcnt(8)
	v_fmac_f32_e32 v66, v43, v69
	v_fmac_f32_e32 v25, v43, v3
	v_fmac_f32_e32 v22, v43, v75
	v_fmac_f32_e32 v23, v43, v73
	v_fmac_f32_e32 v20, v43, v72
	v_fmac_f32_e32 v21, v43, v71
	v_fmac_f32_e32 v42, v43, v70
	v_cndmask_b32_e32 v2, v178, v2, vcc
	s_waitcnt lgkmcnt(7)
	v_fmac_f32_e32 v66, v46, v68
	v_fmac_f32_e32 v24, v46, v3
	v_fmac_f32_e32 v25, v46, v75
	v_fmac_f32_e32 v22, v46, v73
	v_fmac_f32_e32 v23, v46, v72
	v_fmac_f32_e32 v20, v46, v71
	v_fmac_f32_e32 v21, v46, v70
	v_fmac_f32_e32 v42, v46, v69
	v_lshlrev_b32_e32 v39, 2, v2
	v_xor_b32_e32 v2, 2, v178
	s_waitcnt lgkmcnt(6)
	v_fmac_f32_e32 v66, v62, v67
	v_fmac_f32_e32 v27, v62, v3
	v_fmac_f32_e32 v24, v62, v75
	v_fmac_f32_e32 v25, v62, v73
	v_fmac_f32_e32 v22, v62, v72
	v_fmac_f32_e32 v23, v62, v71
	v_fmac_f32_e32 v20, v62, v70
	v_fmac_f32_e32 v21, v62, v69
	v_fmac_f32_e32 v42, v62, v68
	v_cmp_lt_i32_e32 vcc, v2, v8
	s_waitcnt lgkmcnt(5)
	v_fmac_f32_e32 v66, v59, v79
	v_fmac_f32_e32 v26, v59, v3
	v_fmac_f32_e32 v27, v59, v75
	v_fmac_f32_e32 v24, v59, v73
	v_fmac_f32_e32 v25, v59, v72
	v_fmac_f32_e32 v22, v59, v71
	v_fmac_f32_e32 v23, v59, v70
	v_fmac_f32_e32 v20, v59, v69
	v_fmac_f32_e32 v21, v59, v68
	v_fmac_f32_e32 v42, v59, v67
	v_cndmask_b32_e32 v2, v178, v2, vcc
	s_waitcnt lgkmcnt(4)
	v_fmac_f32_e32 v66, v53, v78
	v_fmac_f32_e32 v29, v53, v3
	v_fmac_f32_e32 v26, v53, v75
	v_fmac_f32_e32 v27, v53, v73
	v_fmac_f32_e32 v24, v53, v72
	v_fmac_f32_e32 v25, v53, v71
	v_fmac_f32_e32 v22, v53, v70
	v_fmac_f32_e32 v23, v53, v69
	v_fmac_f32_e32 v20, v53, v68
	v_fmac_f32_e32 v21, v53, v67
	v_fmac_f32_e32 v42, v53, v79
	v_lshlrev_b32_e32 v40, 2, v2
	v_xor_b32_e32 v2, 4, v178
	s_waitcnt lgkmcnt(3)
	v_fmac_f32_e32 v66, v47, v77
	v_fmac_f32_e32 v28, v47, v3
	v_fmac_f32_e32 v29, v47, v75
	v_fmac_f32_e32 v26, v47, v73
	v_fmac_f32_e32 v27, v47, v72
	v_fmac_f32_e32 v24, v47, v71
	v_fmac_f32_e32 v25, v47, v70
	v_fmac_f32_e32 v22, v47, v69
	v_fmac_f32_e32 v23, v47, v68
	v_fmac_f32_e32 v20, v47, v67
	v_fmac_f32_e32 v21, v47, v79
	v_fmac_f32_e32 v42, v47, v78
	v_cmp_lt_i32_e32 vcc, v2, v8
	s_waitcnt lgkmcnt(2)
	v_fmac_f32_e32 v66, v51, v76
	v_fmac_f32_e32 v31, v51, v3
	v_fmac_f32_e32 v28, v51, v75
	v_fmac_f32_e32 v29, v51, v73
	v_fmac_f32_e32 v26, v51, v72
	v_fmac_f32_e32 v27, v51, v71
	v_fmac_f32_e32 v24, v51, v70
	v_fmac_f32_e32 v25, v51, v69
	v_fmac_f32_e32 v22, v51, v68
	v_fmac_f32_e32 v23, v51, v67
	v_fmac_f32_e32 v20, v51, v79
	v_fmac_f32_e32 v21, v51, v78
	v_fmac_f32_e32 v42, v51, v77
	v_cndmask_b32_e32 v2, v178, v2, vcc
	s_waitcnt lgkmcnt(1)
	v_fmac_f32_e32 v66, v49, v74
	v_fmac_f32_e32 v81, v55, v3
	v_fmac_f32_e32 v30, v49, v3
	v_fmac_f32_e32 v31, v49, v75
	v_fmac_f32_e32 v28, v49, v73
	v_fmac_f32_e32 v29, v49, v72
	v_fmac_f32_e32 v26, v49, v71
	v_fmac_f32_e32 v27, v49, v70
	v_fmac_f32_e32 v24, v49, v69
	v_fmac_f32_e32 v25, v49, v68
	v_fmac_f32_e32 v22, v49, v67
	v_fmac_f32_e32 v23, v49, v79
	v_fmac_f32_e32 v20, v49, v78
	v_fmac_f32_e32 v21, v49, v77
	v_fmac_f32_e32 v42, v49, v76
	v_and_b32_e32 v38, 63, v54
	v_add_u32_e32 v0, s6, v60
	v_lshlrev_b32_e32 v41, 2, v2
	v_xor_b32_e32 v2, 8, v178
	s_waitcnt lgkmcnt(0)
	v_fmac_f32_e32 v66, v55, v82
	v_fmac_f32_e32 v30, v55, v75
	v_fmac_f32_e32 v31, v55, v73
	v_fmac_f32_e32 v28, v55, v72
	v_fmac_f32_e32 v29, v55, v71
	v_fmac_f32_e32 v26, v55, v70
	v_fmac_f32_e32 v27, v55, v69
	v_fmac_f32_e32 v24, v55, v68
	v_fmac_f32_e32 v25, v55, v67
	v_fmac_f32_e32 v22, v55, v79
	v_fmac_f32_e32 v23, v55, v78
	v_fmac_f32_e32 v20, v55, v77
	v_fmac_f32_e32 v21, v55, v76
	v_fmac_f32_e32 v42, v55, v74
	ds_write2st64_b32 v0, v80, v81 offset1:8
	ds_write2st64_b32 v0, v30, v31 offset0:16 offset1:24
	ds_write2st64_b32 v0, v28, v29 offset0:32 offset1:40
	ds_write2st64_b32 v0, v26, v27 offset0:48 offset1:56
	ds_write2st64_b32 v0, v24, v25 offset0:64 offset1:72
	ds_write2st64_b32 v0, v22, v23 offset0:80 offset1:88
	ds_write2st64_b32 v0, v20, v21 offset0:96 offset1:104
	ds_write2st64_b32 v0, v42, v66 offset0:112 offset1:120
	v_lshl_add_u32 v0, v38, 2, s6
	v_cmp_lt_i32_e32 vcc, v2, v8
	v_add_u32_e32 v43, 8, v56
	v_lshl_add_u32 v9, v56, 11, v0
	v_cndmask_b32_e32 v2, v178, v2, vcc
	v_lshl_add_u32 v0, v43, 11, v0
	s_waitcnt lgkmcnt(0)
	s_barrier
; __device__ __forceinline__ void conv_task(const Params& p_, int l, int task, unsigned char* lds) {
;     ...
;     for (int tw = 0; tw < 2; ++tw) { const int t = wave + 8 * tw; float v[8]; float s = 0.f;
; #pragma unroll
;         for (int j = 0; j < 8; ++j) { v[j] = ys[t * 512 + lane + 64 * j]; s += v[j]; }
;         const float mu = wave_sum(s) * (1.f / 512.f); float q = 0.f;
; #pragma unroll
;         for (int j = 0; j < 8; ++j) { v[j] -= mu; q += v[j] * v[j]; }
;         const float rstd = rsqrtf(wave_sum(q) * (1.f / 512.f) + 1e-6f);
;         bf16* orow = (bf16*)(p.ws + WS_CVH) + (size_t)(b * SEQ + t0 + t) * DG;
	v_lshlrev_b32_e32 v42, 2, v2
	ds_read2st64_b32 v[2:3], v9 offset0:4 offset1:5
	ds_read2st64_b32 v[4:5], v9 offset1:1
	ds_read2st64_b32 v[6:7], v9 offset0:6 offset1:7
	ds_read2st64_b32 v[16:17], v9 offset0:2 offset1:3
	ds_read2st64_b32 v[10:11], v0 offset1:1
	ds_read2st64_b32 v[14:15], v0 offset0:2 offset1:3
	ds_read2st64_b32 v[18:19], v0 offset0:4 offset1:5
	ds_read2st64_b32 v[20:21], v0 offset0:6 offset1:7
	s_waitcnt lgkmcnt(6)
	v_mov_b32_e32 v23, v4
	v_mov_b32_e32 v9, v2
	s_waitcnt lgkmcnt(5)
	v_mov_b32_e32 v13, v6
	s_waitcnt lgkmcnt(3)
	v_mov_b32_e32 v22, v10
	v_pk_add_f32 v[24:25], v[22:23], 0 op_sel_hi:[1,0]
	v_mov_b32_e32 v4, v11
	v_pk_add_f32 v[10:11], v[24:25], v[4:5]
	s_waitcnt lgkmcnt(2)
	v_mov_b32_e32 v24, v14
	v_mov_b32_e32 v25, v16
	v_pk_add_f32 v[10:11], v[10:11], v[24:25]
	v_mov_b32_e32 v16, v15
	v_pk_add_f32 v[10:11], v[10:11], v[16:17]
	s_waitcnt lgkmcnt(1)
	v_mov_b32_e32 v14, v18
	v_mov_b32_e32 v15, v2
	v_pk_add_f32 v[10:11], v[10:11], v[14:15]
	v_mov_b32_e32 v2, v19
	v_pk_add_f32 v[10:11], v[10:11], v[2:3]
	s_waitcnt lgkmcnt(0)
	v_mov_b32_e32 v14, v20
	v_mov_b32_e32 v15, v6
	v_pk_add_f32 v[10:11], v[10:11], v[14:15]
	v_mov_b32_e32 v6, v21
	v_pk_add_f32 v[10:11], v[10:11], v[6:7]
	ds_bpermute_b32 v15, v39, v11
	ds_bpermute_b32 v14, v39, v10
	v_xor_b32_e32 v12, 16, v178
	v_cmp_lt_i32_e32 vcc, v12, v8
	v_mov_b32_e32 v30, v19
	v_mov_b32_e32 v31, v18
	s_waitcnt lgkmcnt(0)
	v_pk_add_f32 v[10:11], v[10:11], v[14:15]
	ds_bpermute_b32 v15, v40, v11
	ds_bpermute_b32 v14, v40, v10
	v_cndmask_b32_e32 v0, v178, v12, vcc
	v_lshlrev_b32_e32 v44, 2, v0
	v_xor_b32_e32 v0, 32, v178
	v_cmp_lt_i32_e32 vcc, v0, v8
	v_mov_b32_e32 v8, v3
	s_waitcnt lgkmcnt(0)
	v_pk_add_f32 v[2:3], v[10:11], v[14:15]
	ds_bpermute_b32 v11, v41, v3
	ds_bpermute_b32 v10, v41, v2
	v_cndmask_b32_e32 v0, v178, v0, vcc
	v_lshlrev_b32_e32 v45, 2, v0
	v_or_b32_e32 v0, s3, v38
	v_mov_b32_e32 v12, v7
	s_waitcnt lgkmcnt(0)
	v_pk_add_f32 v[2:3], v[2:3], v[10:11]
	ds_bpermute_b32 v11, v42, v3
	ds_bpermute_b32 v10, v42, v2
	v_lshlrev_b64 v[6:7], 2, v[0:1]
	v_lshl_add_u64 v[14:15], s[60:61], 0, v[6:7]
	v_lshl_add_u64 v[6:7], s[62:63], 0, v[6:7]
	global_load_dword v46, v[14:15], off
	global_load_dword v47, v[6:7], off
	s_waitcnt lgkmcnt(0)
	v_pk_add_f32 v[2:3], v[2:3], v[10:11]
	ds_bpermute_b32 v11, v44, v3
	ds_bpermute_b32 v10, v44, v2
	v_add_u32_e32 v6, s3, v38
	v_mov_b32_e32 v7, v1
	v_lshlrev_b64 v[6:7], 2, v[6:7]
	v_lshl_add_u64 v[26:27], s[60:61], 0, v[6:7]
	s_waitcnt lgkmcnt(0)
	v_pk_add_f32 v[2:3], v[2:3], v[10:11]
	ds_bpermute_b32 v11, v45, v3
	ds_bpermute_b32 v10, v45, v2
	global_load_dword v48, v[26:27], off offset:256
	v_lshl_add_u64 v[28:29], s[62:63], 0, v[6:7]
	global_load_dword v49, v[28:29], off offset:256
	s_waitcnt lgkmcnt(0)
	v_pk_add_f32 v[2:3], v[2:3], v[10:11]
	s_nop 0
	v_pk_mul_f32 v[18:19], v[2:3], s[2:3] op_sel_hi:[1,0]
	v_pk_fma_f32 v[10:11], v[2:3], s[2:3], v[4:5] op_sel_hi:[1,0,1] neg_lo:[1,0,0] neg_hi:[1,0,0]
	v_pk_add_f32 v[14:15], v[12:13], v[18:19] op_sel:[0,1] neg_lo:[0,1] neg_hi:[0,1]
	v_pk_fma_f32 v[12:13], v[2:3], s[2:3], v[22:23] op_sel_hi:[1,0,1] neg_lo:[1,0,0] neg_hi:[1,0,0]
	v_pk_mul_f32 v[4:5], v[10:11], v[10:11]
	v_pk_add_f32 v[32:33], v[8:9], v[18:19] op_sel:[0,1] neg_lo:[0,1] neg_hi:[0,1]
	v_pk_fma_f32 v[4:5], v[12:13], v[12:13], v[4:5]
	v_pk_fma_f32 v[8:9], v[2:3], s[2:3], v[24:25] op_sel_hi:[1,0,1] neg_lo:[1,0,0] neg_hi:[1,0,0]
	v_pk_fma_f32 v[6:7], v[2:3], s[2:3], v[16:17] op_sel_hi:[1,0,1] neg_lo:[1,0,0] neg_hi:[1,0,0]
	v_pk_fma_f32 v[4:5], v[8:9], v[8:9], v[4:5]
	v_pk_mul_f32 v[34:35], v[32:33], v[32:33]
	v_pk_fma_f32 v[2:3], v[6:7], v[6:7], v[4:5]
	v_pk_add_f32 v[4:5], v[30:31], v[18:19] op_sel_hi:[1,0] neg_lo:[0,1] neg_hi:[0,1]
	v_mov_b32_e32 v23, v35
	v_pk_mul_f32 v[16:17], v[4:5], v[4:5]
	v_pk_mul_f32 v[36:37], v[14:15], v[14:15]
	v_mov_b32_e32 v22, v17
	v_pk_add_f32 v[22:23], v[22:23], v[2:3]
	v_mov_b32_e32 v2, v21
	v_mov_b32_e32 v3, v20
	v_pk_add_f32 v[2:3], v[2:3], v[18:19] op_sel_hi:[1,0] neg_lo:[0,1] neg_hi:[0,1]
	v_mov_b32_e32 v17, v34
	v_pk_mul_f32 v[18:19], v[2:3], v[2:3]
	v_pk_add_f32 v[16:17], v[16:17], v[22:23]
	v_mov_b32_e32 v20, v19
	v_mov_b32_e32 v21, v37
	v_pk_add_f32 v[16:17], v[20:21], v[16:17]
	v_mov_b32_e32 v19, v36
	v_pk_add_f32 v[16:17], v[18:19], v[16:17]
	ds_bpermute_b32 v19, v39, v17
	ds_bpermute_b32 v18, v39, v16
	global_load_dword v22, v[26:27], off offset:512
	global_load_dword v23, v[28:29], off offset:512
	global_load_dword v24, v[26:27], off offset:768
	global_load_dword v25, v[28:29], off offset:768
	v_add_u32_e32 v20, s68, v56
	v_ashrrev_i32_e32 v21, 31, v20
	s_waitcnt lgkmcnt(0)
	v_pk_add_f32 v[16:17], v[16:17], v[18:19]
	ds_bpermute_b32 v19, v40, v17
	ds_bpermute_b32 v18, v40, v16
	v_lshlrev_b64 v[20:21], 10, v[20:21]
	v_lshl_add_u64 v[20:21], s[40:41], 0, v[20:21]
	s_waitcnt lgkmcnt(0)
	v_pk_add_f32 v[16:17], v[16:17], v[18:19]
	ds_bpermute_b32 v19, v41, v17
	ds_bpermute_b32 v18, v41, v16
	s_waitcnt lgkmcnt(0)
	v_pk_add_f32 v[16:17], v[16:17], v[18:19]
	ds_bpermute_b32 v19, v42, v17
	ds_bpermute_b32 v18, v42, v16
	s_waitcnt lgkmcnt(0)
	v_pk_add_f32 v[16:17], v[16:17], v[18:19]
	ds_bpermute_b32 v19, v44, v17
	ds_bpermute_b32 v18, v44, v16
	s_waitcnt lgkmcnt(0)
	v_pk_add_f32 v[16:17], v[16:17], v[18:19]
	ds_bpermute_b32 v19, v45, v17
	ds_bpermute_b32 v18, v45, v16
	s_waitcnt lgkmcnt(0)
; __device__ __forceinline__ unsigned f2bf(float f) { unsigned u = __float_as_uint(f); return (u + 0x7fffu + ((u >> 16) & 1u)) >> 16; }
; __device__ __forceinline__ float silu_f(float v) { return v / (1.f + __expf(-v)); }
; __device__ __forceinline__ void conv_task(const Params& p_, int l, int task, unsigned char* lds) {
;     ...
;     for (int tw = 0; tw < 2; ++tw) { const int t = wave + 8 * tw; float v[8]; float s = 0.f;
; #pragma unroll
;         for (int j = 0; j < 8; ++j) { v[j] = ys[t * 512 + lane + 64 * j]; s += v[j]; }
;         const float mu = wave_sum(s) * (1.f / 512.f); float q = 0.f;
; #pragma unroll
;         for (int j = 0; j < 8; ++j) { v[j] -= mu; q += v[j] * v[j]; }
;         const float rstd = rsqrtf(wave_sum(q) * (1.f / 512.f) + 1e-6f);
;         bf16* orow = (bf16*)(p.ws + WS_CVH) + (size_t)(b * SEQ + t0 + t) * DG;
; #pragma unroll
;         for (int j = 0; j < 8; ++j) { const int ch = lane + 64 * j; const float y = v[j] * rstd * p.ln_g[l * DG + ch] + p.ln_b[l * DG + ch]; orow[ch] = (bf16)f2bf(silu_f(y)); } }
	v_pk_add_f32 v[16:17], v[16:17], v[18:19]
	s_nop 0
	v_pk_fma_f32 v[16:17], v[16:17], s[2:3], v[146:147] op_sel_hi:[1,0,0]
	s_nop 0
	v_mul_f32_e32 v0, 0x4b800000, v17
	v_cmp_gt_f32_e32 vcc, s92, v17
	v_cmp_gt_f32_e64 s[36:37], s92, v16
	s_nop 0
	v_cndmask_b32_e32 v0, v17, v0, vcc
	v_rsq_f32_e32 v17, v0
	v_lshlrev_b32_e32 v0, 1, v38
	v_lshl_add_u64 v[18:19], v[20:21], 0, v[0:1]
	global_load_dword v20, v[28:29], off offset:1024
	global_load_dword v30, v[26:27], off offset:1024
	global_load_dword v31, v[26:27], off offset:1280
	global_load_dword v34, v[26:27], off offset:1536
	s_nop 0
	global_load_dword v26, v[26:27], off offset:1792
	v_mul_f32_e32 v21, 0x45800000, v17
	v_cndmask_b32_e32 v17, v17, v21, vcc
	v_mul_f32_e32 v13, v13, v17
	s_waitcnt vmcnt(11)
	v_fma_f32 v13, v46, v13, v47
	v_mul_f32_e32 v21, 0xbfb8aa3b, v13
	v_exp_f32_e32 v21, v21
	global_load_dword v36, v[28:29], off offset:1280
	global_load_dword v37, v[28:29], off offset:1536
	s_nop 0
	global_load_dword v28, v[28:29], off offset:1792
	v_mul_f32_e32 v11, v11, v17
	s_waitcnt vmcnt(12)
	v_fma_f32 v11, v48, v11, v49
	v_add_f32_e32 v21, 1.0, v21
	v_div_scale_f32 v27, s[12:13], v21, v21, v13
	v_rcp_f32_e32 v35, v27
	v_mul_f32_e32 v9, v9, v17
	v_mul_f32_e32 v7, v7, v17
	v_fma_f32 v29, -v27, v35, 1.0
	v_fmac_f32_e32 v35, v29, v35
	v_div_scale_f32 v29, vcc, v13, v21, v13
	v_mul_f32_e32 v38, v29, v35
	v_fma_f32 v39, -v27, v38, v29
	v_fmac_f32_e32 v38, v39, v35
	v_fma_f32 v27, -v27, v38, v29
	v_mul_f32_e32 v29, 0xbfb8aa3b, v11
	v_exp_f32_e32 v29, v29
	v_div_fmas_f32 v27, v27, v35, v38
	v_div_fixup_f32 v13, v27, v21, v13
	v_bfe_u32 v35, v13, 16, 1
	v_add_f32_e32 v21, 1.0, v29
	v_div_scale_f32 v27, s[12:13], v21, v21, v11
	v_rcp_f32_e32 v29, v27
	v_add3_u32 v13, v13, v35, s14
	global_store_short_d16_hi v[18:19], v13, off
	s_waitcnt vmcnt(11)
	v_fma_f32 v9, v22, v9, v23
	v_fma_f32 v13, -v27, v29, 1.0
	v_fmac_f32_e32 v29, v13, v29
	v_div_scale_f32 v13, vcc, v11, v21, v11
	v_mul_f32_e32 v35, v13, v29
	v_fma_f32 v38, -v27, v35, v13
	v_fmac_f32_e32 v35, v38, v29
	v_fma_f32 v13, -v27, v35, v13
	v_mul_f32_e32 v27, 0xbfb8aa3b, v9
	v_exp_f32_e32 v27, v27
	v_div_fmas_f32 v13, v13, v29, v35
	v_div_fixup_f32 v11, v13, v21, v11
	v_bfe_u32 v29, v11, 16, 1
	v_add_f32_e32 v13, 1.0, v27
	v_div_scale_f32 v21, s[12:13], v13, v13, v9
	v_rcp_f32_e32 v27, v21
	v_add3_u32 v11, v11, v29, s14
	global_store_short_d16_hi v[18:19], v11, off offset:128
	s_waitcnt vmcnt(10)
	v_fma_f32 v7, v24, v7, v25
	v_fma_f32 v11, -v21, v27, 1.0
	v_fmac_f32_e32 v27, v11, v27
	v_div_scale_f32 v11, vcc, v9, v13, v9
	v_mul_f32_e32 v29, v11, v27
	v_fma_f32 v35, -v21, v29, v11
	v_fmac_f32_e32 v29, v35, v27
	v_fma_f32 v11, -v21, v29, v11
	v_mul_f32_e32 v21, 0xbfb8aa3b, v7
	v_exp_f32_e32 v21, v21
	v_div_fmas_f32 v11, v11, v27, v29
	v_div_fixup_f32 v9, v11, v13, v9
	v_bfe_u32 v27, v9, 16, 1
	v_add_f32_e32 v11, 1.0, v21
	v_div_scale_f32 v13, s[12:13], v11, v11, v7
	v_rcp_f32_e32 v21, v13
	v_add3_u32 v9, v9, v27, s14
	global_store_short_d16_hi v[18:19], v9, off offset:256
	v_fma_f32 v9, -v13, v21, 1.0
	v_fmac_f32_e32 v21, v9, v21
	v_div_scale_f32 v9, vcc, v7, v11, v7
	v_mul_f32_e32 v27, v9, v21
	v_fma_f32 v29, -v13, v27, v9
	v_fmac_f32_e32 v27, v29, v21
	v_fma_f32 v9, -v13, v27, v9
	v_mul_f32_e32 v13, v33, v17
	s_waitcnt vmcnt(9)
	v_fma_f32 v13, v30, v13, v20
	v_mul_f32_e32 v29, 0xbfb8aa3b, v13
	v_exp_f32_e32 v29, v29
	v_div_fmas_f32 v9, v9, v21, v27
	v_div_fixup_f32 v7, v9, v11, v7
	v_bfe_u32 v27, v7, 16, 1
	v_add_f32_e32 v9, 1.0, v29
	v_div_scale_f32 v11, s[12:13], v9, v9, v13
	v_rcp_f32_e32 v21, v11
	v_add3_u32 v7, v7, v27, s14
	global_store_short_d16_hi v[18:19], v7, off offset:384
	v_fma_f32 v7, -v11, v21, 1.0
	v_fmac_f32_e32 v21, v7, v21
	v_div_scale_f32 v7, vcc, v13, v9, v13
	v_mul_f32_e32 v27, v7, v21
	v_fma_f32 v29, -v11, v27, v7
	v_fmac_f32_e32 v27, v29, v21
	v_fma_f32 v7, -v11, v27, v7
	v_mul_f32_e32 v11, v32, v17
	s_waitcnt vmcnt(6)
	v_fma_f32 v11, v31, v11, v36
	v_mul_f32_e32 v29, 0xbfb8aa3b, v11
	v_exp_f32_e32 v29, v29
	v_div_fmas_f32 v7, v7, v21, v27
	v_div_fixup_f32 v7, v7, v9, v13
	v_bfe_u32 v27, v7, 16, 1
	v_add_f32_e32 v9, 1.0, v29
	v_div_scale_f32 v13, s[12:13], v9, v9, v11
	v_rcp_f32_e32 v21, v13
	v_add3_u32 v7, v7, v27, s14
	global_store_short_d16_hi v[18:19], v7, off offset:512
	v_fma_f32 v7, -v13, v21, 1.0
	v_fmac_f32_e32 v21, v7, v21
	v_div_scale_f32 v7, vcc, v11, v9, v11
	v_mul_f32_e32 v27, v7, v21
	v_fma_f32 v29, -v13, v27, v7
	v_fmac_f32_e32 v27, v29, v21
	v_fma_f32 v7, -v13, v27, v7
	v_mul_f32_e32 v13, v15, v17
	s_waitcnt vmcnt(6)
	v_fma_f32 v13, v34, v13, v37
	v_mul_f32_e32 v15, 0xbfb8aa3b, v13
	v_exp_f32_e32 v15, v15
	v_div_fmas_f32 v7, v7, v21, v27
	v_div_fixup_f32 v7, v7, v9, v11
	v_bfe_u32 v21, v7, 16, 1
	v_add_f32_e32 v9, 1.0, v15
	v_div_scale_f32 v11, s[12:13], v9, v9, v13
	v_rcp_f32_e32 v15, v11
	v_add3_u32 v7, v7, v21, s14
	global_store_short_d16_hi v[18:19], v7, off offset:640
	v_fma_f32 v7, -v11, v15, 1.0
	v_fmac_f32_e32 v15, v7, v15
	v_div_scale_f32 v7, vcc, v13, v9, v13
	v_mul_f32_e32 v21, v7, v15
	v_fma_f32 v27, -v11, v21, v7
	v_fmac_f32_e32 v21, v27, v15
	v_fma_f32 v7, -v11, v21, v7
	v_mul_f32_e32 v11, v14, v17
	s_waitcnt vmcnt(6)
; __device__ __forceinline__ unsigned f2bf(float f) { unsigned u = __float_as_uint(f); return (u + 0x7fffu + ((u >> 16) & 1u)) >> 16; }
; __device__ __forceinline__ float silu_f(float v) { return v / (1.f + __expf(-v)); }
; __device__ __forceinline__ void conv_task(const Params& p_, int l, int task, unsigned char* lds) {
;     ...
;     for (int tw = 0; tw < 2; ++tw) { const int t = wave + 8 * tw; float v[8]; float s = 0.f;
; #pragma unroll
;         for (int j = 0; j < 8; ++j) { v[j] = ys[t * 512 + lane + 64 * j]; s += v[j]; }
;         const float mu = wave_sum(s) * (1.f / 512.f); float q = 0.f;
; #pragma unroll
;         for (int j = 0; j < 8; ++j) { v[j] -= mu; q += v[j] * v[j]; }
;         const float rstd = rsqrtf(wave_sum(q) * (1.f / 512.f) + 1e-6f);
;         bf16* orow = (bf16*)(p.ws + WS_CVH) + (size_t)(b * SEQ + t0 + t) * DG;
; #pragma unroll
;         for (int j = 0; j < 8; ++j) { const int ch = lane + 64 * j; const float y = v[j] * rstd * p.ln_g[l * DG + ch] + p.ln_b[l * DG + ch]; orow[ch] = (bf16)f2bf(silu_f(y)); } }
;     __syncthreads();
	v_fma_f32 v11, v11, v26, v28
	v_mul_f32_e32 v14, 0xbfb8aa3b, v11
	v_exp_f32_e32 v14, v14
	v_div_fmas_f32 v7, v7, v15, v21
	v_div_fixup_f32 v7, v7, v9, v13
	v_bfe_u32 v15, v7, 16, 1
	v_add_f32_e32 v9, 1.0, v14
	v_div_scale_f32 v13, s[12:13], v9, v9, v11
	v_rcp_f32_e32 v14, v13
	v_add3_u32 v7, v7, v15, s14
	global_store_short_d16_hi v[18:19], v7, off offset:768
	v_fma_f32 v7, -v13, v14, 1.0
	v_fmac_f32_e32 v14, v7, v14
	v_div_scale_f32 v7, vcc, v11, v9, v11
	v_mul_f32_e32 v15, v7, v14
	v_fma_f32 v17, -v13, v15, v7
	v_fmac_f32_e32 v15, v17, v14
	v_fma_f32 v7, -v13, v15, v7
	v_mul_f32_e32 v13, 0x4b800000, v16
	v_cndmask_b32_e64 v13, v16, v13, s[36:37]
	v_rsq_f32_e32 v13, v13
	v_div_fmas_f32 v7, v7, v14, v15
	v_div_fixup_f32 v7, v7, v9, v11
	v_bfe_u32 v9, v7, 16, 1
	v_mul_f32_e32 v11, 0x45800000, v13
	v_cndmask_b32_e64 v14, v13, v11, s[36:37]
	v_mul_f32_e32 v11, v12, v14
	v_fmac_f32_e32 v47, v46, v11
	v_mul_f32_e32 v11, 0xbfb8aa3b, v47
	v_exp_f32_e32 v11, v11
	v_add3_u32 v7, v7, v9, s14
	global_store_short_d16_hi v[18:19], v7, off offset:896
	v_mul_f32_e32 v10, v10, v14
	v_add_f32_e32 v7, 1.0, v11
	v_div_scale_f32 v9, s[12:13], v7, v7, v47
	v_rcp_f32_e32 v11, v9
	v_fmac_f32_e32 v49, v48, v10
	v_mul_f32_e32 v10, 0xbfb8aa3b, v49
	v_exp_f32_e32 v10, v10
	v_fma_f32 v15, -v9, v11, 1.0
	v_fmac_f32_e32 v11, v15, v11
	v_div_scale_f32 v15, vcc, v47, v7, v47
	v_mul_f32_e32 v16, v15, v11
	v_fma_f32 v17, -v9, v16, v15
	v_fmac_f32_e32 v16, v17, v11
	v_fma_f32 v9, -v9, v16, v15
	v_add_f32_e32 v15, 1.0, v10
	v_div_fmas_f32 v9, v9, v11, v16
	v_div_scale_f32 v16, s[12:13], v15, v15, v49
	v_add_u32_e32 v12, s68, v43
	v_rcp_f32_e32 v17, v16
	v_ashrrev_i32_e32 v13, 31, v12
	v_lshlrev_b64 v[12:13], 10, v[12:13]
	v_lshl_add_u64 v[12:13], s[40:41], 0, v[12:13]
	v_div_fixup_f32 v7, v9, v7, v47
	v_mul_f32_e32 v8, v8, v14
	v_bfe_u32 v9, v7, 16, 1
	v_lshl_add_u64 v[10:11], v[12:13], 0, v[0:1]
	v_fma_f32 v0, -v16, v17, 1.0
	v_fmac_f32_e32 v23, v22, v8
	v_add3_u32 v7, v7, v9, s14
	v_fmac_f32_e32 v17, v0, v17
	v_div_scale_f32 v0, vcc, v49, v15, v49
	v_mul_f32_e32 v8, 0xbfb8aa3b, v23
	global_store_short_d16_hi v[10:11], v7, off
	v_mul_f32_e32 v7, v0, v17
	v_exp_f32_e32 v8, v8
	v_fma_f32 v9, -v16, v7, v0
	v_fmac_f32_e32 v7, v9, v17
	v_fma_f32 v0, -v16, v7, v0
	v_div_fmas_f32 v0, v0, v17, v7
	v_add_f32_e32 v7, 1.0, v8
	v_div_scale_f32 v8, s[12:13], v7, v7, v23
	v_rcp_f32_e32 v9, v8
	v_div_fixup_f32 v0, v0, v15, v49
	v_bfe_u32 v12, v0, 16, 1
	v_add3_u32 v0, v0, v12, s14
	v_mul_f32_e32 v6, v6, v14
	global_store_short_d16_hi v[10:11], v0, off offset:128
	v_fma_f32 v0, -v8, v9, 1.0
	v_fmac_f32_e32 v25, v24, v6
	v_fmac_f32_e32 v9, v0, v9
	v_div_scale_f32 v0, vcc, v23, v7, v23
	v_mul_f32_e32 v6, 0xbfb8aa3b, v25
	v_mul_f32_e32 v12, v0, v9
	v_exp_f32_e32 v6, v6
	v_fma_f32 v13, -v8, v12, v0
	v_fmac_f32_e32 v12, v13, v9
	v_fma_f32 v0, -v8, v12, v0
	v_div_fmas_f32 v0, v0, v9, v12
	v_add_f32_e32 v6, 1.0, v6
	v_div_fixup_f32 v0, v0, v7, v23
	v_div_scale_f32 v7, s[12:13], v6, v6, v25
	v_rcp_f32_e32 v8, v7
	v_bfe_u32 v9, v0, 16, 1
	v_add3_u32 v0, v0, v9, s14
	v_mul_f32_e32 v5, v5, v14
	global_store_short_d16_hi v[10:11], v0, off offset:256
	v_fma_f32 v0, -v7, v8, 1.0
	v_fmac_f32_e32 v20, v30, v5
	v_fmac_f32_e32 v8, v0, v8
	v_div_scale_f32 v0, vcc, v25, v6, v25
	v_mul_f32_e32 v5, 0xbfb8aa3b, v20
	v_mul_f32_e32 v9, v0, v8
	v_exp_f32_e32 v5, v5
	v_fma_f32 v12, -v7, v9, v0
	v_fmac_f32_e32 v9, v12, v8
	v_fma_f32 v0, -v7, v9, v0
	v_div_fmas_f32 v0, v0, v8, v9
	v_add_f32_e32 v5, 1.0, v5
	v_div_fixup_f32 v0, v0, v6, v25
	v_div_scale_f32 v6, s[12:13], v5, v5, v20
	v_rcp_f32_e32 v7, v6
	v_bfe_u32 v8, v0, 16, 1
	v_add3_u32 v0, v0, v8, s14
	v_mul_f32_e32 v4, v4, v14
	global_store_short_d16_hi v[10:11], v0, off offset:384
	v_fma_f32 v0, -v6, v7, 1.0
	v_fmac_f32_e32 v36, v31, v4
	v_fmac_f32_e32 v7, v0, v7
	v_div_scale_f32 v0, vcc, v20, v5, v20
	v_mul_f32_e32 v4, 0xbfb8aa3b, v36
	v_mul_f32_e32 v8, v0, v7
	v_exp_f32_e32 v4, v4
	v_fma_f32 v9, -v6, v8, v0
	v_fmac_f32_e32 v8, v9, v7
	v_fma_f32 v0, -v6, v8, v0
	v_div_fmas_f32 v0, v0, v7, v8
	v_add_f32_e32 v4, 1.0, v4
	v_div_fixup_f32 v0, v0, v5, v20
	v_div_scale_f32 v5, s[12:13], v4, v4, v36
	v_rcp_f32_e32 v6, v5
	v_bfe_u32 v7, v0, 16, 1
	v_add3_u32 v0, v0, v7, s14
	v_mul_f32_e32 v3, v3, v14
	global_store_short_d16_hi v[10:11], v0, off offset:512
	v_fma_f32 v0, -v5, v6, 1.0
	v_fmac_f32_e32 v37, v34, v3
	v_fmac_f32_e32 v6, v0, v6
	v_div_scale_f32 v0, vcc, v36, v4, v36
	v_mul_f32_e32 v3, 0xbfb8aa3b, v37
	v_mul_f32_e32 v7, v0, v6
	v_exp_f32_e32 v3, v3
	v_fma_f32 v8, -v5, v7, v0
	v_fmac_f32_e32 v7, v8, v6
	v_fma_f32 v0, -v5, v7, v0
	v_div_fmas_f32 v0, v0, v6, v7
	v_add_f32_e32 v3, 1.0, v3
	v_div_fixup_f32 v0, v0, v4, v36
	v_div_scale_f32 v4, s[12:13], v3, v3, v37
	v_rcp_f32_e32 v5, v4
	v_bfe_u32 v6, v0, 16, 1
	v_add3_u32 v0, v0, v6, s14
	v_mul_f32_e32 v2, v2, v14
	global_store_short_d16_hi v[10:11], v0, off offset:640
	v_fma_f32 v0, -v4, v5, 1.0
	v_fmac_f32_e32 v28, v26, v2
	v_fmac_f32_e32 v5, v0, v5
	v_div_scale_f32 v0, vcc, v37, v3, v37
	v_mul_f32_e32 v2, 0xbfb8aa3b, v28
	v_mul_f32_e32 v6, v0, v5
	v_exp_f32_e32 v2, v2
	v_fma_f32 v7, -v4, v6, v0
	v_fmac_f32_e32 v6, v7, v5
	v_fma_f32 v0, -v4, v6, v0
	v_div_fmas_f32 v0, v0, v5, v6
	v_add_f32_e32 v2, 1.0, v2
	v_div_fixup_f32 v0, v0, v3, v37
	v_div_scale_f32 v3, s[12:13], v2, v2, v28
	v_rcp_f32_e32 v4, v3
	v_bfe_u32 v5, v0, 16, 1
	v_add3_u32 v0, v0, v5, s14
	global_store_short_d16_hi v[10:11], v0, off offset:768
	v_fma_f32 v0, -v3, v4, 1.0
	v_fmac_f32_e32 v4, v0, v4
	v_div_scale_f32 v0, vcc, v28, v2, v28
	v_mul_f32_e32 v5, v0, v4
	v_fma_f32 v6, -v3, v5, v0
	v_fmac_f32_e32 v5, v6, v4
	v_fma_f32 v0, -v3, v5, v0
	v_div_fmas_f32 v0, v0, v4, v5
	v_div_fixup_f32 v0, v0, v2, v28
	v_bfe_u32 v2, v0, 16, 1
	v_add3_u32 v0, v0, v2, s14
	s_and_b64 vcc, exec, s[38:39]
	global_store_short_d16_hi v[10:11], v0, off offset:896
	s_barrier
	s_cbranch_vccnz .LBB0_451
